# all s_setprio removed from GEMM K-loops (re-measure)
# speedup vs baseline: 1.0099x; 1.0099x over previous
.LBB0_111:
	s_add_u32 s28, s26, 0xfffc0080
	s_addc_u32 s29, s27, -1
	s_add_i32 s57, 0, 0x10000
	s_cmp_eq_u32 s56, 12
	s_cselect_b32 s31, s19, s29
	s_cselect_b32 s30, s52, s28
	v_add_u32_e32 v150, s57, v1
	s_cselect_b32 s29, s17, s55
	s_cselect_b32 s28, s53, s54
	s_add_i32 s60, 0, 0x14000
	ds_read_b128 v[142:145], v150
	ds_read_b128 v[146:149], v150 offset:1024
	ds_read_b128 v[154:157], v150 offset:2048
	ds_read_b128 v[158:161], v150 offset:3072
	v_add_u32_e32 v150, s60, v1
	s_nop 0
	ds_read_b128 v[162:165], v150
	ds_read_b128 v[166:169], v150 offset:1024
	ds_read_b128 v[170:173], v150 offset:2048
	ds_read_b128 v[174:177], v150 offset:3072
	v_lshl_add_u64 v[150:151], s[26:27], 0, v[138:139]
	s_add_i32 m0, s43, 0xc000
	ds_read_b128 v[178:181], v152
	ds_read_b128 v[182:185], v152 offset:1024
	ds_read_b128 v[186:189], v152 offset:2048
	ds_read_b128 v[190:193], v152 offset:3072
	ds_read_b128 v[204:207], v152 offset:4096
	ds_read_b128 v[208:211], v152 offset:5120
	ds_read_b128 v[212:215], v152 offset:6144
	ds_read_b128 v[228:231], v152 offset:7168
	global_load_lds_dwordx4 v[150:151], off
	v_lshl_add_u64 v[150:151], s[26:27], 0, v[140:141]
	s_add_i32 m0, s43, 0xe000
	s_nop 0
	global_load_lds_dwordx4 v[150:151], off
	s_waitcnt vmcnt(8)
	s_waitcnt lgkmcnt(0)
	s_barrier
	s_waitcnt lgkmcnt(0)
	v_mfma_f32_16x16x32_bf16 v[126:129], v[142:145], v[178:181], v[126:129]
	v_mfma_f32_16x16x32_bf16 v[122:125], v[154:157], v[178:181], v[122:125]
	v_mfma_f32_16x16x32_bf16 v[110:113], v[142:145], v[186:189], v[110:113]
	v_mfma_f32_16x16x32_bf16 v[106:109], v[154:157], v[186:189], v[106:109]
	v_mfma_f32_16x16x32_bf16 v[94:97], v[142:145], v[204:207], v[94:97]
	v_mfma_f32_16x16x32_bf16 v[90:93], v[154:157], v[204:207], v[90:93]
	v_mfma_f32_16x16x32_bf16 v[78:81], v[142:145], v[212:215], v[78:81]
	v_mfma_f32_16x16x32_bf16 v[74:77], v[154:157], v[212:215], v[74:77]
	v_mfma_f32_16x16x32_bf16 v[126:129], v[146:149], v[182:185], v[126:129]
	v_mfma_f32_16x16x32_bf16 v[122:125], v[158:161], v[182:185], v[122:125]
	v_mfma_f32_16x16x32_bf16 v[110:113], v[146:149], v[190:193], v[110:113]
	v_mfma_f32_16x16x32_bf16 v[106:109], v[158:161], v[190:193], v[106:109]
	v_mfma_f32_16x16x32_bf16 v[94:97], v[146:149], v[208:211], v[94:97]
	v_mfma_f32_16x16x32_bf16 v[90:93], v[158:161], v[208:211], v[90:93]
	v_mfma_f32_16x16x32_bf16 v[78:81], v[146:149], v[228:231], v[78:81]
	v_mfma_f32_16x16x32_bf16 v[74:77], v[158:161], v[228:231], v[74:77]
	v_mfma_f32_16x16x32_bf16 v[118:121], v[162:165], v[178:181], v[118:121]
	v_mfma_f32_16x16x32_bf16 v[114:117], v[170:173], v[178:181], v[114:117]
	v_mfma_f32_16x16x32_bf16 v[102:105], v[162:165], v[186:189], v[102:105]
	v_mfma_f32_16x16x32_bf16 v[98:101], v[170:173], v[186:189], v[98:101]
	v_mfma_f32_16x16x32_bf16 v[86:89], v[162:165], v[204:207], v[86:89]
	v_mfma_f32_16x16x32_bf16 v[82:85], v[170:173], v[204:207], v[82:85]
	v_mfma_f32_16x16x32_bf16 v[70:73], v[162:165], v[212:215], v[70:73]
	v_mfma_f32_16x16x32_bf16 v[66:69], v[170:173], v[212:215], v[66:69]
	v_mfma_f32_16x16x32_bf16 v[118:121], v[166:169], v[182:185], v[118:121]
	v_mfma_f32_16x16x32_bf16 v[114:117], v[174:177], v[182:185], v[114:117]
	v_mfma_f32_16x16x32_bf16 v[102:105], v[166:169], v[190:193], v[102:105]
	v_mfma_f32_16x16x32_bf16 v[98:101], v[174:177], v[190:193], v[98:101]
	v_mfma_f32_16x16x32_bf16 v[86:89], v[166:169], v[208:211], v[86:89]
	v_mfma_f32_16x16x32_bf16 v[82:85], v[174:177], v[208:211], v[82:85]
	v_mfma_f32_16x16x32_bf16 v[70:73], v[166:169], v[228:231], v[70:73]
	v_mfma_f32_16x16x32_bf16 v[66:69], v[174:177], v[228:231], v[66:69]
	s_barrier
	s_add_i32 s57, s57, s42
	v_lshl_add_u64 v[150:151], s[28:29], 0, v[134:135]
	s_mov_b32 m0, s57
	ds_read_b128 v[178:181], v152 offset:16384
	ds_read_b128 v[182:185], v152 offset:17408
	ds_read_b128 v[186:189], v152 offset:18432
	ds_read_b128 v[190:193], v152 offset:19456
	ds_read_b128 v[204:207], v152 offset:20480
	ds_read_b128 v[208:211], v152 offset:21504
	ds_read_b128 v[212:215], v152 offset:22528
	ds_read_b128 v[228:231], v152 offset:23552
	global_load_lds_dwordx4 v[150:151], off
	s_add_i32 m0, s57, 0x2000
	s_add_u32 s58, s28, 0x40000
	v_lshl_add_u64 v[194:195], s[28:29], 0, v[130:131]
	s_addc_u32 s59, s29, 0
	s_add_i32 s57, s60, s42
	global_load_lds_dwordx4 v[194:195], off
	v_lshl_add_u64 v[216:217], s[58:59], 0, v[134:135]
	s_mov_b32 m0, s57
	v_lshl_add_u64 v[232:233], s[30:31], 0, v[132:133]
	global_load_lds_dwordx4 v[216:217], off
	v_lshl_add_u64 v[216:217], s[58:59], 0, v[130:131]
	s_add_i32 m0, s57, 0x2000
	s_nop 0
	global_load_lds_dwordx4 v[216:217], off
	v_lshl_add_u64 v[216:217], s[30:31], 0, v[136:137]
	s_mov_b32 m0, s43
	s_nop 0
	global_load_lds_dwordx4 v[216:217], off
	s_mov_b32 m0, s44
	s_nop 0
	global_load_lds_dwordx4 v[232:233], off
	s_waitcnt vmcnt(8)
	s_waitcnt lgkmcnt(0)
	s_barrier
	s_waitcnt lgkmcnt(0)
	v_mfma_f32_16x16x32_bf16 v[62:65], v[142:145], v[178:181], v[62:65]
	v_mfma_f32_16x16x32_bf16 v[58:61], v[154:157], v[178:181], v[58:61]
	v_mfma_f32_16x16x32_bf16 v[46:49], v[142:145], v[186:189], v[46:49]
	v_mfma_f32_16x16x32_bf16 v[42:45], v[154:157], v[186:189], v[42:45]
	v_mfma_f32_16x16x32_bf16 v[30:33], v[142:145], v[204:207], v[30:33]
	v_mfma_f32_16x16x32_bf16 v[26:29], v[154:157], v[204:207], v[26:29]
	v_mfma_f32_16x16x32_bf16 v[14:17], v[142:145], v[212:215], v[14:17]
	v_mfma_f32_16x16x32_bf16 v[10:13], v[154:157], v[212:215], v[10:13]
	v_mfma_f32_16x16x32_bf16 v[62:65], v[146:149], v[182:185], v[62:65]
	v_mfma_f32_16x16x32_bf16 v[58:61], v[158:161], v[182:185], v[58:61]
	v_mfma_f32_16x16x32_bf16 v[46:49], v[146:149], v[190:193], v[46:49]
	v_mfma_f32_16x16x32_bf16 v[42:45], v[158:161], v[190:193], v[42:45]
	v_mfma_f32_16x16x32_bf16 v[30:33], v[146:149], v[208:211], v[30:33]
	v_mfma_f32_16x16x32_bf16 v[26:29], v[158:161], v[208:211], v[26:29]
	v_mfma_f32_16x16x32_bf16 v[14:17], v[146:149], v[228:231], v[14:17]
	v_mfma_f32_16x16x32_bf16 v[10:13], v[158:161], v[228:231], v[10:13]
	v_mfma_f32_16x16x32_bf16 v[54:57], v[162:165], v[178:181], v[54:57]
	v_mfma_f32_16x16x32_bf16 v[50:53], v[170:173], v[178:181], v[50:53]
	v_mfma_f32_16x16x32_bf16 v[38:41], v[162:165], v[186:189], v[38:41]
	v_mfma_f32_16x16x32_bf16 v[34:37], v[170:173], v[186:189], v[34:37]
	v_mfma_f32_16x16x32_bf16 v[22:25], v[162:165], v[204:207], v[22:25]
	v_mfma_f32_16x16x32_bf16 v[18:21], v[170:173], v[204:207], v[18:21]
	v_mfma_f32_16x16x32_bf16 v[6:9], v[162:165], v[212:215], v[6:9]
	v_mfma_f32_16x16x32_bf16 v[2:5], v[170:173], v[212:215], v[2:5]
	v_mfma_f32_16x16x32_bf16 v[54:57], v[166:169], v[182:185], v[54:57]
	v_mfma_f32_16x16x32_bf16 v[50:53], v[174:177], v[182:185], v[50:53]
	v_mfma_f32_16x16x32_bf16 v[38:41], v[166:169], v[190:193], v[38:41]
	v_mfma_f32_16x16x32_bf16 v[34:37], v[174:177], v[190:193], v[34:37]
	v_mfma_f32_16x16x32_bf16 v[22:25], v[166:169], v[208:211], v[22:25]
	v_mfma_f32_16x16x32_bf16 v[18:21], v[174:177], v[208:211], v[18:21]
	v_mfma_f32_16x16x32_bf16 v[6:9], v[166:169], v[228:231], v[6:9]
	v_mfma_f32_16x16x32_bf16 v[2:5], v[174:177], v[228:231], v[2:5]
	s_barrier
	s_add_i32 s57, 0, 0x18000
	v_add_u32_e32 v153, s57, v1
	s_add_i32 s58, 0, 0x1c000
	ds_read_b128 v[142:145], v153
	ds_read_b128 v[146:149], v153 offset:1024
	ds_read_b128 v[154:157], v153 offset:2048
	ds_read_b128 v[158:161], v153 offset:3072
	v_add_u32_e32 v153, s58, v1
	ds_read_b128 v[162:165], v153
	ds_read_b128 v[166:169], v153 offset:1024
	ds_read_b128 v[170:173], v153 offset:2048
	ds_read_b128 v[174:177], v153 offset:3072
	s_add_u32 s30, s30, 0x40000
	s_addc_u32 s31, s31, 0
	s_mov_b32 m0, s45
	v_lshl_add_u64 v[234:235], s[30:31], 0, v[136:137]
	ds_read_b128 v[178:181], v152 offset:32768
	ds_read_b128 v[182:185], v152 offset:33792
	ds_read_b128 v[186:189], v152 offset:34816
	ds_read_b128 v[190:193], v152 offset:35840
	ds_read_b128 v[204:207], v152 offset:36864
	ds_read_b128 v[208:211], v152 offset:37888
	ds_read_b128 v[212:215], v152 offset:38912
	ds_read_b128 v[228:231], v152 offset:39936
	global_load_lds_dwordx4 v[234:235], off
	v_lshl_add_u64 v[234:235], s[30:31], 0, v[132:133]
	s_mov_b32 m0, s46
	s_nop 0
	global_load_lds_dwordx4 v[234:235], off
	s_waitcnt vmcnt(8)
	s_waitcnt lgkmcnt(0)
	s_barrier
	s_waitcnt lgkmcnt(0)
	v_mfma_f32_16x16x32_bf16 v[126:129], v[142:145], v[178:181], v[126:129]
	v_mfma_f32_16x16x32_bf16 v[122:125], v[154:157], v[178:181], v[122:125]
	v_mfma_f32_16x16x32_bf16 v[110:113], v[142:145], v[186:189], v[110:113]
	v_mfma_f32_16x16x32_bf16 v[106:109], v[154:157], v[186:189], v[106:109]
	v_mfma_f32_16x16x32_bf16 v[94:97], v[142:145], v[204:207], v[94:97]
	v_mfma_f32_16x16x32_bf16 v[90:93], v[154:157], v[204:207], v[90:93]
	v_mfma_f32_16x16x32_bf16 v[78:81], v[142:145], v[212:215], v[78:81]
	v_mfma_f32_16x16x32_bf16 v[74:77], v[154:157], v[212:215], v[74:77]
	v_mfma_f32_16x16x32_bf16 v[126:129], v[146:149], v[182:185], v[126:129]
	v_mfma_f32_16x16x32_bf16 v[122:125], v[158:161], v[182:185], v[122:125]
	v_mfma_f32_16x16x32_bf16 v[110:113], v[146:149], v[190:193], v[110:113]
	v_mfma_f32_16x16x32_bf16 v[106:109], v[158:161], v[190:193], v[106:109]
	v_mfma_f32_16x16x32_bf16 v[94:97], v[146:149], v[208:211], v[94:97]
	v_mfma_f32_16x16x32_bf16 v[90:93], v[158:161], v[208:211], v[90:93]
	v_mfma_f32_16x16x32_bf16 v[78:81], v[146:149], v[228:231], v[78:81]
	v_mfma_f32_16x16x32_bf16 v[74:77], v[158:161], v[228:231], v[74:77]
	v_mfma_f32_16x16x32_bf16 v[118:121], v[162:165], v[178:181], v[118:121]
	v_mfma_f32_16x16x32_bf16 v[114:117], v[170:173], v[178:181], v[114:117]
	v_mfma_f32_16x16x32_bf16 v[102:105], v[162:165], v[186:189], v[102:105]
	v_mfma_f32_16x16x32_bf16 v[98:101], v[170:173], v[186:189], v[98:101]
	v_mfma_f32_16x16x32_bf16 v[86:89], v[162:165], v[204:207], v[86:89]
	v_mfma_f32_16x16x32_bf16 v[82:85], v[170:173], v[204:207], v[82:85]
	v_mfma_f32_16x16x32_bf16 v[70:73], v[162:165], v[212:215], v[70:73]
	v_mfma_f32_16x16x32_bf16 v[66:69], v[170:173], v[212:215], v[66:69]
	v_mfma_f32_16x16x32_bf16 v[118:121], v[166:169], v[182:185], v[118:121]
	v_mfma_f32_16x16x32_bf16 v[114:117], v[174:177], v[182:185], v[114:117]
	v_mfma_f32_16x16x32_bf16 v[102:105], v[166:169], v[190:193], v[102:105]
	v_mfma_f32_16x16x32_bf16 v[98:101], v[174:177], v[190:193], v[98:101]
	v_mfma_f32_16x16x32_bf16 v[86:89], v[166:169], v[208:211], v[86:89]
	v_mfma_f32_16x16x32_bf16 v[82:85], v[174:177], v[208:211], v[82:85]
	v_mfma_f32_16x16x32_bf16 v[70:73], v[166:169], v[228:231], v[70:73]
	v_mfma_f32_16x16x32_bf16 v[66:69], v[174:177], v[228:231], v[66:69]
	s_barrier
	s_add_i32 s30, s57, s42
	v_lshl_add_u64 v[150:151], v[150:151], 0, s[94:95]
	s_mov_b32 m0, s30
	ds_read_b128 v[178:181], v152 offset:49152
	ds_read_b128 v[182:185], v152 offset:50176
	ds_read_b128 v[186:189], v152 offset:51200
	ds_read_b128 v[190:193], v152 offset:52224
	ds_read_b128 v[204:207], v152 offset:53248
	ds_read_b128 v[208:211], v152 offset:54272
	ds_read_b128 v[212:215], v152 offset:55296
	ds_read_b128 v[228:231], v152 offset:56320
	global_load_lds_dwordx4 v[150:151], off
	s_add_i32 m0, s30, 0x2000
	s_add_u32 s28, s28, 0x40080
	v_lshl_add_u64 v[150:151], v[194:195], 0, s[94:95]
	s_addc_u32 s29, s29, 0
	s_add_i32 s30, s58, s42
	global_load_lds_dwordx4 v[150:151], off
	v_lshl_add_u64 v[150:151], s[28:29], 0, v[134:135]
	s_mov_b32 m0, s30
	s_nop 0
	global_load_lds_dwordx4 v[150:151], off
	v_lshl_add_u64 v[150:151], s[28:29], 0, v[130:131]
	s_add_i32 m0, s30, 0x2000
	s_nop 0
	global_load_lds_dwordx4 v[150:151], off
	v_lshl_add_u64 v[150:151], v[216:217], 0, s[94:95]
	s_mov_b32 m0, s49
	s_nop 0
	global_load_lds_dwordx4 v[150:151], off
	v_lshl_add_u64 v[150:151], v[232:233], 0, s[94:95]
	s_mov_b32 m0, s50
	s_nop 0
	global_load_lds_dwordx4 v[150:151], off
	s_waitcnt vmcnt(8)
	s_waitcnt lgkmcnt(0)
	s_barrier
	s_waitcnt lgkmcnt(0)
	v_mfma_f32_16x16x32_bf16 v[62:65], v[142:145], v[178:181], v[62:65]
	v_mfma_f32_16x16x32_bf16 v[58:61], v[154:157], v[178:181], v[58:61]
	v_mfma_f32_16x16x32_bf16 v[46:49], v[142:145], v[186:189], v[46:49]
	v_mfma_f32_16x16x32_bf16 v[42:45], v[154:157], v[186:189], v[42:45]
	v_mfma_f32_16x16x32_bf16 v[30:33], v[142:145], v[204:207], v[30:33]
	v_mfma_f32_16x16x32_bf16 v[26:29], v[154:157], v[204:207], v[26:29]
	v_mfma_f32_16x16x32_bf16 v[14:17], v[142:145], v[212:215], v[14:17]
	v_mfma_f32_16x16x32_bf16 v[10:13], v[154:157], v[212:215], v[10:13]
	v_mfma_f32_16x16x32_bf16 v[62:65], v[146:149], v[182:185], v[62:65]
	v_mfma_f32_16x16x32_bf16 v[58:61], v[158:161], v[182:185], v[58:61]
	v_mfma_f32_16x16x32_bf16 v[46:49], v[146:149], v[190:193], v[46:49]
	v_mfma_f32_16x16x32_bf16 v[42:45], v[158:161], v[190:193], v[42:45]
	v_mfma_f32_16x16x32_bf16 v[30:33], v[146:149], v[208:211], v[30:33]
	v_mfma_f32_16x16x32_bf16 v[26:29], v[158:161], v[208:211], v[26:29]
	v_mfma_f32_16x16x32_bf16 v[14:17], v[146:149], v[228:231], v[14:17]
	v_mfma_f32_16x16x32_bf16 v[10:13], v[158:161], v[228:231], v[10:13]
	v_mfma_f32_16x16x32_bf16 v[54:57], v[162:165], v[178:181], v[54:57]
	v_mfma_f32_16x16x32_bf16 v[50:53], v[170:173], v[178:181], v[50:53]
	v_mfma_f32_16x16x32_bf16 v[38:41], v[162:165], v[186:189], v[38:41]
	v_mfma_f32_16x16x32_bf16 v[34:37], v[170:173], v[186:189], v[34:37]
	v_mfma_f32_16x16x32_bf16 v[22:25], v[162:165], v[204:207], v[22:25]
	v_mfma_f32_16x16x32_bf16 v[18:21], v[170:173], v[204:207], v[18:21]
	v_mfma_f32_16x16x32_bf16 v[6:9], v[162:165], v[212:215], v[6:9]
	v_mfma_f32_16x16x32_bf16 v[2:5], v[170:173], v[212:215], v[2:5]
	v_mfma_f32_16x16x32_bf16 v[54:57], v[166:169], v[182:185], v[54:57]
	v_mfma_f32_16x16x32_bf16 v[50:53], v[174:177], v[182:185], v[50:53]
	v_mfma_f32_16x16x32_bf16 v[38:41], v[166:169], v[190:193], v[38:41]
	v_mfma_f32_16x16x32_bf16 v[34:37], v[174:177], v[190:193], v[34:37]
	v_mfma_f32_16x16x32_bf16 v[22:25], v[166:169], v[208:211], v[22:25]
	v_mfma_f32_16x16x32_bf16 v[18:21], v[174:177], v[208:211], v[18:21]
	v_mfma_f32_16x16x32_bf16 v[6:9], v[166:169], v[228:231], v[6:9]
	v_mfma_f32_16x16x32_bf16 v[2:5], v[174:177], v[228:231], v[2:5]
	s_barrier
	s_add_i32 s56, s56, 2
	s_add_u32 s26, s26, 0x100
	s_addc_u32 s27, s27, 0
	s_add_u32 s54, s54, 0x100
	s_addc_u32 s55, s55, 0
	s_cmp_gt_u32 s56, 13
	s_cbranch_scc0 .LBB0_111
	s_and_b64 vcc, exec, s[14:15]
	s_cbranch_vccz .LBB0_114
	s_barrier

.LBB0_139:
	s_add_u32 s28, s26, 0xfffc0080
	s_addc_u32 s29, s27, -1
	s_add_i32 s64, 0, 0x10000
	s_cmp_eq_u32 s63, 12
	s_cselect_b32 s31, s21, s29
	s_cselect_b32 s30, s59, s28
	v_add_u32_e32 v143, s64, v1
	s_cselect_b32 s29, s19, s62
	s_cselect_b32 s28, s60, s61
	s_add_i32 s66, 0, 0x14000
	ds_read_b128 v[144:147], v143
	ds_read_b128 v[148:151], v143 offset:1024
	ds_read_b128 v[152:155], v143 offset:2048
	ds_read_b128 v[156:159], v143 offset:3072
	v_add_u32_e32 v143, s66, v1
	ds_read_b128 v[160:163], v143
	ds_read_b128 v[164:167], v143 offset:1024
	ds_read_b128 v[168:171], v143 offset:2048
	ds_read_b128 v[172:175], v143 offset:3072
	v_lshl_add_u64 v[216:217], s[26:27], 0, v[138:139]
	s_add_i32 m0, s50, 0xc000
	ds_read_b128 v[176:179], v142
	ds_read_b128 v[180:183], v142 offset:1024
	ds_read_b128 v[184:187], v142 offset:2048
	ds_read_b128 v[188:191], v142 offset:3072
	ds_read_b128 v[192:195], v142 offset:4096
	ds_read_b128 v[204:207], v142 offset:5120
	ds_read_b128 v[208:211], v142 offset:6144
	ds_read_b128 v[212:215], v142 offset:7168
	global_load_lds_dwordx4 v[216:217], off
	v_lshl_add_u64 v[216:217], s[26:27], 0, v[140:141]
	s_add_i32 m0, s50, 0xe000
	s_nop 0
	global_load_lds_dwordx4 v[216:217], off
	s_waitcnt vmcnt(8)
	s_waitcnt lgkmcnt(0)
	s_barrier
	s_waitcnt lgkmcnt(0)
	v_mfma_f32_16x16x32_bf16 v[126:129], v[144:147], v[176:179], v[126:129]
	v_mfma_f32_16x16x32_bf16 v[122:125], v[152:155], v[176:179], v[122:125]
	v_mfma_f32_16x16x32_bf16 v[118:121], v[144:147], v[184:187], v[118:121]
	v_mfma_f32_16x16x32_bf16 v[114:117], v[152:155], v[184:187], v[114:117]
	v_mfma_f32_16x16x32_bf16 v[102:105], v[144:147], v[192:195], v[102:105]
	v_mfma_f32_16x16x32_bf16 v[98:101], v[152:155], v[192:195], v[98:101]
	v_mfma_f32_16x16x32_bf16 v[86:89], v[144:147], v[208:211], v[86:89]
	v_mfma_f32_16x16x32_bf16 v[82:85], v[152:155], v[208:211], v[82:85]
	v_mfma_f32_16x16x32_bf16 v[126:129], v[148:151], v[180:183], v[126:129]
	v_mfma_f32_16x16x32_bf16 v[122:125], v[156:159], v[180:183], v[122:125]
	v_mfma_f32_16x16x32_bf16 v[118:121], v[148:151], v[188:191], v[118:121]
	v_mfma_f32_16x16x32_bf16 v[114:117], v[156:159], v[188:191], v[114:117]
	v_mfma_f32_16x16x32_bf16 v[102:105], v[148:151], v[204:207], v[102:105]
	v_mfma_f32_16x16x32_bf16 v[98:101], v[156:159], v[204:207], v[98:101]
	v_mfma_f32_16x16x32_bf16 v[86:89], v[148:151], v[212:215], v[86:89]
	v_mfma_f32_16x16x32_bf16 v[82:85], v[156:159], v[212:215], v[82:85]
	v_mfma_f32_16x16x32_bf16 v[110:113], v[160:163], v[176:179], v[110:113]
	v_mfma_f32_16x16x32_bf16 v[106:109], v[168:171], v[176:179], v[106:109]
	v_mfma_f32_16x16x32_bf16 v[94:97], v[160:163], v[184:187], v[94:97]
	v_mfma_f32_16x16x32_bf16 v[90:93], v[168:171], v[184:187], v[90:93]
	v_mfma_f32_16x16x32_bf16 v[78:81], v[160:163], v[192:195], v[78:81]
	v_mfma_f32_16x16x32_bf16 v[74:77], v[168:171], v[192:195], v[74:77]
	v_mfma_f32_16x16x32_bf16 v[70:73], v[160:163], v[208:211], v[70:73]
	v_mfma_f32_16x16x32_bf16 v[66:69], v[168:171], v[208:211], v[66:69]
	v_mfma_f32_16x16x32_bf16 v[110:113], v[164:167], v[180:183], v[110:113]
	v_mfma_f32_16x16x32_bf16 v[106:109], v[172:175], v[180:183], v[106:109]
	v_mfma_f32_16x16x32_bf16 v[94:97], v[164:167], v[188:191], v[94:97]
	v_mfma_f32_16x16x32_bf16 v[90:93], v[172:175], v[188:191], v[90:93]
	v_mfma_f32_16x16x32_bf16 v[78:81], v[164:167], v[204:207], v[78:81]
	v_mfma_f32_16x16x32_bf16 v[74:77], v[172:175], v[204:207], v[74:77]
	v_mfma_f32_16x16x32_bf16 v[70:73], v[164:167], v[212:215], v[70:73]
	v_mfma_f32_16x16x32_bf16 v[66:69], v[172:175], v[212:215], v[66:69]
	s_barrier
	s_add_i32 s64, s64, s49
	v_lshl_add_u64 v[216:217], s[28:29], 0, v[132:133]
	s_mov_b32 m0, s64
	ds_read_b128 v[176:179], v142 offset:16384
	ds_read_b128 v[180:183], v142 offset:17408
	ds_read_b128 v[184:187], v142 offset:18432
	ds_read_b128 v[188:191], v142 offset:19456
	ds_read_b128 v[192:195], v142 offset:20480
	ds_read_b128 v[204:207], v142 offset:21504
	ds_read_b128 v[208:211], v142 offset:22528
	ds_read_b128 v[212:215], v142 offset:23552
	global_load_lds_dwordx4 v[216:217], off
	s_add_i32 m0, s64, 0x2000
	s_add_u32 s64, s28, 0x40000
	v_lshl_add_u64 v[228:229], s[28:29], 0, v[136:137]
	s_addc_u32 s65, s29, 0
	s_add_i32 s66, s66, s49
	global_load_lds_dwordx4 v[228:229], off
	v_lshl_add_u64 v[230:231], s[64:65], 0, v[132:133]
	s_mov_b32 m0, s66
	v_lshl_add_u64 v[232:233], s[30:31], 0, v[134:135]
	global_load_lds_dwordx4 v[230:231], off
	v_lshl_add_u64 v[230:231], s[64:65], 0, v[136:137]
	s_add_i32 m0, s66, 0x2000
	s_nop 0
	global_load_lds_dwordx4 v[230:231], off
	v_lshl_add_u64 v[230:231], s[30:31], 0, v[130:131]
	s_mov_b32 m0, s50
	s_nop 0
	global_load_lds_dwordx4 v[230:231], off
	s_mov_b32 m0, s51
	s_nop 0
	global_load_lds_dwordx4 v[232:233], off
	s_waitcnt vmcnt(8)
	s_waitcnt lgkmcnt(0)
	s_barrier
	s_waitcnt lgkmcnt(0)
	v_mfma_f32_16x16x32_bf16 v[62:65], v[144:147], v[176:179], v[62:65]
	v_mfma_f32_16x16x32_bf16 v[58:61], v[152:155], v[176:179], v[58:61]
	v_mfma_f32_16x16x32_bf16 v[54:57], v[144:147], v[184:187], v[54:57]
	v_mfma_f32_16x16x32_bf16 v[50:53], v[152:155], v[184:187], v[50:53]
	v_mfma_f32_16x16x32_bf16 v[38:41], v[144:147], v[192:195], v[38:41]
	v_mfma_f32_16x16x32_bf16 v[34:37], v[152:155], v[192:195], v[34:37]
	v_mfma_f32_16x16x32_bf16 v[22:25], v[144:147], v[208:211], v[22:25]
	v_mfma_f32_16x16x32_bf16 v[18:21], v[152:155], v[208:211], v[18:21]
	v_mfma_f32_16x16x32_bf16 v[62:65], v[148:151], v[180:183], v[62:65]
	v_mfma_f32_16x16x32_bf16 v[58:61], v[156:159], v[180:183], v[58:61]
	v_mfma_f32_16x16x32_bf16 v[54:57], v[148:151], v[188:191], v[54:57]
	v_mfma_f32_16x16x32_bf16 v[50:53], v[156:159], v[188:191], v[50:53]
	v_mfma_f32_16x16x32_bf16 v[38:41], v[148:151], v[204:207], v[38:41]
	v_mfma_f32_16x16x32_bf16 v[34:37], v[156:159], v[204:207], v[34:37]
	v_mfma_f32_16x16x32_bf16 v[22:25], v[148:151], v[212:215], v[22:25]
	v_mfma_f32_16x16x32_bf16 v[18:21], v[156:159], v[212:215], v[18:21]
	v_mfma_f32_16x16x32_bf16 v[46:49], v[160:163], v[176:179], v[46:49]
	v_mfma_f32_16x16x32_bf16 v[42:45], v[168:171], v[176:179], v[42:45]
	v_mfma_f32_16x16x32_bf16 v[30:33], v[160:163], v[184:187], v[30:33]
	v_mfma_f32_16x16x32_bf16 v[26:29], v[168:171], v[184:187], v[26:29]
	v_mfma_f32_16x16x32_bf16 v[14:17], v[160:163], v[192:195], v[14:17]
	v_mfma_f32_16x16x32_bf16 v[10:13], v[168:171], v[192:195], v[10:13]
	v_mfma_f32_16x16x32_bf16 v[6:9], v[160:163], v[208:211], v[6:9]
	v_mfma_f32_16x16x32_bf16 v[2:5], v[168:171], v[208:211], v[2:5]
	v_mfma_f32_16x16x32_bf16 v[46:49], v[164:167], v[180:183], v[46:49]
	v_mfma_f32_16x16x32_bf16 v[42:45], v[172:175], v[180:183], v[42:45]
	v_mfma_f32_16x16x32_bf16 v[30:33], v[164:167], v[188:191], v[30:33]
	v_mfma_f32_16x16x32_bf16 v[26:29], v[172:175], v[188:191], v[26:29]
	v_mfma_f32_16x16x32_bf16 v[14:17], v[164:167], v[204:207], v[14:17]
	v_mfma_f32_16x16x32_bf16 v[10:13], v[172:175], v[204:207], v[10:13]
	v_mfma_f32_16x16x32_bf16 v[6:9], v[164:167], v[212:215], v[6:9]
	v_mfma_f32_16x16x32_bf16 v[2:5], v[172:175], v[212:215], v[2:5]
	s_barrier
	s_add_i32 s64, 0, 0x18000
	v_add_u32_e32 v143, s64, v1
	s_add_i32 s65, 0, 0x1c000
	ds_read_b128 v[144:147], v143
	ds_read_b128 v[148:151], v143 offset:1024
	ds_read_b128 v[152:155], v143 offset:2048
	ds_read_b128 v[156:159], v143 offset:3072
	v_add_u32_e32 v143, s65, v1
	ds_read_b128 v[160:163], v143
	ds_read_b128 v[164:167], v143 offset:1024
	ds_read_b128 v[168:171], v143 offset:2048
	ds_read_b128 v[172:175], v143 offset:3072
	s_add_u32 s30, s30, 0x40000
	s_addc_u32 s31, s31, 0
	s_mov_b32 m0, s52
	v_lshl_add_u64 v[234:235], s[30:31], 0, v[130:131]
	ds_read_b128 v[176:179], v142 offset:32768
	ds_read_b128 v[180:183], v142 offset:33792
	ds_read_b128 v[184:187], v142 offset:34816
	ds_read_b128 v[188:191], v142 offset:35840
	ds_read_b128 v[192:195], v142 offset:36864
	ds_read_b128 v[204:207], v142 offset:37888
	ds_read_b128 v[208:211], v142 offset:38912
	ds_read_b128 v[212:215], v142 offset:39936
	global_load_lds_dwordx4 v[234:235], off
	v_lshl_add_u64 v[234:235], s[30:31], 0, v[134:135]
	s_mov_b32 m0, s53
	s_nop 0
	global_load_lds_dwordx4 v[234:235], off
	s_waitcnt vmcnt(8)
	s_waitcnt lgkmcnt(0)
	s_barrier
	s_waitcnt lgkmcnt(0)
	v_mfma_f32_16x16x32_bf16 v[126:129], v[144:147], v[176:179], v[126:129]
	v_mfma_f32_16x16x32_bf16 v[122:125], v[152:155], v[176:179], v[122:125]
	v_mfma_f32_16x16x32_bf16 v[118:121], v[144:147], v[184:187], v[118:121]
	v_mfma_f32_16x16x32_bf16 v[114:117], v[152:155], v[184:187], v[114:117]
	v_mfma_f32_16x16x32_bf16 v[102:105], v[144:147], v[192:195], v[102:105]
	v_mfma_f32_16x16x32_bf16 v[98:101], v[152:155], v[192:195], v[98:101]
	v_mfma_f32_16x16x32_bf16 v[86:89], v[144:147], v[208:211], v[86:89]
	v_mfma_f32_16x16x32_bf16 v[82:85], v[152:155], v[208:211], v[82:85]
	v_mfma_f32_16x16x32_bf16 v[126:129], v[148:151], v[180:183], v[126:129]
	v_mfma_f32_16x16x32_bf16 v[122:125], v[156:159], v[180:183], v[122:125]
	v_mfma_f32_16x16x32_bf16 v[118:121], v[148:151], v[188:191], v[118:121]
	v_mfma_f32_16x16x32_bf16 v[114:117], v[156:159], v[188:191], v[114:117]
	v_mfma_f32_16x16x32_bf16 v[102:105], v[148:151], v[204:207], v[102:105]
	v_mfma_f32_16x16x32_bf16 v[98:101], v[156:159], v[204:207], v[98:101]
	v_mfma_f32_16x16x32_bf16 v[86:89], v[148:151], v[212:215], v[86:89]
	v_mfma_f32_16x16x32_bf16 v[82:85], v[156:159], v[212:215], v[82:85]
	v_mfma_f32_16x16x32_bf16 v[110:113], v[160:163], v[176:179], v[110:113]
	v_mfma_f32_16x16x32_bf16 v[106:109], v[168:171], v[176:179], v[106:109]
	v_mfma_f32_16x16x32_bf16 v[94:97], v[160:163], v[184:187], v[94:97]
	v_mfma_f32_16x16x32_bf16 v[90:93], v[168:171], v[184:187], v[90:93]
	v_mfma_f32_16x16x32_bf16 v[78:81], v[160:163], v[192:195], v[78:81]
	v_mfma_f32_16x16x32_bf16 v[74:77], v[168:171], v[192:195], v[74:77]
	v_mfma_f32_16x16x32_bf16 v[70:73], v[160:163], v[208:211], v[70:73]
	v_mfma_f32_16x16x32_bf16 v[66:69], v[168:171], v[208:211], v[66:69]
	v_mfma_f32_16x16x32_bf16 v[110:113], v[164:167], v[180:183], v[110:113]
	v_mfma_f32_16x16x32_bf16 v[106:109], v[172:175], v[180:183], v[106:109]
	v_mfma_f32_16x16x32_bf16 v[94:97], v[164:167], v[188:191], v[94:97]
	v_mfma_f32_16x16x32_bf16 v[90:93], v[172:175], v[188:191], v[90:93]
	v_mfma_f32_16x16x32_bf16 v[78:81], v[164:167], v[204:207], v[78:81]
	v_mfma_f32_16x16x32_bf16 v[74:77], v[172:175], v[204:207], v[74:77]
	v_mfma_f32_16x16x32_bf16 v[70:73], v[164:167], v[212:215], v[70:73]
	v_mfma_f32_16x16x32_bf16 v[66:69], v[172:175], v[212:215], v[66:69]
	s_barrier
	s_add_i32 s30, s64, s49
	v_lshl_add_u64 v[216:217], v[216:217], 0, s[94:95]
	s_mov_b32 m0, s30
	ds_read_b128 v[176:179], v142 offset:49152
	ds_read_b128 v[180:183], v142 offset:50176
	ds_read_b128 v[184:187], v142 offset:51200
	ds_read_b128 v[188:191], v142 offset:52224
	ds_read_b128 v[192:195], v142 offset:53248
	ds_read_b128 v[204:207], v142 offset:54272
	ds_read_b128 v[208:211], v142 offset:55296
	ds_read_b128 v[212:215], v142 offset:56320
	global_load_lds_dwordx4 v[216:217], off
	s_add_i32 m0, s30, 0x2000
	s_add_u32 s28, s28, 0x40080
	v_lshl_add_u64 v[216:217], v[228:229], 0, s[94:95]
	s_addc_u32 s29, s29, 0
	s_add_i32 s30, s65, s49
	global_load_lds_dwordx4 v[216:217], off
	v_lshl_add_u64 v[216:217], s[28:29], 0, v[132:133]
	s_mov_b32 m0, s30
	s_nop 0
	global_load_lds_dwordx4 v[216:217], off
	v_lshl_add_u64 v[216:217], s[28:29], 0, v[136:137]
	s_add_i32 m0, s30, 0x2000
	s_nop 0
	global_load_lds_dwordx4 v[216:217], off
	v_lshl_add_u64 v[216:217], v[230:231], 0, s[94:95]
	s_mov_b32 m0, s56
	s_nop 0
	global_load_lds_dwordx4 v[216:217], off
	v_lshl_add_u64 v[216:217], v[232:233], 0, s[94:95]
	s_mov_b32 m0, s57
	s_nop 0
	global_load_lds_dwordx4 v[216:217], off
	s_waitcnt vmcnt(8)
	s_waitcnt lgkmcnt(0)
	s_barrier
	s_waitcnt lgkmcnt(0)
	v_mfma_f32_16x16x32_bf16 v[62:65], v[144:147], v[176:179], v[62:65]
	v_mfma_f32_16x16x32_bf16 v[58:61], v[152:155], v[176:179], v[58:61]
	v_mfma_f32_16x16x32_bf16 v[54:57], v[144:147], v[184:187], v[54:57]
	v_mfma_f32_16x16x32_bf16 v[50:53], v[152:155], v[184:187], v[50:53]
	v_mfma_f32_16x16x32_bf16 v[38:41], v[144:147], v[192:195], v[38:41]
	v_mfma_f32_16x16x32_bf16 v[34:37], v[152:155], v[192:195], v[34:37]
	v_mfma_f32_16x16x32_bf16 v[22:25], v[144:147], v[208:211], v[22:25]
	v_mfma_f32_16x16x32_bf16 v[18:21], v[152:155], v[208:211], v[18:21]
	v_mfma_f32_16x16x32_bf16 v[62:65], v[148:151], v[180:183], v[62:65]
	v_mfma_f32_16x16x32_bf16 v[58:61], v[156:159], v[180:183], v[58:61]
	v_mfma_f32_16x16x32_bf16 v[54:57], v[148:151], v[188:191], v[54:57]
	v_mfma_f32_16x16x32_bf16 v[50:53], v[156:159], v[188:191], v[50:53]
	v_mfma_f32_16x16x32_bf16 v[38:41], v[148:151], v[204:207], v[38:41]
	v_mfma_f32_16x16x32_bf16 v[34:37], v[156:159], v[204:207], v[34:37]
	v_mfma_f32_16x16x32_bf16 v[22:25], v[148:151], v[212:215], v[22:25]
	v_mfma_f32_16x16x32_bf16 v[18:21], v[156:159], v[212:215], v[18:21]
	v_mfma_f32_16x16x32_bf16 v[46:49], v[160:163], v[176:179], v[46:49]
	v_mfma_f32_16x16x32_bf16 v[42:45], v[168:171], v[176:179], v[42:45]
	v_mfma_f32_16x16x32_bf16 v[30:33], v[160:163], v[184:187], v[30:33]
	v_mfma_f32_16x16x32_bf16 v[26:29], v[168:171], v[184:187], v[26:29]
	v_mfma_f32_16x16x32_bf16 v[14:17], v[160:163], v[192:195], v[14:17]
	v_mfma_f32_16x16x32_bf16 v[10:13], v[168:171], v[192:195], v[10:13]
	v_mfma_f32_16x16x32_bf16 v[6:9], v[160:163], v[208:211], v[6:9]
	v_mfma_f32_16x16x32_bf16 v[2:5], v[168:171], v[208:211], v[2:5]
	v_mfma_f32_16x16x32_bf16 v[46:49], v[164:167], v[180:183], v[46:49]
	v_mfma_f32_16x16x32_bf16 v[42:45], v[172:175], v[180:183], v[42:45]
	v_mfma_f32_16x16x32_bf16 v[30:33], v[164:167], v[188:191], v[30:33]
	v_mfma_f32_16x16x32_bf16 v[26:29], v[172:175], v[188:191], v[26:29]
	v_mfma_f32_16x16x32_bf16 v[14:17], v[164:167], v[204:207], v[14:17]
	v_mfma_f32_16x16x32_bf16 v[10:13], v[172:175], v[204:207], v[10:13]
	v_mfma_f32_16x16x32_bf16 v[6:9], v[164:167], v[212:215], v[6:9]
	v_mfma_f32_16x16x32_bf16 v[2:5], v[172:175], v[212:215], v[2:5]
	s_barrier
	s_add_i32 s63, s63, 2
	s_add_u32 s26, s26, 0x100
	s_addc_u32 s27, s27, 0
	s_add_u32 s61, s61, 0x100
	s_addc_u32 s62, s62, 0
	s_cmp_gt_u32 s63, 13
	s_cbranch_scc0 .LBB0_139
	s_and_b64 vcc, exec, s[10:11]
	s_cbranch_vccz .LBB0_142
	s_barrier

.LBB0_220:
	s_add_u32 s26, s24, 0x100
	s_addc_u32 s27, s25, 0
	s_add_i32 s59, 0, 0x10000
	s_cmp_eq_u32 s58, 40
	s_cselect_b32 s31, s7, s27
	s_cselect_b32 s30, s6, s26
	s_cselect_b32 s29, s23, s57
	s_cselect_b32 s28, s22, s56
	s_add_i32 s60, 0, 0x14000
	v_add_u32_e32 v134, s59, v1
	v_add_u32_e32 v154, s60, v1
	ds_read_b128 v[110:113], v134
	ds_read_b128 v[118:121], v134 offset:1024
	ds_read_b128 v[122:125], v134 offset:2048
	ds_read_b128 v[134:137], v134 offset:3072
	ds_read_b128 v[138:141], v154
	ds_read_b128 v[142:145], v154 offset:1024
	ds_read_b128 v[146:149], v154 offset:2048
	ds_read_b128 v[154:157], v154 offset:3072
	v_lshl_add_u64 v[216:217], s[24:25], 0, v[206:207]
	s_add_i32 m0, s41, 0xc000
	ds_read_b128 v[162:165], v214
	ds_read_b128 v[166:169], v214 offset:1024
	ds_read_b128 v[170:173], v214 offset:2048
	ds_read_b128 v[174:177], v214 offset:3072
	ds_read_b128 v[178:181], v214 offset:4096
	ds_read_b128 v[182:185], v214 offset:5120
	ds_read_b128 v[186:189], v214 offset:6144
	ds_read_b128 v[210:213], v214 offset:7168
	global_load_lds_dwordx4 v[216:217], off
	v_lshl_add_u64 v[216:217], s[24:25], 0, v[208:209]
	s_add_i32 m0, s41, 0xe000
	s_nop 0
	global_load_lds_dwordx4 v[216:217], off
	s_waitcnt vmcnt(8)
	s_waitcnt lgkmcnt(0)
	s_barrier
	s_waitcnt lgkmcnt(0)
	v_mfma_f32_16x16x32_bf16 v[158:161], v[110:113], v[162:165], v[158:161]
	v_mfma_f32_16x16x32_bf16 v[150:153], v[122:125], v[162:165], v[150:153]
	v_mfma_f32_16x16x32_bf16 v[114:117], v[110:113], v[170:173], v[114:117]
	v_mfma_f32_16x16x32_bf16 v[106:109], v[122:125], v[170:173], v[106:109]
	v_mfma_f32_16x16x32_bf16 v[94:97], v[110:113], v[178:181], v[94:97]
	v_mfma_f32_16x16x32_bf16 v[90:93], v[122:125], v[178:181], v[90:93]
	v_mfma_f32_16x16x32_bf16 v[78:81], v[110:113], v[186:189], v[78:81]
	v_mfma_f32_16x16x32_bf16 v[74:77], v[122:125], v[186:189], v[74:77]
	v_mfma_f32_16x16x32_bf16 v[158:161], v[118:121], v[166:169], v[158:161]
	v_mfma_f32_16x16x32_bf16 v[150:153], v[134:137], v[166:169], v[150:153]
	v_mfma_f32_16x16x32_bf16 v[114:117], v[118:121], v[174:177], v[114:117]
	v_mfma_f32_16x16x32_bf16 v[106:109], v[134:137], v[174:177], v[106:109]
	v_mfma_f32_16x16x32_bf16 v[94:97], v[118:121], v[182:185], v[94:97]
	v_mfma_f32_16x16x32_bf16 v[90:93], v[134:137], v[182:185], v[90:93]
	v_mfma_f32_16x16x32_bf16 v[78:81], v[118:121], v[210:213], v[78:81]
	v_mfma_f32_16x16x32_bf16 v[74:77], v[134:137], v[210:213], v[74:77]
	v_mfma_f32_16x16x32_bf16 v[130:133], v[138:141], v[162:165], v[130:133]
	v_mfma_f32_16x16x32_bf16 v[126:129], v[146:149], v[162:165], v[126:129]
	v_mfma_f32_16x16x32_bf16 v[102:105], v[138:141], v[170:173], v[102:105]
	v_mfma_f32_16x16x32_bf16 v[98:101], v[146:149], v[170:173], v[98:101]
	v_mfma_f32_16x16x32_bf16 v[86:89], v[138:141], v[178:181], v[86:89]
	v_mfma_f32_16x16x32_bf16 v[82:85], v[146:149], v[178:181], v[82:85]
	v_mfma_f32_16x16x32_bf16 v[70:73], v[138:141], v[186:189], v[70:73]
	v_mfma_f32_16x16x32_bf16 v[66:69], v[146:149], v[186:189], v[66:69]
	v_mfma_f32_16x16x32_bf16 v[130:133], v[142:145], v[166:169], v[130:133]
	v_mfma_f32_16x16x32_bf16 v[126:129], v[154:157], v[166:169], v[126:129]
	v_mfma_f32_16x16x32_bf16 v[102:105], v[142:145], v[174:177], v[102:105]
	v_mfma_f32_16x16x32_bf16 v[98:101], v[154:157], v[174:177], v[98:101]
	v_mfma_f32_16x16x32_bf16 v[86:89], v[142:145], v[182:185], v[86:89]
	v_mfma_f32_16x16x32_bf16 v[82:85], v[154:157], v[182:185], v[82:85]
	v_mfma_f32_16x16x32_bf16 v[70:73], v[142:145], v[210:213], v[70:73]
	v_mfma_f32_16x16x32_bf16 v[66:69], v[154:157], v[210:213], v[66:69]
	s_barrier
	s_add_i32 s24, s59, s40
	v_lshl_add_u64 v[216:217], s[28:29], 0, v[192:193]
	s_mov_b32 m0, s24
	ds_read_b128 v[162:165], v214 offset:16384
	ds_read_b128 v[166:169], v214 offset:17408
	ds_read_b128 v[170:173], v214 offset:18432
	ds_read_b128 v[174:177], v214 offset:19456
	ds_read_b128 v[178:181], v214 offset:20480
	ds_read_b128 v[182:185], v214 offset:21504
	ds_read_b128 v[186:189], v214 offset:22528
	ds_read_b128 v[210:213], v214 offset:23552
	global_load_lds_dwordx4 v[216:217], off
	s_add_i32 m0, s24, 0x2000
	s_add_u32 s24, s28, 0xb0000
	v_lshl_add_u64 v[228:229], s[28:29], 0, v[204:205]
	s_addc_u32 s25, s29, 0
	s_add_i32 s59, s60, s40
	global_load_lds_dwordx4 v[228:229], off
	v_lshl_add_u64 v[230:231], s[24:25], 0, v[192:193]
	s_mov_b32 m0, s59
	v_lshl_add_u64 v[232:233], s[30:31], 0, v[194:195]
	global_load_lds_dwordx4 v[230:231], off
	v_lshl_add_u64 v[230:231], s[24:25], 0, v[204:205]
	s_add_i32 m0, s59, 0x2000
	s_nop 0
	global_load_lds_dwordx4 v[230:231], off
	v_lshl_add_u64 v[230:231], s[30:31], 0, v[190:191]
	s_mov_b32 m0, s41
	s_nop 0
	global_load_lds_dwordx4 v[230:231], off
	s_mov_b32 m0, s42
	s_nop 0
	global_load_lds_dwordx4 v[232:233], off
	s_waitcnt vmcnt(8)
	s_waitcnt lgkmcnt(0)
	s_barrier
	s_waitcnt lgkmcnt(0)
	v_mfma_f32_16x16x32_bf16 v[62:65], v[110:113], v[162:165], v[62:65]
	v_mfma_f32_16x16x32_bf16 v[58:61], v[122:125], v[162:165], v[58:61]
	v_mfma_f32_16x16x32_bf16 v[46:49], v[110:113], v[170:173], v[46:49]
	v_mfma_f32_16x16x32_bf16 v[42:45], v[122:125], v[170:173], v[42:45]
	v_mfma_f32_16x16x32_bf16 v[30:33], v[110:113], v[178:181], v[30:33]
	v_mfma_f32_16x16x32_bf16 v[26:29], v[122:125], v[178:181], v[26:29]
	v_mfma_f32_16x16x32_bf16 v[14:17], v[110:113], v[186:189], v[14:17]
	v_mfma_f32_16x16x32_bf16 v[10:13], v[122:125], v[186:189], v[10:13]
	v_mfma_f32_16x16x32_bf16 v[62:65], v[118:121], v[166:169], v[62:65]
	v_mfma_f32_16x16x32_bf16 v[58:61], v[134:137], v[166:169], v[58:61]
	v_mfma_f32_16x16x32_bf16 v[46:49], v[118:121], v[174:177], v[46:49]
	v_mfma_f32_16x16x32_bf16 v[42:45], v[134:137], v[174:177], v[42:45]
	v_mfma_f32_16x16x32_bf16 v[30:33], v[118:121], v[182:185], v[30:33]
	v_mfma_f32_16x16x32_bf16 v[26:29], v[134:137], v[182:185], v[26:29]
	v_mfma_f32_16x16x32_bf16 v[14:17], v[118:121], v[210:213], v[14:17]
	v_mfma_f32_16x16x32_bf16 v[10:13], v[134:137], v[210:213], v[10:13]
	v_mfma_f32_16x16x32_bf16 v[54:57], v[138:141], v[162:165], v[54:57]
	v_mfma_f32_16x16x32_bf16 v[50:53], v[146:149], v[162:165], v[50:53]
	v_mfma_f32_16x16x32_bf16 v[38:41], v[138:141], v[170:173], v[38:41]
	v_mfma_f32_16x16x32_bf16 v[34:37], v[146:149], v[170:173], v[34:37]
	v_mfma_f32_16x16x32_bf16 v[22:25], v[138:141], v[178:181], v[22:25]
	v_mfma_f32_16x16x32_bf16 v[18:21], v[146:149], v[178:181], v[18:21]
	v_mfma_f32_16x16x32_bf16 v[6:9], v[138:141], v[186:189], v[6:9]
	v_mfma_f32_16x16x32_bf16 v[2:5], v[146:149], v[186:189], v[2:5]
	v_mfma_f32_16x16x32_bf16 v[54:57], v[142:145], v[166:169], v[54:57]
	v_mfma_f32_16x16x32_bf16 v[50:53], v[154:157], v[166:169], v[50:53]
	v_mfma_f32_16x16x32_bf16 v[38:41], v[142:145], v[174:177], v[38:41]
	v_mfma_f32_16x16x32_bf16 v[34:37], v[154:157], v[174:177], v[34:37]
	v_mfma_f32_16x16x32_bf16 v[22:25], v[142:145], v[182:185], v[22:25]
	v_mfma_f32_16x16x32_bf16 v[18:21], v[154:157], v[182:185], v[18:21]
	v_mfma_f32_16x16x32_bf16 v[6:9], v[142:145], v[210:213], v[6:9]
	v_mfma_f32_16x16x32_bf16 v[2:5], v[154:157], v[210:213], v[2:5]
	s_barrier
	s_add_i32 s59, 0, 0x18000
	s_add_i32 s60, 0, 0x1c000
	v_add_u32_e32 v134, s59, v1
	v_add_u32_e32 v154, s60, v1
	ds_read_b128 v[110:113], v134
	ds_read_b128 v[118:121], v134 offset:1024
	ds_read_b128 v[122:125], v134 offset:2048
	ds_read_b128 v[134:137], v134 offset:3072
	ds_read_b128 v[138:141], v154
	ds_read_b128 v[142:145], v154 offset:1024
	ds_read_b128 v[146:149], v154 offset:2048
	ds_read_b128 v[154:157], v154 offset:3072
	s_add_u32 s24, s30, 0xb0000
	s_addc_u32 s25, s31, 0
	s_mov_b32 m0, s43
	v_lshl_add_u64 v[234:235], s[24:25], 0, v[190:191]
	ds_read_b128 v[162:165], v214 offset:32768
	ds_read_b128 v[166:169], v214 offset:33792
	ds_read_b128 v[170:173], v214 offset:34816
	ds_read_b128 v[174:177], v214 offset:35840
	ds_read_b128 v[178:181], v214 offset:36864
	ds_read_b128 v[182:185], v214 offset:37888
	ds_read_b128 v[186:189], v214 offset:38912
	ds_read_b128 v[210:213], v214 offset:39936
	global_load_lds_dwordx4 v[234:235], off
	v_lshl_add_u64 v[234:235], s[24:25], 0, v[194:195]
	s_mov_b32 m0, s44
	s_nop 0
	global_load_lds_dwordx4 v[234:235], off
	s_waitcnt vmcnt(8)
	s_waitcnt lgkmcnt(0)
	s_barrier
	s_waitcnt lgkmcnt(0)
	v_mfma_f32_16x16x32_bf16 v[158:161], v[110:113], v[162:165], v[158:161]
	v_mfma_f32_16x16x32_bf16 v[150:153], v[122:125], v[162:165], v[150:153]
	v_mfma_f32_16x16x32_bf16 v[114:117], v[110:113], v[170:173], v[114:117]
	v_mfma_f32_16x16x32_bf16 v[106:109], v[122:125], v[170:173], v[106:109]
	v_mfma_f32_16x16x32_bf16 v[94:97], v[110:113], v[178:181], v[94:97]
	v_mfma_f32_16x16x32_bf16 v[90:93], v[122:125], v[178:181], v[90:93]
	v_mfma_f32_16x16x32_bf16 v[78:81], v[110:113], v[186:189], v[78:81]
	v_mfma_f32_16x16x32_bf16 v[74:77], v[122:125], v[186:189], v[74:77]
	v_mfma_f32_16x16x32_bf16 v[158:161], v[118:121], v[166:169], v[158:161]
	v_mfma_f32_16x16x32_bf16 v[150:153], v[134:137], v[166:169], v[150:153]
	v_mfma_f32_16x16x32_bf16 v[114:117], v[118:121], v[174:177], v[114:117]
	v_mfma_f32_16x16x32_bf16 v[106:109], v[134:137], v[174:177], v[106:109]
	v_mfma_f32_16x16x32_bf16 v[94:97], v[118:121], v[182:185], v[94:97]
	v_mfma_f32_16x16x32_bf16 v[90:93], v[134:137], v[182:185], v[90:93]
	v_mfma_f32_16x16x32_bf16 v[78:81], v[118:121], v[210:213], v[78:81]
	v_mfma_f32_16x16x32_bf16 v[74:77], v[134:137], v[210:213], v[74:77]
	v_mfma_f32_16x16x32_bf16 v[130:133], v[138:141], v[162:165], v[130:133]
	v_mfma_f32_16x16x32_bf16 v[126:129], v[146:149], v[162:165], v[126:129]
	v_mfma_f32_16x16x32_bf16 v[102:105], v[138:141], v[170:173], v[102:105]
	v_mfma_f32_16x16x32_bf16 v[98:101], v[146:149], v[170:173], v[98:101]
	v_mfma_f32_16x16x32_bf16 v[86:89], v[138:141], v[178:181], v[86:89]
	v_mfma_f32_16x16x32_bf16 v[82:85], v[146:149], v[178:181], v[82:85]
	v_mfma_f32_16x16x32_bf16 v[70:73], v[138:141], v[186:189], v[70:73]
	v_mfma_f32_16x16x32_bf16 v[66:69], v[146:149], v[186:189], v[66:69]
	v_mfma_f32_16x16x32_bf16 v[130:133], v[142:145], v[166:169], v[130:133]
	v_mfma_f32_16x16x32_bf16 v[126:129], v[154:157], v[166:169], v[126:129]
	v_mfma_f32_16x16x32_bf16 v[102:105], v[142:145], v[174:177], v[102:105]
	v_mfma_f32_16x16x32_bf16 v[98:101], v[154:157], v[174:177], v[98:101]
	v_mfma_f32_16x16x32_bf16 v[86:89], v[142:145], v[182:185], v[86:89]
	v_mfma_f32_16x16x32_bf16 v[82:85], v[154:157], v[182:185], v[82:85]
	v_mfma_f32_16x16x32_bf16 v[70:73], v[142:145], v[210:213], v[70:73]
	v_mfma_f32_16x16x32_bf16 v[66:69], v[154:157], v[210:213], v[66:69]
	s_barrier
	s_add_i32 s24, s59, s40
	v_lshl_add_u64 v[216:217], v[216:217], 0, s[94:95]
	s_mov_b32 m0, s24
	ds_read_b128 v[162:165], v214 offset:49152
	ds_read_b128 v[166:169], v214 offset:50176
	ds_read_b128 v[170:173], v214 offset:51200
	ds_read_b128 v[174:177], v214 offset:52224
	ds_read_b128 v[178:181], v214 offset:53248
	ds_read_b128 v[182:185], v214 offset:54272
	ds_read_b128 v[186:189], v214 offset:55296
	ds_read_b128 v[210:213], v214 offset:56320
	global_load_lds_dwordx4 v[216:217], off
	s_add_i32 m0, s24, 0x2000
	s_add_u32 s24, s28, 0xb0080
	v_lshl_add_u64 v[216:217], v[228:229], 0, s[94:95]
	s_addc_u32 s25, s29, 0
	s_add_i32 s28, s60, s40
	global_load_lds_dwordx4 v[216:217], off
	v_lshl_add_u64 v[216:217], s[24:25], 0, v[192:193]
	s_mov_b32 m0, s28
	s_nop 0
	global_load_lds_dwordx4 v[216:217], off
	v_lshl_add_u64 v[216:217], s[24:25], 0, v[204:205]
	s_add_i32 m0, s28, 0x2000
	s_nop 0
	global_load_lds_dwordx4 v[216:217], off
	v_lshl_add_u64 v[216:217], v[230:231], 0, s[94:95]
	s_mov_b32 m0, s47
	s_nop 0
	global_load_lds_dwordx4 v[216:217], off
	v_lshl_add_u64 v[216:217], v[232:233], 0, s[94:95]
	s_mov_b32 m0, s48
	s_nop 0
	global_load_lds_dwordx4 v[216:217], off
	s_waitcnt vmcnt(8)
	s_waitcnt lgkmcnt(0)
	s_barrier
	s_waitcnt lgkmcnt(0)
	v_mfma_f32_16x16x32_bf16 v[62:65], v[110:113], v[162:165], v[62:65]
	v_mfma_f32_16x16x32_bf16 v[58:61], v[122:125], v[162:165], v[58:61]
	v_mfma_f32_16x16x32_bf16 v[46:49], v[110:113], v[170:173], v[46:49]
	v_mfma_f32_16x16x32_bf16 v[42:45], v[122:125], v[170:173], v[42:45]
	v_mfma_f32_16x16x32_bf16 v[30:33], v[110:113], v[178:181], v[30:33]
	v_mfma_f32_16x16x32_bf16 v[26:29], v[122:125], v[178:181], v[26:29]
	v_mfma_f32_16x16x32_bf16 v[14:17], v[110:113], v[186:189], v[14:17]
	v_mfma_f32_16x16x32_bf16 v[10:13], v[122:125], v[186:189], v[10:13]
	v_mfma_f32_16x16x32_bf16 v[62:65], v[118:121], v[166:169], v[62:65]
	v_mfma_f32_16x16x32_bf16 v[58:61], v[134:137], v[166:169], v[58:61]
	v_mfma_f32_16x16x32_bf16 v[46:49], v[118:121], v[174:177], v[46:49]
	v_mfma_f32_16x16x32_bf16 v[42:45], v[134:137], v[174:177], v[42:45]
	v_mfma_f32_16x16x32_bf16 v[30:33], v[118:121], v[182:185], v[30:33]
	v_mfma_f32_16x16x32_bf16 v[26:29], v[134:137], v[182:185], v[26:29]
	v_mfma_f32_16x16x32_bf16 v[14:17], v[118:121], v[210:213], v[14:17]
	v_mfma_f32_16x16x32_bf16 v[10:13], v[134:137], v[210:213], v[10:13]
	v_mfma_f32_16x16x32_bf16 v[54:57], v[138:141], v[162:165], v[54:57]
	v_mfma_f32_16x16x32_bf16 v[50:53], v[146:149], v[162:165], v[50:53]
	v_mfma_f32_16x16x32_bf16 v[38:41], v[138:141], v[170:173], v[38:41]
	v_mfma_f32_16x16x32_bf16 v[34:37], v[146:149], v[170:173], v[34:37]
	v_mfma_f32_16x16x32_bf16 v[22:25], v[138:141], v[178:181], v[22:25]
	v_mfma_f32_16x16x32_bf16 v[18:21], v[146:149], v[178:181], v[18:21]
	v_mfma_f32_16x16x32_bf16 v[6:9], v[138:141], v[186:189], v[6:9]
	v_mfma_f32_16x16x32_bf16 v[2:5], v[146:149], v[186:189], v[2:5]
	v_mfma_f32_16x16x32_bf16 v[54:57], v[142:145], v[166:169], v[54:57]
	v_mfma_f32_16x16x32_bf16 v[50:53], v[154:157], v[166:169], v[50:53]
	v_mfma_f32_16x16x32_bf16 v[38:41], v[142:145], v[174:177], v[38:41]
	v_mfma_f32_16x16x32_bf16 v[34:37], v[154:157], v[174:177], v[34:37]
	v_mfma_f32_16x16x32_bf16 v[22:25], v[142:145], v[182:185], v[22:25]
	v_mfma_f32_16x16x32_bf16 v[18:21], v[154:157], v[182:185], v[18:21]
	v_mfma_f32_16x16x32_bf16 v[6:9], v[142:145], v[210:213], v[6:9]
	v_mfma_f32_16x16x32_bf16 v[2:5], v[154:157], v[210:213], v[2:5]
	s_barrier
	s_add_i32 s58, s58, 2
	s_add_u32 s56, s56, 0x100
	s_addc_u32 s57, s57, 0
	s_cmp_gt_u32 s58, 41
	s_mov_b64 s[24:25], s[26:27]
	s_cbranch_scc0 .LBB0_220
	s_and_b64 vcc, exec, s[20:21]
	s_cbranch_vccz .LBB0_223
	s_barrier

.LBB0_252:
	s_add_i32 s15, s14, 0x100
	s_and_b64 s[12:13], s[12:13], exec
	s_cselect_b32 s13, 0, s15
	s_cselect_b32 s12, 0, 0
	s_add_u32 s16, s4, s13
	s_addc_u32 s17, s5, s12
	s_add_i32 s61, 0, 0x10000
	s_add_u32 s18, s2, s13
	s_addc_u32 s19, s3, s12
	s_add_i32 s13, 0, 0x14000
	s_add_u32 s22, s6, s14
	s_addc_u32 s23, s7, 0
	s_add_i32 s60, s61, s43
	s_add_i32 m0, s44, 0xc000
	s_add_i32 s63, s44, 0xe000
	s_add_i32 s57, s60, 0x2000
	v_add_u32_e32 v139, s61, v1
	s_add_u32 s20, s18, 0x80800
	ds_read_b128 v[140:143], v139
	ds_read_b128 v[144:147], v139 offset:1024
	ds_read_b128 v[148:151], v139 offset:2048
	ds_read_b128 v[152:155], v139 offset:3072
	v_add_u32_e32 v139, s13, v1
	s_addc_u32 s21, s19, 0
	s_add_i32 s59, s13, s43
	ds_read_b128 v[156:159], v139
	ds_read_b128 v[160:163], v139 offset:1024
	ds_read_b128 v[164:167], v139 offset:2048
	ds_read_b128 v[168:171], v139 offset:3072
	s_add_i32 s58, s59, 0x2000
	s_add_i32 s56, 0, 0x18000
	s_add_i32 s55, 0, 0x1c000
	s_add_u32 s14, s16, 0x40000
	s_addc_u32 s15, s17, 0
	s_add_i32 s54, s56, s43
	s_add_i32 s53, s54, 0x2000
	s_add_u32 s12, s18, 0x80880
	s_addc_u32 s13, s19, 0
	s_add_i32 s62, s55, s43
	s_add_i32 s61, s62, 0x2000
	v_lshl_add_u64 v[212:213], s[22:23], 0, v[130:131]
	v_lshl_add_u64 v[212:213], v[212:213], 0, s[94:95]
	ds_read_b128 v[172:175], v138
	ds_read_b128 v[176:179], v138 offset:1024
	ds_read_b128 v[180:183], v138 offset:2048
	ds_read_b128 v[184:187], v138 offset:3072
	ds_read_b128 v[188:191], v138 offset:4096
	ds_read_b128 v[192:195], v138 offset:5120
	ds_read_b128 v[204:207], v138 offset:6144
	ds_read_b128 v[208:211], v138 offset:7168
	global_load_lds_dwordx4 v[212:213], off
	v_lshl_add_u64 v[212:213], s[22:23], 0, v[134:135]
	v_lshl_add_u64 v[212:213], v[212:213], 0, s[94:95]
	s_mov_b32 m0, s63
	s_nop 0
	global_load_lds_dwordx4 v[212:213], off
	s_waitcnt vmcnt(8)
	s_waitcnt lgkmcnt(0)
	s_barrier
	s_waitcnt lgkmcnt(0)
	v_mfma_f32_16x16x32_bf16 v[126:129], v[140:143], v[172:175], v[126:129]
	v_mfma_f32_16x16x32_bf16 v[122:125], v[148:151], v[172:175], v[122:125]
	v_mfma_f32_16x16x32_bf16 v[118:121], v[140:143], v[180:183], v[118:121]
	v_mfma_f32_16x16x32_bf16 v[114:117], v[148:151], v[180:183], v[114:117]
	v_mfma_f32_16x16x32_bf16 v[102:105], v[140:143], v[188:191], v[102:105]
	v_mfma_f32_16x16x32_bf16 v[98:101], v[148:151], v[188:191], v[98:101]
	v_mfma_f32_16x16x32_bf16 v[86:89], v[140:143], v[204:207], v[86:89]
	v_mfma_f32_16x16x32_bf16 v[82:85], v[148:151], v[204:207], v[82:85]
	v_mfma_f32_16x16x32_bf16 v[126:129], v[144:147], v[176:179], v[126:129]
	v_mfma_f32_16x16x32_bf16 v[122:125], v[152:155], v[176:179], v[122:125]
	v_mfma_f32_16x16x32_bf16 v[118:121], v[144:147], v[184:187], v[118:121]
	v_mfma_f32_16x16x32_bf16 v[114:117], v[152:155], v[184:187], v[114:117]
	v_mfma_f32_16x16x32_bf16 v[102:105], v[144:147], v[192:195], v[102:105]
	v_mfma_f32_16x16x32_bf16 v[98:101], v[152:155], v[192:195], v[98:101]
	v_mfma_f32_16x16x32_bf16 v[86:89], v[144:147], v[208:211], v[86:89]
	v_mfma_f32_16x16x32_bf16 v[82:85], v[152:155], v[208:211], v[82:85]
	v_mfma_f32_16x16x32_bf16 v[110:113], v[156:159], v[172:175], v[110:113]
	v_mfma_f32_16x16x32_bf16 v[106:109], v[164:167], v[172:175], v[106:109]
	v_mfma_f32_16x16x32_bf16 v[94:97], v[156:159], v[180:183], v[94:97]
	v_mfma_f32_16x16x32_bf16 v[90:93], v[164:167], v[180:183], v[90:93]
	v_mfma_f32_16x16x32_bf16 v[78:81], v[156:159], v[188:191], v[78:81]
	v_mfma_f32_16x16x32_bf16 v[74:77], v[164:167], v[188:191], v[74:77]
	v_mfma_f32_16x16x32_bf16 v[70:73], v[156:159], v[204:207], v[70:73]
	v_mfma_f32_16x16x32_bf16 v[66:69], v[164:167], v[204:207], v[66:69]
	v_mfma_f32_16x16x32_bf16 v[110:113], v[160:163], v[176:179], v[110:113]
	v_mfma_f32_16x16x32_bf16 v[106:109], v[168:171], v[176:179], v[106:109]
	v_mfma_f32_16x16x32_bf16 v[94:97], v[160:163], v[184:187], v[94:97]
	v_mfma_f32_16x16x32_bf16 v[90:93], v[168:171], v[184:187], v[90:93]
	v_mfma_f32_16x16x32_bf16 v[78:81], v[160:163], v[192:195], v[78:81]
	v_mfma_f32_16x16x32_bf16 v[74:77], v[168:171], v[192:195], v[74:77]
	v_mfma_f32_16x16x32_bf16 v[70:73], v[160:163], v[208:211], v[70:73]
	v_mfma_f32_16x16x32_bf16 v[66:69], v[168:171], v[208:211], v[66:69]
	s_barrier
	v_lshl_add_u64 v[212:213], s[18:19], 0, v[132:133]
	s_mov_b32 m0, s60
	v_lshl_add_u64 v[214:215], v[212:213], 0, s[90:91]
	ds_read_b128 v[172:175], v138 offset:16384
	ds_read_b128 v[176:179], v138 offset:17408
	ds_read_b128 v[180:183], v138 offset:18432
	ds_read_b128 v[184:187], v138 offset:19456
	ds_read_b128 v[188:191], v138 offset:20480
	ds_read_b128 v[192:195], v138 offset:21504
	ds_read_b128 v[204:207], v138 offset:22528
	ds_read_b128 v[208:211], v138 offset:23552
	global_load_lds_dwordx4 v[214:215], off
	v_lshl_add_u64 v[214:215], s[18:19], 0, v[136:137]
	v_lshl_add_u64 v[216:217], v[214:215], 0, s[90:91]
	s_mov_b32 m0, s57
	v_lshl_add_u64 v[228:229], s[16:17], 0, v[134:135]
	global_load_lds_dwordx4 v[216:217], off
	v_lshl_add_u64 v[216:217], s[20:21], 0, v[132:133]
	s_mov_b32 m0, s59
	s_nop 0
	global_load_lds_dwordx4 v[216:217], off
	v_lshl_add_u64 v[216:217], s[20:21], 0, v[136:137]
	s_mov_b32 m0, s58
	s_nop 0
	global_load_lds_dwordx4 v[216:217], off
	v_lshl_add_u64 v[216:217], s[16:17], 0, v[130:131]
	s_mov_b32 m0, s44
	s_nop 0
	global_load_lds_dwordx4 v[216:217], off
	s_mov_b32 m0, s45
	s_nop 0
	global_load_lds_dwordx4 v[228:229], off
	s_waitcnt vmcnt(8)
	s_waitcnt lgkmcnt(0)
	s_barrier
	s_waitcnt lgkmcnt(0)
	v_mfma_f32_16x16x32_bf16 v[62:65], v[140:143], v[172:175], v[62:65]
	v_mfma_f32_16x16x32_bf16 v[58:61], v[148:151], v[172:175], v[58:61]
	v_mfma_f32_16x16x32_bf16 v[54:57], v[140:143], v[180:183], v[54:57]
	v_mfma_f32_16x16x32_bf16 v[50:53], v[148:151], v[180:183], v[50:53]
	v_mfma_f32_16x16x32_bf16 v[38:41], v[140:143], v[188:191], v[38:41]
	v_mfma_f32_16x16x32_bf16 v[34:37], v[148:151], v[188:191], v[34:37]
	v_mfma_f32_16x16x32_bf16 v[22:25], v[140:143], v[204:207], v[22:25]
	v_mfma_f32_16x16x32_bf16 v[18:21], v[148:151], v[204:207], v[18:21]
	v_mfma_f32_16x16x32_bf16 v[62:65], v[144:147], v[176:179], v[62:65]
	v_mfma_f32_16x16x32_bf16 v[58:61], v[152:155], v[176:179], v[58:61]
	v_mfma_f32_16x16x32_bf16 v[54:57], v[144:147], v[184:187], v[54:57]
	v_mfma_f32_16x16x32_bf16 v[50:53], v[152:155], v[184:187], v[50:53]
	v_mfma_f32_16x16x32_bf16 v[38:41], v[144:147], v[192:195], v[38:41]
	v_mfma_f32_16x16x32_bf16 v[34:37], v[152:155], v[192:195], v[34:37]
	v_mfma_f32_16x16x32_bf16 v[22:25], v[144:147], v[208:211], v[22:25]
	v_mfma_f32_16x16x32_bf16 v[18:21], v[152:155], v[208:211], v[18:21]
	v_mfma_f32_16x16x32_bf16 v[46:49], v[156:159], v[172:175], v[46:49]
	v_mfma_f32_16x16x32_bf16 v[42:45], v[164:167], v[172:175], v[42:45]
	v_mfma_f32_16x16x32_bf16 v[30:33], v[156:159], v[180:183], v[30:33]
	v_mfma_f32_16x16x32_bf16 v[26:29], v[164:167], v[180:183], v[26:29]
	v_mfma_f32_16x16x32_bf16 v[14:17], v[156:159], v[188:191], v[14:17]
	v_mfma_f32_16x16x32_bf16 v[10:13], v[164:167], v[188:191], v[10:13]
	v_mfma_f32_16x16x32_bf16 v[6:9], v[156:159], v[204:207], v[6:9]
	v_mfma_f32_16x16x32_bf16 v[2:5], v[164:167], v[204:207], v[2:5]
	v_mfma_f32_16x16x32_bf16 v[46:49], v[160:163], v[176:179], v[46:49]
	v_mfma_f32_16x16x32_bf16 v[42:45], v[168:171], v[176:179], v[42:45]
	v_mfma_f32_16x16x32_bf16 v[30:33], v[160:163], v[184:187], v[30:33]
	v_mfma_f32_16x16x32_bf16 v[26:29], v[168:171], v[184:187], v[26:29]
	v_mfma_f32_16x16x32_bf16 v[14:17], v[160:163], v[192:195], v[14:17]
	v_mfma_f32_16x16x32_bf16 v[10:13], v[168:171], v[192:195], v[10:13]
	v_mfma_f32_16x16x32_bf16 v[6:9], v[160:163], v[208:211], v[6:9]
	v_mfma_f32_16x16x32_bf16 v[2:5], v[168:171], v[208:211], v[2:5]
	s_barrier
	v_add_u32_e32 v139, s56, v1
	ds_read_b128 v[140:143], v139
	ds_read_b128 v[144:147], v139 offset:1024
	ds_read_b128 v[148:151], v139 offset:2048
	ds_read_b128 v[152:155], v139 offset:3072
	v_add_u32_e32 v139, s55, v1
	ds_read_b128 v[156:159], v139
	ds_read_b128 v[160:163], v139 offset:1024
	ds_read_b128 v[164:167], v139 offset:2048
	ds_read_b128 v[168:171], v139 offset:3072
	s_mov_b32 m0, s46
	v_lshl_add_u64 v[230:231], s[14:15], 0, v[130:131]
	ds_read_b128 v[172:175], v138 offset:32768
	ds_read_b128 v[176:179], v138 offset:33792
	ds_read_b128 v[180:183], v138 offset:34816
	ds_read_b128 v[184:187], v138 offset:35840
	ds_read_b128 v[188:191], v138 offset:36864
	ds_read_b128 v[192:195], v138 offset:37888
	ds_read_b128 v[204:207], v138 offset:38912
	ds_read_b128 v[208:211], v138 offset:39936
	global_load_lds_dwordx4 v[230:231], off
	v_lshl_add_u64 v[230:231], s[14:15], 0, v[134:135]
	s_mov_b32 m0, s47
	s_nop 0
	global_load_lds_dwordx4 v[230:231], off
	s_waitcnt vmcnt(8)
	s_waitcnt lgkmcnt(0)
	s_barrier
	s_waitcnt lgkmcnt(0)
	v_mfma_f32_16x16x32_bf16 v[126:129], v[140:143], v[172:175], v[126:129]
	v_mfma_f32_16x16x32_bf16 v[122:125], v[148:151], v[172:175], v[122:125]
	v_mfma_f32_16x16x32_bf16 v[118:121], v[140:143], v[180:183], v[118:121]
	v_mfma_f32_16x16x32_bf16 v[114:117], v[148:151], v[180:183], v[114:117]
	v_mfma_f32_16x16x32_bf16 v[102:105], v[140:143], v[188:191], v[102:105]
	v_mfma_f32_16x16x32_bf16 v[98:101], v[148:151], v[188:191], v[98:101]
	v_mfma_f32_16x16x32_bf16 v[86:89], v[140:143], v[204:207], v[86:89]
	v_mfma_f32_16x16x32_bf16 v[82:85], v[148:151], v[204:207], v[82:85]
	v_mfma_f32_16x16x32_bf16 v[126:129], v[144:147], v[176:179], v[126:129]
	v_mfma_f32_16x16x32_bf16 v[122:125], v[152:155], v[176:179], v[122:125]
	v_mfma_f32_16x16x32_bf16 v[118:121], v[144:147], v[184:187], v[118:121]
	v_mfma_f32_16x16x32_bf16 v[114:117], v[152:155], v[184:187], v[114:117]
	v_mfma_f32_16x16x32_bf16 v[102:105], v[144:147], v[192:195], v[102:105]
	v_mfma_f32_16x16x32_bf16 v[98:101], v[152:155], v[192:195], v[98:101]
	v_mfma_f32_16x16x32_bf16 v[86:89], v[144:147], v[208:211], v[86:89]
	v_mfma_f32_16x16x32_bf16 v[82:85], v[152:155], v[208:211], v[82:85]
	v_mfma_f32_16x16x32_bf16 v[110:113], v[156:159], v[172:175], v[110:113]
	v_mfma_f32_16x16x32_bf16 v[106:109], v[164:167], v[172:175], v[106:109]
	v_mfma_f32_16x16x32_bf16 v[94:97], v[156:159], v[180:183], v[94:97]
	v_mfma_f32_16x16x32_bf16 v[90:93], v[164:167], v[180:183], v[90:93]
	v_mfma_f32_16x16x32_bf16 v[78:81], v[156:159], v[188:191], v[78:81]
	v_mfma_f32_16x16x32_bf16 v[74:77], v[164:167], v[188:191], v[74:77]
	v_mfma_f32_16x16x32_bf16 v[70:73], v[156:159], v[204:207], v[70:73]
	v_mfma_f32_16x16x32_bf16 v[66:69], v[164:167], v[204:207], v[66:69]
	v_mfma_f32_16x16x32_bf16 v[110:113], v[160:163], v[176:179], v[110:113]
	v_mfma_f32_16x16x32_bf16 v[106:109], v[168:171], v[176:179], v[106:109]
	v_mfma_f32_16x16x32_bf16 v[94:97], v[160:163], v[184:187], v[94:97]
	v_mfma_f32_16x16x32_bf16 v[90:93], v[168:171], v[184:187], v[90:93]
	v_mfma_f32_16x16x32_bf16 v[78:81], v[160:163], v[192:195], v[78:81]
	v_mfma_f32_16x16x32_bf16 v[74:77], v[168:171], v[192:195], v[74:77]
	v_mfma_f32_16x16x32_bf16 v[70:73], v[160:163], v[208:211], v[70:73]
	v_mfma_f32_16x16x32_bf16 v[66:69], v[168:171], v[208:211], v[66:69]
	s_barrier
	s_mov_b32 m0, s54
	v_lshl_add_u64 v[212:213], v[212:213], 0, s[64:65]
	ds_read_b128 v[172:175], v138 offset:49152
	ds_read_b128 v[176:179], v138 offset:50176
	ds_read_b128 v[180:183], v138 offset:51200
	ds_read_b128 v[184:187], v138 offset:52224
	ds_read_b128 v[188:191], v138 offset:53248
	ds_read_b128 v[192:195], v138 offset:54272
	ds_read_b128 v[204:207], v138 offset:55296
	ds_read_b128 v[208:211], v138 offset:56320
	global_load_lds_dwordx4 v[212:213], off
	v_lshl_add_u64 v[212:213], v[214:215], 0, s[64:65]
	s_mov_b32 m0, s53
	s_nop 0
	global_load_lds_dwordx4 v[212:213], off
	v_lshl_add_u64 v[212:213], s[12:13], 0, v[132:133]
	s_mov_b32 m0, s62
	s_nop 0
	global_load_lds_dwordx4 v[212:213], off
	v_lshl_add_u64 v[212:213], s[12:13], 0, v[136:137]
	s_mov_b32 m0, s61
	s_nop 0
	global_load_lds_dwordx4 v[212:213], off
	v_lshl_add_u64 v[212:213], v[216:217], 0, s[94:95]
	s_mov_b32 m0, s51
	s_nop 0
	global_load_lds_dwordx4 v[212:213], off
	v_lshl_add_u64 v[212:213], v[228:229], 0, s[94:95]
	s_mov_b32 m0, s52
	s_nop 0
	global_load_lds_dwordx4 v[212:213], off
	s_waitcnt vmcnt(8)
	s_waitcnt lgkmcnt(0)
	s_barrier
	s_waitcnt lgkmcnt(0)
	v_mfma_f32_16x16x32_bf16 v[62:65], v[140:143], v[172:175], v[62:65]
	v_mfma_f32_16x16x32_bf16 v[58:61], v[148:151], v[172:175], v[58:61]
	v_mfma_f32_16x16x32_bf16 v[54:57], v[140:143], v[180:183], v[54:57]
	v_mfma_f32_16x16x32_bf16 v[50:53], v[148:151], v[180:183], v[50:53]
	v_mfma_f32_16x16x32_bf16 v[38:41], v[140:143], v[188:191], v[38:41]
	v_mfma_f32_16x16x32_bf16 v[34:37], v[148:151], v[188:191], v[34:37]
	v_mfma_f32_16x16x32_bf16 v[22:25], v[140:143], v[204:207], v[22:25]
	v_mfma_f32_16x16x32_bf16 v[18:21], v[148:151], v[204:207], v[18:21]
	v_mfma_f32_16x16x32_bf16 v[62:65], v[144:147], v[176:179], v[62:65]
	v_mfma_f32_16x16x32_bf16 v[58:61], v[152:155], v[176:179], v[58:61]
	v_mfma_f32_16x16x32_bf16 v[54:57], v[144:147], v[184:187], v[54:57]
	v_mfma_f32_16x16x32_bf16 v[50:53], v[152:155], v[184:187], v[50:53]
	v_mfma_f32_16x16x32_bf16 v[38:41], v[144:147], v[192:195], v[38:41]
	v_mfma_f32_16x16x32_bf16 v[34:37], v[152:155], v[192:195], v[34:37]
	v_mfma_f32_16x16x32_bf16 v[22:25], v[144:147], v[208:211], v[22:25]
	v_mfma_f32_16x16x32_bf16 v[18:21], v[152:155], v[208:211], v[18:21]
	v_mfma_f32_16x16x32_bf16 v[46:49], v[156:159], v[172:175], v[46:49]
	v_mfma_f32_16x16x32_bf16 v[42:45], v[164:167], v[172:175], v[42:45]
	v_mfma_f32_16x16x32_bf16 v[30:33], v[156:159], v[180:183], v[30:33]
	v_mfma_f32_16x16x32_bf16 v[26:29], v[164:167], v[180:183], v[26:29]
	v_mfma_f32_16x16x32_bf16 v[14:17], v[156:159], v[188:191], v[14:17]
	v_mfma_f32_16x16x32_bf16 v[10:13], v[164:167], v[188:191], v[10:13]
	v_mfma_f32_16x16x32_bf16 v[6:9], v[156:159], v[204:207], v[6:9]
	v_mfma_f32_16x16x32_bf16 v[2:5], v[164:167], v[204:207], v[2:5]
	v_mfma_f32_16x16x32_bf16 v[46:49], v[160:163], v[176:179], v[46:49]
	v_mfma_f32_16x16x32_bf16 v[42:45], v[168:171], v[176:179], v[42:45]
	v_mfma_f32_16x16x32_bf16 v[30:33], v[160:163], v[184:187], v[30:33]
	v_mfma_f32_16x16x32_bf16 v[26:29], v[168:171], v[184:187], v[26:29]
	v_mfma_f32_16x16x32_bf16 v[14:17], v[160:163], v[192:195], v[14:17]
	v_mfma_f32_16x16x32_bf16 v[10:13], v[168:171], v[192:195], v[10:13]
	v_mfma_f32_16x16x32_bf16 v[6:9], v[160:163], v[208:211], v[6:9]
	v_mfma_f32_16x16x32_bf16 v[2:5], v[168:171], v[208:211], v[2:5]
	s_barrier
	s_andn2_b64 vcc, exec, s[8:9]
	s_mov_b64 s[12:13], -1
	s_mov_b64 s[8:9], 0
	s_movk_i32 s14, 0x100
	s_cbranch_vccz .LBB0_252
	s_cmpk_lt_u32 s42, 0x100
	s_cbranch_scc0 .LBB0_255
	s_barrier

.LBB0_260:
	s_add_i32 s15, s14, 0x100
	s_and_b64 s[12:13], s[12:13], exec
	s_cselect_b32 s13, 0, s15
	s_cselect_b32 s12, 0, 0
	s_add_u32 s16, s2, s13
	s_addc_u32 s17, s3, s12
	s_add_i32 s56, 0, 0x10000
	s_add_u32 s18, s4, s13
	s_addc_u32 s19, s5, s12
	s_add_i32 s13, 0, 0x14000
	s_add_u32 s22, s6, s14
	s_addc_u32 s23, s7, 0
	s_add_i32 s55, s56, s39
	s_add_i32 m0, s40, 0xc000
	s_add_i32 s58, s40, 0xe000
	s_add_i32 s52, s55, 0x2000
	v_add_u32_e32 v139, s56, v1
	s_add_u32 s20, s18, 0x40000
	ds_read_b128 v[140:143], v139
	ds_read_b128 v[144:147], v139 offset:1024
	ds_read_b128 v[148:151], v139 offset:2048
	ds_read_b128 v[152:155], v139 offset:3072
	v_add_u32_e32 v139, s13, v1
	s_addc_u32 s21, s19, 0
	s_add_i32 s54, s13, s39
	ds_read_b128 v[156:159], v139
	ds_read_b128 v[160:163], v139 offset:1024
	ds_read_b128 v[164:167], v139 offset:2048
	ds_read_b128 v[168:171], v139 offset:3072
	s_add_i32 s53, s54, 0x2000
	s_add_i32 s51, 0, 0x18000
	s_add_i32 s50, 0, 0x1c000
	s_add_u32 s14, s16, 0x80000
	s_addc_u32 s15, s17, 0
	s_add_i32 s49, s51, s39
	s_add_i32 s48, s49, 0x2000
	s_add_u32 s12, s18, 0x40080
	s_addc_u32 s13, s19, 0
	s_add_i32 s57, s50, s39
	s_add_i32 s56, s57, 0x2000
	v_lshl_add_u64 v[212:213], s[22:23], 0, v[130:131]
	v_lshl_add_u64 v[212:213], v[212:213], 0, s[94:95]
	ds_read_b128 v[172:175], v138
	ds_read_b128 v[176:179], v138 offset:1024
	ds_read_b128 v[180:183], v138 offset:2048
	ds_read_b128 v[184:187], v138 offset:3072
	ds_read_b128 v[188:191], v138 offset:4096
	ds_read_b128 v[192:195], v138 offset:5120
	ds_read_b128 v[204:207], v138 offset:6144
	ds_read_b128 v[208:211], v138 offset:7168
	global_load_lds_dwordx4 v[212:213], off
	v_lshl_add_u64 v[212:213], s[22:23], 0, v[134:135]
	v_lshl_add_u64 v[212:213], v[212:213], 0, s[94:95]
	s_mov_b32 m0, s58
	s_nop 0
	global_load_lds_dwordx4 v[212:213], off
	s_waitcnt vmcnt(8)
	s_waitcnt lgkmcnt(0)
	s_barrier
	s_waitcnt lgkmcnt(0)
	v_mfma_f32_16x16x32_bf16 v[126:129], v[140:143], v[172:175], v[126:129]
	v_mfma_f32_16x16x32_bf16 v[122:125], v[148:151], v[172:175], v[122:125]
	v_mfma_f32_16x16x32_bf16 v[118:121], v[140:143], v[180:183], v[118:121]
	v_mfma_f32_16x16x32_bf16 v[114:117], v[148:151], v[180:183], v[114:117]
	v_mfma_f32_16x16x32_bf16 v[102:105], v[140:143], v[188:191], v[102:105]
	v_mfma_f32_16x16x32_bf16 v[98:101], v[148:151], v[188:191], v[98:101]
	v_mfma_f32_16x16x32_bf16 v[86:89], v[140:143], v[204:207], v[86:89]
	v_mfma_f32_16x16x32_bf16 v[82:85], v[148:151], v[204:207], v[82:85]
	v_mfma_f32_16x16x32_bf16 v[126:129], v[144:147], v[176:179], v[126:129]
	v_mfma_f32_16x16x32_bf16 v[122:125], v[152:155], v[176:179], v[122:125]
	v_mfma_f32_16x16x32_bf16 v[118:121], v[144:147], v[184:187], v[118:121]
	v_mfma_f32_16x16x32_bf16 v[114:117], v[152:155], v[184:187], v[114:117]
	v_mfma_f32_16x16x32_bf16 v[102:105], v[144:147], v[192:195], v[102:105]
	v_mfma_f32_16x16x32_bf16 v[98:101], v[152:155], v[192:195], v[98:101]
	v_mfma_f32_16x16x32_bf16 v[86:89], v[144:147], v[208:211], v[86:89]
	v_mfma_f32_16x16x32_bf16 v[82:85], v[152:155], v[208:211], v[82:85]
	v_mfma_f32_16x16x32_bf16 v[110:113], v[156:159], v[172:175], v[110:113]
	v_mfma_f32_16x16x32_bf16 v[106:109], v[164:167], v[172:175], v[106:109]
	v_mfma_f32_16x16x32_bf16 v[94:97], v[156:159], v[180:183], v[94:97]
	v_mfma_f32_16x16x32_bf16 v[90:93], v[164:167], v[180:183], v[90:93]
	v_mfma_f32_16x16x32_bf16 v[78:81], v[156:159], v[188:191], v[78:81]
	v_mfma_f32_16x16x32_bf16 v[74:77], v[164:167], v[188:191], v[74:77]
	v_mfma_f32_16x16x32_bf16 v[70:73], v[156:159], v[204:207], v[70:73]
	v_mfma_f32_16x16x32_bf16 v[66:69], v[164:167], v[204:207], v[66:69]
	v_mfma_f32_16x16x32_bf16 v[110:113], v[160:163], v[176:179], v[110:113]
	v_mfma_f32_16x16x32_bf16 v[106:109], v[168:171], v[176:179], v[106:109]
	v_mfma_f32_16x16x32_bf16 v[94:97], v[160:163], v[184:187], v[94:97]
	v_mfma_f32_16x16x32_bf16 v[90:93], v[168:171], v[184:187], v[90:93]
	v_mfma_f32_16x16x32_bf16 v[78:81], v[160:163], v[192:195], v[78:81]
	v_mfma_f32_16x16x32_bf16 v[74:77], v[168:171], v[192:195], v[74:77]
	v_mfma_f32_16x16x32_bf16 v[70:73], v[160:163], v[208:211], v[70:73]
	v_mfma_f32_16x16x32_bf16 v[66:69], v[168:171], v[208:211], v[66:69]
	s_barrier
	s_mov_b32 m0, s55
	v_lshl_add_u64 v[212:213], s[18:19], 0, v[132:133]
	ds_read_b128 v[172:175], v138 offset:16384
	ds_read_b128 v[176:179], v138 offset:17408
	ds_read_b128 v[180:183], v138 offset:18432
	ds_read_b128 v[184:187], v138 offset:19456
	ds_read_b128 v[188:191], v138 offset:20480
	ds_read_b128 v[192:195], v138 offset:21504
	ds_read_b128 v[204:207], v138 offset:22528
	ds_read_b128 v[208:211], v138 offset:23552
	global_load_lds_dwordx4 v[212:213], off
	v_lshl_add_u64 v[214:215], s[18:19], 0, v[136:137]
	s_mov_b32 m0, s52
	v_lshl_add_u64 v[216:217], s[20:21], 0, v[132:133]
	global_load_lds_dwordx4 v[214:215], off
	s_mov_b32 m0, s54
	v_lshl_add_u64 v[228:229], s[16:17], 0, v[134:135]
	global_load_lds_dwordx4 v[216:217], off
	v_lshl_add_u64 v[216:217], s[20:21], 0, v[136:137]
	s_mov_b32 m0, s53
	s_nop 0
	global_load_lds_dwordx4 v[216:217], off
	v_lshl_add_u64 v[216:217], s[16:17], 0, v[130:131]
	s_mov_b32 m0, s40
	s_nop 0
	global_load_lds_dwordx4 v[216:217], off
	s_mov_b32 m0, s41
	s_nop 0
	global_load_lds_dwordx4 v[228:229], off
	s_waitcnt vmcnt(8)
	s_waitcnt lgkmcnt(0)
	s_barrier
	s_waitcnt lgkmcnt(0)
	v_mfma_f32_16x16x32_bf16 v[62:65], v[140:143], v[172:175], v[62:65]
	v_mfma_f32_16x16x32_bf16 v[58:61], v[148:151], v[172:175], v[58:61]
	v_mfma_f32_16x16x32_bf16 v[54:57], v[140:143], v[180:183], v[54:57]
	v_mfma_f32_16x16x32_bf16 v[50:53], v[148:151], v[180:183], v[50:53]
	v_mfma_f32_16x16x32_bf16 v[38:41], v[140:143], v[188:191], v[38:41]
	v_mfma_f32_16x16x32_bf16 v[34:37], v[148:151], v[188:191], v[34:37]
	v_mfma_f32_16x16x32_bf16 v[22:25], v[140:143], v[204:207], v[22:25]
	v_mfma_f32_16x16x32_bf16 v[18:21], v[148:151], v[204:207], v[18:21]
	v_mfma_f32_16x16x32_bf16 v[62:65], v[144:147], v[176:179], v[62:65]
	v_mfma_f32_16x16x32_bf16 v[58:61], v[152:155], v[176:179], v[58:61]
	v_mfma_f32_16x16x32_bf16 v[54:57], v[144:147], v[184:187], v[54:57]
	v_mfma_f32_16x16x32_bf16 v[50:53], v[152:155], v[184:187], v[50:53]
	v_mfma_f32_16x16x32_bf16 v[38:41], v[144:147], v[192:195], v[38:41]
	v_mfma_f32_16x16x32_bf16 v[34:37], v[152:155], v[192:195], v[34:37]
	v_mfma_f32_16x16x32_bf16 v[22:25], v[144:147], v[208:211], v[22:25]
	v_mfma_f32_16x16x32_bf16 v[18:21], v[152:155], v[208:211], v[18:21]
	v_mfma_f32_16x16x32_bf16 v[46:49], v[156:159], v[172:175], v[46:49]
	v_mfma_f32_16x16x32_bf16 v[42:45], v[164:167], v[172:175], v[42:45]
	v_mfma_f32_16x16x32_bf16 v[30:33], v[156:159], v[180:183], v[30:33]
	v_mfma_f32_16x16x32_bf16 v[26:29], v[164:167], v[180:183], v[26:29]
	v_mfma_f32_16x16x32_bf16 v[14:17], v[156:159], v[188:191], v[14:17]
	v_mfma_f32_16x16x32_bf16 v[10:13], v[164:167], v[188:191], v[10:13]
	v_mfma_f32_16x16x32_bf16 v[6:9], v[156:159], v[204:207], v[6:9]
	v_mfma_f32_16x16x32_bf16 v[2:5], v[164:167], v[204:207], v[2:5]
	v_mfma_f32_16x16x32_bf16 v[46:49], v[160:163], v[176:179], v[46:49]
	v_mfma_f32_16x16x32_bf16 v[42:45], v[168:171], v[176:179], v[42:45]
	v_mfma_f32_16x16x32_bf16 v[30:33], v[160:163], v[184:187], v[30:33]
	v_mfma_f32_16x16x32_bf16 v[26:29], v[168:171], v[184:187], v[26:29]
	v_mfma_f32_16x16x32_bf16 v[14:17], v[160:163], v[192:195], v[14:17]
	v_mfma_f32_16x16x32_bf16 v[10:13], v[168:171], v[192:195], v[10:13]
	v_mfma_f32_16x16x32_bf16 v[6:9], v[160:163], v[208:211], v[6:9]
	v_mfma_f32_16x16x32_bf16 v[2:5], v[168:171], v[208:211], v[2:5]
	s_barrier
	v_add_u32_e32 v139, s51, v1
	ds_read_b128 v[140:143], v139
	ds_read_b128 v[144:147], v139 offset:1024
	ds_read_b128 v[148:151], v139 offset:2048
	ds_read_b128 v[152:155], v139 offset:3072
	v_add_u32_e32 v139, s50, v1
	ds_read_b128 v[156:159], v139
	ds_read_b128 v[160:163], v139 offset:1024
	ds_read_b128 v[164:167], v139 offset:2048
	ds_read_b128 v[168:171], v139 offset:3072
	s_mov_b32 m0, s42
	v_lshl_add_u64 v[230:231], s[14:15], 0, v[130:131]
	ds_read_b128 v[172:175], v138 offset:32768
	ds_read_b128 v[176:179], v138 offset:33792
	ds_read_b128 v[180:183], v138 offset:34816
	ds_read_b128 v[184:187], v138 offset:35840
	ds_read_b128 v[188:191], v138 offset:36864
	ds_read_b128 v[192:195], v138 offset:37888
	ds_read_b128 v[204:207], v138 offset:38912
	ds_read_b128 v[208:211], v138 offset:39936
	global_load_lds_dwordx4 v[230:231], off
	v_lshl_add_u64 v[230:231], s[14:15], 0, v[134:135]
	s_mov_b32 m0, s43
	s_nop 0
	global_load_lds_dwordx4 v[230:231], off
	s_waitcnt vmcnt(8)
	s_waitcnt lgkmcnt(0)
	s_barrier
	s_waitcnt lgkmcnt(0)
	v_mfma_f32_16x16x32_bf16 v[126:129], v[140:143], v[172:175], v[126:129]
	v_mfma_f32_16x16x32_bf16 v[122:125], v[148:151], v[172:175], v[122:125]
	v_mfma_f32_16x16x32_bf16 v[118:121], v[140:143], v[180:183], v[118:121]
	v_mfma_f32_16x16x32_bf16 v[114:117], v[148:151], v[180:183], v[114:117]
	v_mfma_f32_16x16x32_bf16 v[102:105], v[140:143], v[188:191], v[102:105]
	v_mfma_f32_16x16x32_bf16 v[98:101], v[148:151], v[188:191], v[98:101]
	v_mfma_f32_16x16x32_bf16 v[86:89], v[140:143], v[204:207], v[86:89]
	v_mfma_f32_16x16x32_bf16 v[82:85], v[148:151], v[204:207], v[82:85]
	v_mfma_f32_16x16x32_bf16 v[126:129], v[144:147], v[176:179], v[126:129]
	v_mfma_f32_16x16x32_bf16 v[122:125], v[152:155], v[176:179], v[122:125]
	v_mfma_f32_16x16x32_bf16 v[118:121], v[144:147], v[184:187], v[118:121]
	v_mfma_f32_16x16x32_bf16 v[114:117], v[152:155], v[184:187], v[114:117]
	v_mfma_f32_16x16x32_bf16 v[102:105], v[144:147], v[192:195], v[102:105]
	v_mfma_f32_16x16x32_bf16 v[98:101], v[152:155], v[192:195], v[98:101]
	v_mfma_f32_16x16x32_bf16 v[86:89], v[144:147], v[208:211], v[86:89]
	v_mfma_f32_16x16x32_bf16 v[82:85], v[152:155], v[208:211], v[82:85]
	v_mfma_f32_16x16x32_bf16 v[110:113], v[156:159], v[172:175], v[110:113]
	v_mfma_f32_16x16x32_bf16 v[106:109], v[164:167], v[172:175], v[106:109]
	v_mfma_f32_16x16x32_bf16 v[94:97], v[156:159], v[180:183], v[94:97]
	v_mfma_f32_16x16x32_bf16 v[90:93], v[164:167], v[180:183], v[90:93]
	v_mfma_f32_16x16x32_bf16 v[78:81], v[156:159], v[188:191], v[78:81]
	v_mfma_f32_16x16x32_bf16 v[74:77], v[164:167], v[188:191], v[74:77]
	v_mfma_f32_16x16x32_bf16 v[70:73], v[156:159], v[204:207], v[70:73]
	v_mfma_f32_16x16x32_bf16 v[66:69], v[164:167], v[204:207], v[66:69]
	v_mfma_f32_16x16x32_bf16 v[110:113], v[160:163], v[176:179], v[110:113]
	v_mfma_f32_16x16x32_bf16 v[106:109], v[168:171], v[176:179], v[106:109]
	v_mfma_f32_16x16x32_bf16 v[94:97], v[160:163], v[184:187], v[94:97]
	v_mfma_f32_16x16x32_bf16 v[90:93], v[168:171], v[184:187], v[90:93]
	v_mfma_f32_16x16x32_bf16 v[78:81], v[160:163], v[192:195], v[78:81]
	v_mfma_f32_16x16x32_bf16 v[74:77], v[168:171], v[192:195], v[74:77]
	v_mfma_f32_16x16x32_bf16 v[70:73], v[160:163], v[208:211], v[70:73]
	v_mfma_f32_16x16x32_bf16 v[66:69], v[168:171], v[208:211], v[66:69]
	s_barrier
	s_mov_b32 m0, s49
	v_lshl_add_u64 v[212:213], v[212:213], 0, s[94:95]
	ds_read_b128 v[172:175], v138 offset:49152
	ds_read_b128 v[176:179], v138 offset:50176
	ds_read_b128 v[180:183], v138 offset:51200
	ds_read_b128 v[184:187], v138 offset:52224
	ds_read_b128 v[188:191], v138 offset:53248
	ds_read_b128 v[192:195], v138 offset:54272
	ds_read_b128 v[204:207], v138 offset:55296
	ds_read_b128 v[208:211], v138 offset:56320
	global_load_lds_dwordx4 v[212:213], off
	v_lshl_add_u64 v[212:213], v[214:215], 0, s[94:95]
	s_mov_b32 m0, s48
	s_nop 0
	global_load_lds_dwordx4 v[212:213], off
	v_lshl_add_u64 v[212:213], s[12:13], 0, v[132:133]
	s_mov_b32 m0, s57
	s_nop 0
	global_load_lds_dwordx4 v[212:213], off
	v_lshl_add_u64 v[212:213], s[12:13], 0, v[136:137]
	s_mov_b32 m0, s56
	s_nop 0
	global_load_lds_dwordx4 v[212:213], off
	v_lshl_add_u64 v[212:213], v[216:217], 0, s[94:95]
	s_mov_b32 m0, s46
	s_nop 0
	global_load_lds_dwordx4 v[212:213], off
	v_lshl_add_u64 v[212:213], v[228:229], 0, s[94:95]
	s_mov_b32 m0, s47
	s_nop 0
	global_load_lds_dwordx4 v[212:213], off
	s_waitcnt vmcnt(8)
	s_waitcnt lgkmcnt(0)
	s_barrier
	s_waitcnt lgkmcnt(0)
	v_mfma_f32_16x16x32_bf16 v[62:65], v[140:143], v[172:175], v[62:65]
	v_mfma_f32_16x16x32_bf16 v[58:61], v[148:151], v[172:175], v[58:61]
	v_mfma_f32_16x16x32_bf16 v[54:57], v[140:143], v[180:183], v[54:57]
	v_mfma_f32_16x16x32_bf16 v[50:53], v[148:151], v[180:183], v[50:53]
	v_mfma_f32_16x16x32_bf16 v[38:41], v[140:143], v[188:191], v[38:41]
	v_mfma_f32_16x16x32_bf16 v[34:37], v[148:151], v[188:191], v[34:37]
	v_mfma_f32_16x16x32_bf16 v[22:25], v[140:143], v[204:207], v[22:25]
	v_mfma_f32_16x16x32_bf16 v[18:21], v[148:151], v[204:207], v[18:21]
	v_mfma_f32_16x16x32_bf16 v[62:65], v[144:147], v[176:179], v[62:65]
	v_mfma_f32_16x16x32_bf16 v[58:61], v[152:155], v[176:179], v[58:61]
	v_mfma_f32_16x16x32_bf16 v[54:57], v[144:147], v[184:187], v[54:57]
	v_mfma_f32_16x16x32_bf16 v[50:53], v[152:155], v[184:187], v[50:53]
	v_mfma_f32_16x16x32_bf16 v[38:41], v[144:147], v[192:195], v[38:41]
	v_mfma_f32_16x16x32_bf16 v[34:37], v[152:155], v[192:195], v[34:37]
	v_mfma_f32_16x16x32_bf16 v[22:25], v[144:147], v[208:211], v[22:25]
	v_mfma_f32_16x16x32_bf16 v[18:21], v[152:155], v[208:211], v[18:21]
	v_mfma_f32_16x16x32_bf16 v[46:49], v[156:159], v[172:175], v[46:49]
	v_mfma_f32_16x16x32_bf16 v[42:45], v[164:167], v[172:175], v[42:45]
	v_mfma_f32_16x16x32_bf16 v[30:33], v[156:159], v[180:183], v[30:33]
	v_mfma_f32_16x16x32_bf16 v[26:29], v[164:167], v[180:183], v[26:29]
	v_mfma_f32_16x16x32_bf16 v[14:17], v[156:159], v[188:191], v[14:17]
	v_mfma_f32_16x16x32_bf16 v[10:13], v[164:167], v[188:191], v[10:13]
	v_mfma_f32_16x16x32_bf16 v[6:9], v[156:159], v[204:207], v[6:9]
	v_mfma_f32_16x16x32_bf16 v[2:5], v[164:167], v[204:207], v[2:5]
	v_mfma_f32_16x16x32_bf16 v[46:49], v[160:163], v[176:179], v[46:49]
	v_mfma_f32_16x16x32_bf16 v[42:45], v[168:171], v[176:179], v[42:45]
	v_mfma_f32_16x16x32_bf16 v[30:33], v[160:163], v[184:187], v[30:33]
	v_mfma_f32_16x16x32_bf16 v[26:29], v[168:171], v[184:187], v[26:29]
	v_mfma_f32_16x16x32_bf16 v[14:17], v[160:163], v[192:195], v[14:17]
	v_mfma_f32_16x16x32_bf16 v[10:13], v[168:171], v[192:195], v[10:13]
	v_mfma_f32_16x16x32_bf16 v[6:9], v[160:163], v[208:211], v[6:9]
	v_mfma_f32_16x16x32_bf16 v[2:5], v[168:171], v[208:211], v[2:5]
	s_barrier
	s_andn2_b64 vcc, exec, s[8:9]
	s_mov_b64 s[12:13], -1
	s_mov_b64 s[8:9], 0
	s_movk_i32 s14, 0x100
	s_cbranch_vccz .LBB0_260
	s_cmpk_lt_u32 s38, 0x100
	s_cbranch_scc0 .LBB0_246
	s_barrier
	s_branch .LBB0_246

.LBB0_326:
	s_add_u32 s30, s28, 0xfffc0080
	s_addc_u32 s31, s29, -1
	s_add_i32 s72, 0, 0x10000
	s_cmp_eq_u32 s71, 12
	s_cselect_b32 s35, s5, s31
	s_cselect_b32 s34, s21, s30
	s_cselect_b32 s31, s19, s70
	s_cselect_b32 s30, s36, s37
	s_add_i32 s74, 0, 0x14000
	v_add_u32_e32 v154, s72, v1
	v_add_u32_e32 v167, s74, v1
	ds_read_b128 v[142:145], v154
	ds_read_b128 v[146:149], v154 offset:1024
	ds_read_b128 v[150:153], v154 offset:2048
	ds_read_b128 v[154:157], v154 offset:3072
	ds_read_b128 v[158:161], v167
	ds_read_b128 v[162:165], v167 offset:1024
	ds_read_b128 v[168:171], v167 offset:2048
	ds_read_b128 v[172:175], v167 offset:3072
	v_lshl_add_u64 v[216:217], s[28:29], 0, v[138:139]
	s_add_i32 m0, s27, 0xc000
	ds_read_b128 v[176:179], v166
	ds_read_b128 v[180:183], v166 offset:1024
	ds_read_b128 v[184:187], v166 offset:2048
	ds_read_b128 v[188:191], v166 offset:3072
	ds_read_b128 v[192:195], v166 offset:4096
	ds_read_b128 v[204:207], v166 offset:5120
	ds_read_b128 v[208:211], v166 offset:6144
	ds_read_b128 v[212:215], v166 offset:7168
	global_load_lds_dwordx4 v[216:217], off
	v_lshl_add_u64 v[216:217], s[28:29], 0, v[140:141]
	s_add_i32 m0, s27, 0xe000
	s_nop 0
	global_load_lds_dwordx4 v[216:217], off
	s_waitcnt vmcnt(8)
	s_waitcnt lgkmcnt(0)
	s_barrier
	s_waitcnt lgkmcnt(0)
	v_mfma_f32_16x16x32_bf16 v[126:129], v[142:145], v[176:179], v[126:129]
	v_mfma_f32_16x16x32_bf16 v[122:125], v[150:153], v[176:179], v[122:125]
	v_mfma_f32_16x16x32_bf16 v[110:113], v[142:145], v[184:187], v[110:113]
	v_mfma_f32_16x16x32_bf16 v[106:109], v[150:153], v[184:187], v[106:109]
	v_mfma_f32_16x16x32_bf16 v[94:97], v[142:145], v[192:195], v[94:97]
	v_mfma_f32_16x16x32_bf16 v[90:93], v[150:153], v[192:195], v[90:93]
	v_mfma_f32_16x16x32_bf16 v[78:81], v[142:145], v[208:211], v[78:81]
	v_mfma_f32_16x16x32_bf16 v[74:77], v[150:153], v[208:211], v[74:77]
	v_mfma_f32_16x16x32_bf16 v[126:129], v[146:149], v[180:183], v[126:129]
	v_mfma_f32_16x16x32_bf16 v[122:125], v[154:157], v[180:183], v[122:125]
	v_mfma_f32_16x16x32_bf16 v[110:113], v[146:149], v[188:191], v[110:113]
	v_mfma_f32_16x16x32_bf16 v[106:109], v[154:157], v[188:191], v[106:109]
	v_mfma_f32_16x16x32_bf16 v[94:97], v[146:149], v[204:207], v[94:97]
	v_mfma_f32_16x16x32_bf16 v[90:93], v[154:157], v[204:207], v[90:93]
	v_mfma_f32_16x16x32_bf16 v[78:81], v[146:149], v[212:215], v[78:81]
	v_mfma_f32_16x16x32_bf16 v[74:77], v[154:157], v[212:215], v[74:77]
	v_mfma_f32_16x16x32_bf16 v[118:121], v[158:161], v[176:179], v[118:121]
	v_mfma_f32_16x16x32_bf16 v[114:117], v[168:171], v[176:179], v[114:117]
	v_mfma_f32_16x16x32_bf16 v[102:105], v[158:161], v[184:187], v[102:105]
	v_mfma_f32_16x16x32_bf16 v[98:101], v[168:171], v[184:187], v[98:101]
	v_mfma_f32_16x16x32_bf16 v[86:89], v[158:161], v[192:195], v[86:89]
	v_mfma_f32_16x16x32_bf16 v[82:85], v[168:171], v[192:195], v[82:85]
	v_mfma_f32_16x16x32_bf16 v[70:73], v[158:161], v[208:211], v[70:73]
	v_mfma_f32_16x16x32_bf16 v[66:69], v[168:171], v[208:211], v[66:69]
	v_mfma_f32_16x16x32_bf16 v[118:121], v[162:165], v[180:183], v[118:121]
	v_mfma_f32_16x16x32_bf16 v[114:117], v[172:175], v[180:183], v[114:117]
	v_mfma_f32_16x16x32_bf16 v[102:105], v[162:165], v[188:191], v[102:105]
	v_mfma_f32_16x16x32_bf16 v[98:101], v[172:175], v[188:191], v[98:101]
	v_mfma_f32_16x16x32_bf16 v[86:89], v[162:165], v[204:207], v[86:89]
	v_mfma_f32_16x16x32_bf16 v[82:85], v[172:175], v[204:207], v[82:85]
	v_mfma_f32_16x16x32_bf16 v[70:73], v[162:165], v[212:215], v[70:73]
	v_mfma_f32_16x16x32_bf16 v[66:69], v[172:175], v[212:215], v[66:69]
	s_barrier
	s_add_i32 s72, s72, s44
	v_lshl_add_u64 v[216:217], s[30:31], 0, v[132:133]
	s_mov_b32 m0, s72
	ds_read_b128 v[176:179], v166 offset:16384
	ds_read_b128 v[180:183], v166 offset:17408
	ds_read_b128 v[184:187], v166 offset:18432
	ds_read_b128 v[188:191], v166 offset:19456
	ds_read_b128 v[192:195], v166 offset:20480
	ds_read_b128 v[204:207], v166 offset:21504
	ds_read_b128 v[208:211], v166 offset:22528
	ds_read_b128 v[212:215], v166 offset:23552
	global_load_lds_dwordx4 v[216:217], off
	s_add_i32 m0, s72, 0x2000
	s_add_u32 s72, s30, 0x40000
	v_lshl_add_u64 v[228:229], s[30:31], 0, v[136:137]
	s_addc_u32 s73, s31, 0
	s_add_i32 s74, s74, s44
	global_load_lds_dwordx4 v[228:229], off
	v_lshl_add_u64 v[230:231], s[72:73], 0, v[132:133]
	s_mov_b32 m0, s74
	v_lshl_add_u64 v[232:233], s[34:35], 0, v[134:135]
	global_load_lds_dwordx4 v[230:231], off
	v_lshl_add_u64 v[230:231], s[72:73], 0, v[136:137]
	s_add_i32 m0, s74, 0x2000
	s_nop 0
	global_load_lds_dwordx4 v[230:231], off
	v_lshl_add_u64 v[230:231], s[34:35], 0, v[130:131]
	s_mov_b32 m0, s27
	s_nop 0
	global_load_lds_dwordx4 v[230:231], off
	s_mov_b32 m0, s45
	s_nop 0
	global_load_lds_dwordx4 v[232:233], off
	s_waitcnt vmcnt(8)
	s_waitcnt lgkmcnt(0)
	s_barrier
	s_waitcnt lgkmcnt(0)
	v_mfma_f32_16x16x32_bf16 v[62:65], v[142:145], v[176:179], v[62:65]
	v_mfma_f32_16x16x32_bf16 v[58:61], v[150:153], v[176:179], v[58:61]
	v_mfma_f32_16x16x32_bf16 v[46:49], v[142:145], v[184:187], v[46:49]
	v_mfma_f32_16x16x32_bf16 v[42:45], v[150:153], v[184:187], v[42:45]
	v_mfma_f32_16x16x32_bf16 v[30:33], v[142:145], v[192:195], v[30:33]
	v_mfma_f32_16x16x32_bf16 v[26:29], v[150:153], v[192:195], v[26:29]
	v_mfma_f32_16x16x32_bf16 v[14:17], v[142:145], v[208:211], v[14:17]
	v_mfma_f32_16x16x32_bf16 v[10:13], v[150:153], v[208:211], v[10:13]
	v_mfma_f32_16x16x32_bf16 v[62:65], v[146:149], v[180:183], v[62:65]
	v_mfma_f32_16x16x32_bf16 v[58:61], v[154:157], v[180:183], v[58:61]
	v_mfma_f32_16x16x32_bf16 v[46:49], v[146:149], v[188:191], v[46:49]
	v_mfma_f32_16x16x32_bf16 v[42:45], v[154:157], v[188:191], v[42:45]
	v_mfma_f32_16x16x32_bf16 v[30:33], v[146:149], v[204:207], v[30:33]
	v_mfma_f32_16x16x32_bf16 v[26:29], v[154:157], v[204:207], v[26:29]
	v_mfma_f32_16x16x32_bf16 v[14:17], v[146:149], v[212:215], v[14:17]
	v_mfma_f32_16x16x32_bf16 v[10:13], v[154:157], v[212:215], v[10:13]
	v_mfma_f32_16x16x32_bf16 v[54:57], v[158:161], v[176:179], v[54:57]
	v_mfma_f32_16x16x32_bf16 v[50:53], v[168:171], v[176:179], v[50:53]
	v_mfma_f32_16x16x32_bf16 v[38:41], v[158:161], v[184:187], v[38:41]
	v_mfma_f32_16x16x32_bf16 v[34:37], v[168:171], v[184:187], v[34:37]
	v_mfma_f32_16x16x32_bf16 v[22:25], v[158:161], v[192:195], v[22:25]
	v_mfma_f32_16x16x32_bf16 v[18:21], v[168:171], v[192:195], v[18:21]
	v_mfma_f32_16x16x32_bf16 v[6:9], v[158:161], v[208:211], v[6:9]
	v_mfma_f32_16x16x32_bf16 v[2:5], v[168:171], v[208:211], v[2:5]
	v_mfma_f32_16x16x32_bf16 v[54:57], v[162:165], v[180:183], v[54:57]
	v_mfma_f32_16x16x32_bf16 v[50:53], v[172:175], v[180:183], v[50:53]
	v_mfma_f32_16x16x32_bf16 v[38:41], v[162:165], v[188:191], v[38:41]
	v_mfma_f32_16x16x32_bf16 v[34:37], v[172:175], v[188:191], v[34:37]
	v_mfma_f32_16x16x32_bf16 v[22:25], v[162:165], v[204:207], v[22:25]
	v_mfma_f32_16x16x32_bf16 v[18:21], v[172:175], v[204:207], v[18:21]
	v_mfma_f32_16x16x32_bf16 v[6:9], v[162:165], v[212:215], v[6:9]
	v_mfma_f32_16x16x32_bf16 v[2:5], v[172:175], v[212:215], v[2:5]
	s_barrier
	s_add_i32 s72, 0, 0x18000
	s_add_i32 s73, 0, 0x1c000
	v_add_u32_e32 v154, s72, v1
	v_add_u32_e32 v167, s73, v1
	ds_read_b128 v[142:145], v154
	ds_read_b128 v[146:149], v154 offset:1024
	ds_read_b128 v[150:153], v154 offset:2048
	ds_read_b128 v[154:157], v154 offset:3072
	ds_read_b128 v[158:161], v167
	ds_read_b128 v[162:165], v167 offset:1024
	ds_read_b128 v[168:171], v167 offset:2048
	ds_read_b128 v[172:175], v167 offset:3072
	s_add_u32 s34, s34, 0x40000
	s_addc_u32 s35, s35, 0
	s_mov_b32 m0, s46
	v_lshl_add_u64 v[234:235], s[34:35], 0, v[130:131]
	ds_read_b128 v[176:179], v166 offset:32768
	ds_read_b128 v[180:183], v166 offset:33792
	ds_read_b128 v[184:187], v166 offset:34816
	ds_read_b128 v[188:191], v166 offset:35840
	ds_read_b128 v[192:195], v166 offset:36864
	ds_read_b128 v[204:207], v166 offset:37888
	ds_read_b128 v[208:211], v166 offset:38912
	ds_read_b128 v[212:215], v166 offset:39936
	global_load_lds_dwordx4 v[234:235], off
	v_lshl_add_u64 v[234:235], s[34:35], 0, v[134:135]
	s_mov_b32 m0, s47
	s_nop 0
	global_load_lds_dwordx4 v[234:235], off
	s_waitcnt vmcnt(8)
	s_waitcnt lgkmcnt(0)
	s_barrier
	s_waitcnt lgkmcnt(0)
	v_mfma_f32_16x16x32_bf16 v[126:129], v[142:145], v[176:179], v[126:129]
	v_mfma_f32_16x16x32_bf16 v[122:125], v[150:153], v[176:179], v[122:125]
	v_mfma_f32_16x16x32_bf16 v[110:113], v[142:145], v[184:187], v[110:113]
	v_mfma_f32_16x16x32_bf16 v[106:109], v[150:153], v[184:187], v[106:109]
	v_mfma_f32_16x16x32_bf16 v[94:97], v[142:145], v[192:195], v[94:97]
	v_mfma_f32_16x16x32_bf16 v[90:93], v[150:153], v[192:195], v[90:93]
	v_mfma_f32_16x16x32_bf16 v[78:81], v[142:145], v[208:211], v[78:81]
	v_mfma_f32_16x16x32_bf16 v[74:77], v[150:153], v[208:211], v[74:77]
	v_mfma_f32_16x16x32_bf16 v[126:129], v[146:149], v[180:183], v[126:129]
	v_mfma_f32_16x16x32_bf16 v[122:125], v[154:157], v[180:183], v[122:125]
	v_mfma_f32_16x16x32_bf16 v[110:113], v[146:149], v[188:191], v[110:113]
	v_mfma_f32_16x16x32_bf16 v[106:109], v[154:157], v[188:191], v[106:109]
	v_mfma_f32_16x16x32_bf16 v[94:97], v[146:149], v[204:207], v[94:97]
	v_mfma_f32_16x16x32_bf16 v[90:93], v[154:157], v[204:207], v[90:93]
	v_mfma_f32_16x16x32_bf16 v[78:81], v[146:149], v[212:215], v[78:81]
	v_mfma_f32_16x16x32_bf16 v[74:77], v[154:157], v[212:215], v[74:77]
	v_mfma_f32_16x16x32_bf16 v[118:121], v[158:161], v[176:179], v[118:121]
	v_mfma_f32_16x16x32_bf16 v[114:117], v[168:171], v[176:179], v[114:117]
	v_mfma_f32_16x16x32_bf16 v[102:105], v[158:161], v[184:187], v[102:105]
	v_mfma_f32_16x16x32_bf16 v[98:101], v[168:171], v[184:187], v[98:101]
	v_mfma_f32_16x16x32_bf16 v[86:89], v[158:161], v[192:195], v[86:89]
	v_mfma_f32_16x16x32_bf16 v[82:85], v[168:171], v[192:195], v[82:85]
	v_mfma_f32_16x16x32_bf16 v[70:73], v[158:161], v[208:211], v[70:73]
	v_mfma_f32_16x16x32_bf16 v[66:69], v[168:171], v[208:211], v[66:69]
	v_mfma_f32_16x16x32_bf16 v[118:121], v[162:165], v[180:183], v[118:121]
	v_mfma_f32_16x16x32_bf16 v[114:117], v[172:175], v[180:183], v[114:117]
	v_mfma_f32_16x16x32_bf16 v[102:105], v[162:165], v[188:191], v[102:105]
	v_mfma_f32_16x16x32_bf16 v[98:101], v[172:175], v[188:191], v[98:101]
	v_mfma_f32_16x16x32_bf16 v[86:89], v[162:165], v[204:207], v[86:89]
	v_mfma_f32_16x16x32_bf16 v[82:85], v[172:175], v[204:207], v[82:85]
	v_mfma_f32_16x16x32_bf16 v[70:73], v[162:165], v[212:215], v[70:73]
	v_mfma_f32_16x16x32_bf16 v[66:69], v[172:175], v[212:215], v[66:69]
	s_barrier
	s_add_i32 s34, s72, s44
	v_lshl_add_u64 v[216:217], v[216:217], 0, s[94:95]
	s_mov_b32 m0, s34
	ds_read_b128 v[176:179], v166 offset:49152
	ds_read_b128 v[180:183], v166 offset:50176
	ds_read_b128 v[184:187], v166 offset:51200
	ds_read_b128 v[188:191], v166 offset:52224
	ds_read_b128 v[192:195], v166 offset:53248
	ds_read_b128 v[204:207], v166 offset:54272
	ds_read_b128 v[208:211], v166 offset:55296
	ds_read_b128 v[212:215], v166 offset:56320
	global_load_lds_dwordx4 v[216:217], off
	s_add_i32 m0, s34, 0x2000
	s_add_u32 s30, s30, 0x40080
	v_lshl_add_u64 v[216:217], v[228:229], 0, s[94:95]
	s_addc_u32 s31, s31, 0
	s_add_i32 s34, s73, s44
	global_load_lds_dwordx4 v[216:217], off
	v_lshl_add_u64 v[216:217], s[30:31], 0, v[132:133]
	s_mov_b32 m0, s34
	s_nop 0
	global_load_lds_dwordx4 v[216:217], off
	v_lshl_add_u64 v[216:217], s[30:31], 0, v[136:137]
	s_add_i32 m0, s34, 0x2000
	s_nop 0
	global_load_lds_dwordx4 v[216:217], off
	v_lshl_add_u64 v[216:217], v[230:231], 0, s[94:95]
	s_mov_b32 m0, s60
	s_nop 0
	global_load_lds_dwordx4 v[216:217], off
	v_lshl_add_u64 v[216:217], v[232:233], 0, s[94:95]
	s_mov_b32 m0, s61
	s_nop 0
	global_load_lds_dwordx4 v[216:217], off
	s_waitcnt vmcnt(8)
	s_waitcnt lgkmcnt(0)
	s_barrier
	s_waitcnt lgkmcnt(0)
	v_mfma_f32_16x16x32_bf16 v[62:65], v[142:145], v[176:179], v[62:65]
	v_mfma_f32_16x16x32_bf16 v[58:61], v[150:153], v[176:179], v[58:61]
	v_mfma_f32_16x16x32_bf16 v[46:49], v[142:145], v[184:187], v[46:49]
	v_mfma_f32_16x16x32_bf16 v[42:45], v[150:153], v[184:187], v[42:45]
	v_mfma_f32_16x16x32_bf16 v[30:33], v[142:145], v[192:195], v[30:33]
	v_mfma_f32_16x16x32_bf16 v[26:29], v[150:153], v[192:195], v[26:29]
	v_mfma_f32_16x16x32_bf16 v[14:17], v[142:145], v[208:211], v[14:17]
	v_mfma_f32_16x16x32_bf16 v[10:13], v[150:153], v[208:211], v[10:13]
	v_mfma_f32_16x16x32_bf16 v[62:65], v[146:149], v[180:183], v[62:65]
	v_mfma_f32_16x16x32_bf16 v[58:61], v[154:157], v[180:183], v[58:61]
	v_mfma_f32_16x16x32_bf16 v[46:49], v[146:149], v[188:191], v[46:49]
	v_mfma_f32_16x16x32_bf16 v[42:45], v[154:157], v[188:191], v[42:45]
	v_mfma_f32_16x16x32_bf16 v[30:33], v[146:149], v[204:207], v[30:33]
	v_mfma_f32_16x16x32_bf16 v[26:29], v[154:157], v[204:207], v[26:29]
	v_mfma_f32_16x16x32_bf16 v[14:17], v[146:149], v[212:215], v[14:17]
	v_mfma_f32_16x16x32_bf16 v[10:13], v[154:157], v[212:215], v[10:13]
	v_mfma_f32_16x16x32_bf16 v[54:57], v[158:161], v[176:179], v[54:57]
	v_mfma_f32_16x16x32_bf16 v[50:53], v[168:171], v[176:179], v[50:53]
	v_mfma_f32_16x16x32_bf16 v[38:41], v[158:161], v[184:187], v[38:41]
	v_mfma_f32_16x16x32_bf16 v[34:37], v[168:171], v[184:187], v[34:37]
	v_mfma_f32_16x16x32_bf16 v[22:25], v[158:161], v[192:195], v[22:25]
	v_mfma_f32_16x16x32_bf16 v[18:21], v[168:171], v[192:195], v[18:21]
	v_mfma_f32_16x16x32_bf16 v[6:9], v[158:161], v[208:211], v[6:9]
	v_mfma_f32_16x16x32_bf16 v[2:5], v[168:171], v[208:211], v[2:5]
	v_mfma_f32_16x16x32_bf16 v[54:57], v[162:165], v[180:183], v[54:57]
	v_mfma_f32_16x16x32_bf16 v[50:53], v[172:175], v[180:183], v[50:53]
	v_mfma_f32_16x16x32_bf16 v[38:41], v[162:165], v[188:191], v[38:41]
	v_mfma_f32_16x16x32_bf16 v[34:37], v[172:175], v[188:191], v[34:37]
	v_mfma_f32_16x16x32_bf16 v[22:25], v[162:165], v[204:207], v[22:25]
	v_mfma_f32_16x16x32_bf16 v[18:21], v[172:175], v[204:207], v[18:21]
	v_mfma_f32_16x16x32_bf16 v[6:9], v[162:165], v[212:215], v[6:9]
	v_mfma_f32_16x16x32_bf16 v[2:5], v[172:175], v[212:215], v[2:5]
	s_barrier
	s_add_i32 s71, s71, 2
	s_add_u32 s28, s28, 0x100
	s_addc_u32 s29, s29, 0
	s_add_u32 s37, s37, 0x100
	s_addc_u32 s70, s70, 0
	s_cmp_gt_u32 s71, 13
	s_cbranch_scc0 .LBB0_326
	s_and_b64 vcc, exec, s[14:15]
	s_cbranch_vccz .LBB0_329
	s_barrier

.LBB0_807:
	s_add_u32 s36, s26, s34
	s_addc_u32 s37, s27, s35
	s_add_u32 s36, s36, 0x100
	s_addc_u32 s37, s37, 0
	s_add_u32 s65, s62, s34
	s_addc_u32 s66, s63, s35
	s_add_i32 s67, 0, 0x10000
	s_cmpk_eq_i32 s34, 0x700
	s_cselect_b32 s39, s19, s37
	s_cselect_b32 s38, s25, s36
	s_cselect_b32 s37, s17, s66
	s_cselect_b32 s36, s60, s65
	s_add_i32 s65, 0, 0x14000
	v_add_u32_e32 v142, s67, v1
	v_add_u32_e32 v158, s65, v1
	ds_read_b128 v[130:133], v142
	ds_read_b128 v[134:137], v142 offset:1024
	ds_read_b128 v[138:141], v142 offset:2048
	ds_read_b128 v[142:145], v142 offset:3072
	ds_read_b128 v[146:149], v158
	ds_read_b128 v[150:153], v158 offset:1024
	ds_read_b128 v[154:157], v158 offset:2048
	ds_read_b128 v[158:161], v158 offset:3072
	v_lshl_add_u64 v[196:197], v[206:207], 0, s[34:35]
	s_add_i32 m0, s46, 0xc000
	ds_read_b128 v[162:165], v228
	ds_read_b128 v[166:169], v228 offset:1024
	ds_read_b128 v[170:173], v228 offset:2048
	ds_read_b128 v[174:177], v228 offset:3072
	ds_read_b128 v[178:181], v228 offset:4096
	ds_read_b128 v[182:185], v228 offset:5120
	ds_read_b128 v[210:213], v228 offset:6144
	ds_read_b128 v[214:217], v228 offset:7168
	global_load_lds_dwordx4 v[196:197], off
	v_lshl_add_u64 v[196:197], v[208:209], 0, s[34:35]
	s_add_i32 m0, s46, 0xe000
	s_nop 0
	global_load_lds_dwordx4 v[196:197], off
	s_waitcnt vmcnt(8)
	s_waitcnt lgkmcnt(0)
	s_barrier
	s_waitcnt lgkmcnt(0)
	v_mfma_f32_16x16x32_bf16 v[126:129], v[130:133], v[162:165], v[126:129]
	v_mfma_f32_16x16x32_bf16 v[122:125], v[138:141], v[162:165], v[122:125]
	v_mfma_f32_16x16x32_bf16 v[110:113], v[130:133], v[170:173], v[110:113]
	v_mfma_f32_16x16x32_bf16 v[106:109], v[138:141], v[170:173], v[106:109]
	v_mfma_f32_16x16x32_bf16 v[94:97], v[130:133], v[178:181], v[94:97]
	v_mfma_f32_16x16x32_bf16 v[90:93], v[138:141], v[178:181], v[90:93]
	v_mfma_f32_16x16x32_bf16 v[78:81], v[130:133], v[210:213], v[78:81]
	v_mfma_f32_16x16x32_bf16 v[74:77], v[138:141], v[210:213], v[74:77]
	v_mfma_f32_16x16x32_bf16 v[126:129], v[134:137], v[166:169], v[126:129]
	v_mfma_f32_16x16x32_bf16 v[122:125], v[142:145], v[166:169], v[122:125]
	v_mfma_f32_16x16x32_bf16 v[110:113], v[134:137], v[174:177], v[110:113]
	v_mfma_f32_16x16x32_bf16 v[106:109], v[142:145], v[174:177], v[106:109]
	v_mfma_f32_16x16x32_bf16 v[94:97], v[134:137], v[182:185], v[94:97]
	v_mfma_f32_16x16x32_bf16 v[90:93], v[142:145], v[182:185], v[90:93]
	v_mfma_f32_16x16x32_bf16 v[78:81], v[134:137], v[214:217], v[78:81]
	v_mfma_f32_16x16x32_bf16 v[74:77], v[142:145], v[214:217], v[74:77]
	v_mfma_f32_16x16x32_bf16 v[118:121], v[146:149], v[162:165], v[118:121]
	v_mfma_f32_16x16x32_bf16 v[114:117], v[154:157], v[162:165], v[114:117]
	v_mfma_f32_16x16x32_bf16 v[102:105], v[146:149], v[170:173], v[102:105]
	v_mfma_f32_16x16x32_bf16 v[98:101], v[154:157], v[170:173], v[98:101]
	v_mfma_f32_16x16x32_bf16 v[86:89], v[146:149], v[178:181], v[86:89]
	v_mfma_f32_16x16x32_bf16 v[82:85], v[154:157], v[178:181], v[82:85]
	v_mfma_f32_16x16x32_bf16 v[70:73], v[146:149], v[210:213], v[70:73]
	v_mfma_f32_16x16x32_bf16 v[66:69], v[154:157], v[210:213], v[66:69]
	v_mfma_f32_16x16x32_bf16 v[118:121], v[150:153], v[166:169], v[118:121]
	v_mfma_f32_16x16x32_bf16 v[114:117], v[158:161], v[166:169], v[114:117]
	v_mfma_f32_16x16x32_bf16 v[102:105], v[150:153], v[174:177], v[102:105]
	v_mfma_f32_16x16x32_bf16 v[98:101], v[158:161], v[174:177], v[98:101]
	v_mfma_f32_16x16x32_bf16 v[86:89], v[150:153], v[182:185], v[86:89]
	v_mfma_f32_16x16x32_bf16 v[82:85], v[158:161], v[182:185], v[82:85]
	v_mfma_f32_16x16x32_bf16 v[70:73], v[150:153], v[214:217], v[70:73]
	v_mfma_f32_16x16x32_bf16 v[66:69], v[158:161], v[214:217], v[66:69]
	s_barrier
	s_add_i32 s66, s67, s45
	v_lshl_add_u64 v[196:197], s[36:37], 0, v[190:191]
	s_mov_b32 m0, s66
	ds_read_b128 v[162:165], v228 offset:16384
	ds_read_b128 v[166:169], v228 offset:17408
	ds_read_b128 v[170:173], v228 offset:18432
	ds_read_b128 v[174:177], v228 offset:19456
	ds_read_b128 v[178:181], v228 offset:20480
	ds_read_b128 v[182:185], v228 offset:21504
	ds_read_b128 v[210:213], v228 offset:22528
	ds_read_b128 v[214:217], v228 offset:23552
	global_load_lds_dwordx4 v[196:197], off
	s_add_i32 m0, s66, 0x2000
	s_add_u32 s66, s36, 0x40000
	v_lshl_add_u64 v[198:199], s[36:37], 0, v[186:187]
	s_addc_u32 s67, s37, 0
	s_add_i32 s65, s65, s45
	global_load_lds_dwordx4 v[198:199], off
	v_lshl_add_u64 v[220:221], s[66:67], 0, v[190:191]
	s_mov_b32 m0, s65
	v_lshl_add_u64 v[222:223], s[38:39], 0, v[188:189]
	global_load_lds_dwordx4 v[220:221], off
	v_lshl_add_u64 v[220:221], s[66:67], 0, v[186:187]
	s_add_i32 m0, s65, 0x2000
	s_nop 0
	global_load_lds_dwordx4 v[220:221], off
	v_lshl_add_u64 v[220:221], s[38:39], 0, v[192:193]
	s_mov_b32 m0, s46
	s_nop 0
	global_load_lds_dwordx4 v[220:221], off
	s_mov_b32 m0, s47
	s_nop 0
	global_load_lds_dwordx4 v[222:223], off
	s_waitcnt vmcnt(8)
	s_waitcnt lgkmcnt(0)
	s_barrier
	s_waitcnt lgkmcnt(0)
	v_mfma_f32_16x16x32_bf16 v[62:65], v[130:133], v[162:165], v[62:65]
	v_mfma_f32_16x16x32_bf16 v[58:61], v[138:141], v[162:165], v[58:61]
	v_mfma_f32_16x16x32_bf16 v[46:49], v[130:133], v[170:173], v[46:49]
	v_mfma_f32_16x16x32_bf16 v[42:45], v[138:141], v[170:173], v[42:45]
	v_mfma_f32_16x16x32_bf16 v[30:33], v[130:133], v[178:181], v[30:33]
	v_mfma_f32_16x16x32_bf16 v[26:29], v[138:141], v[178:181], v[26:29]
	v_mfma_f32_16x16x32_bf16 v[14:17], v[130:133], v[210:213], v[14:17]
	v_mfma_f32_16x16x32_bf16 v[10:13], v[138:141], v[210:213], v[10:13]
	v_mfma_f32_16x16x32_bf16 v[62:65], v[134:137], v[166:169], v[62:65]
	v_mfma_f32_16x16x32_bf16 v[58:61], v[142:145], v[166:169], v[58:61]
	v_mfma_f32_16x16x32_bf16 v[46:49], v[134:137], v[174:177], v[46:49]
	v_mfma_f32_16x16x32_bf16 v[42:45], v[142:145], v[174:177], v[42:45]
	v_mfma_f32_16x16x32_bf16 v[30:33], v[134:137], v[182:185], v[30:33]
	v_mfma_f32_16x16x32_bf16 v[26:29], v[142:145], v[182:185], v[26:29]
	v_mfma_f32_16x16x32_bf16 v[14:17], v[134:137], v[214:217], v[14:17]
	v_mfma_f32_16x16x32_bf16 v[10:13], v[142:145], v[214:217], v[10:13]
	v_mfma_f32_16x16x32_bf16 v[54:57], v[146:149], v[162:165], v[54:57]
	v_mfma_f32_16x16x32_bf16 v[50:53], v[154:157], v[162:165], v[50:53]
	v_mfma_f32_16x16x32_bf16 v[38:41], v[146:149], v[170:173], v[38:41]
	v_mfma_f32_16x16x32_bf16 v[34:37], v[154:157], v[170:173], v[34:37]
	v_mfma_f32_16x16x32_bf16 v[22:25], v[146:149], v[178:181], v[22:25]
	v_mfma_f32_16x16x32_bf16 v[18:21], v[154:157], v[178:181], v[18:21]
	v_mfma_f32_16x16x32_bf16 v[6:9], v[146:149], v[210:213], v[6:9]
	v_mfma_f32_16x16x32_bf16 v[2:5], v[154:157], v[210:213], v[2:5]
	v_mfma_f32_16x16x32_bf16 v[54:57], v[150:153], v[166:169], v[54:57]
	v_mfma_f32_16x16x32_bf16 v[50:53], v[158:161], v[166:169], v[50:53]
	v_mfma_f32_16x16x32_bf16 v[38:41], v[150:153], v[174:177], v[38:41]
	v_mfma_f32_16x16x32_bf16 v[34:37], v[158:161], v[174:177], v[34:37]
	v_mfma_f32_16x16x32_bf16 v[22:25], v[150:153], v[182:185], v[22:25]
	v_mfma_f32_16x16x32_bf16 v[18:21], v[158:161], v[182:185], v[18:21]
	v_mfma_f32_16x16x32_bf16 v[6:9], v[150:153], v[214:217], v[6:9]
	v_mfma_f32_16x16x32_bf16 v[2:5], v[158:161], v[214:217], v[2:5]
	s_barrier
	s_add_i32 s65, 0, 0x18000
	s_add_i32 s66, 0, 0x1c000
	v_add_u32_e32 v142, s65, v1
	v_add_u32_e32 v158, s66, v1
	ds_read_b128 v[130:133], v142
	ds_read_b128 v[134:137], v142 offset:1024
	ds_read_b128 v[138:141], v142 offset:2048
	ds_read_b128 v[142:145], v142 offset:3072
	ds_read_b128 v[146:149], v158
	ds_read_b128 v[150:153], v158 offset:1024
	ds_read_b128 v[154:157], v158 offset:2048
	ds_read_b128 v[158:161], v158 offset:3072
	s_add_u32 s38, s38, 0x40000
	s_addc_u32 s39, s39, 0
	s_mov_b32 m0, s48
	v_lshl_add_u64 v[230:231], s[38:39], 0, v[192:193]
	ds_read_b128 v[162:165], v228 offset:32768
	ds_read_b128 v[166:169], v228 offset:33792
	ds_read_b128 v[170:173], v228 offset:34816
	ds_read_b128 v[174:177], v228 offset:35840
	ds_read_b128 v[178:181], v228 offset:36864
	ds_read_b128 v[182:185], v228 offset:37888
	ds_read_b128 v[210:213], v228 offset:38912
	ds_read_b128 v[214:217], v228 offset:39936
	global_load_lds_dwordx4 v[230:231], off
	v_lshl_add_u64 v[230:231], s[38:39], 0, v[188:189]
	s_mov_b32 m0, s49
	s_nop 0
	global_load_lds_dwordx4 v[230:231], off
	s_waitcnt vmcnt(8)
	s_waitcnt lgkmcnt(0)
	s_barrier
	s_waitcnt lgkmcnt(0)
	v_mfma_f32_16x16x32_bf16 v[126:129], v[130:133], v[162:165], v[126:129]
	v_mfma_f32_16x16x32_bf16 v[122:125], v[138:141], v[162:165], v[122:125]
	v_mfma_f32_16x16x32_bf16 v[110:113], v[130:133], v[170:173], v[110:113]
	v_mfma_f32_16x16x32_bf16 v[106:109], v[138:141], v[170:173], v[106:109]
	v_mfma_f32_16x16x32_bf16 v[94:97], v[130:133], v[178:181], v[94:97]
	v_mfma_f32_16x16x32_bf16 v[90:93], v[138:141], v[178:181], v[90:93]
	v_mfma_f32_16x16x32_bf16 v[78:81], v[130:133], v[210:213], v[78:81]
	v_mfma_f32_16x16x32_bf16 v[74:77], v[138:141], v[210:213], v[74:77]
	v_mfma_f32_16x16x32_bf16 v[126:129], v[134:137], v[166:169], v[126:129]
	v_mfma_f32_16x16x32_bf16 v[122:125], v[142:145], v[166:169], v[122:125]
	v_mfma_f32_16x16x32_bf16 v[110:113], v[134:137], v[174:177], v[110:113]
	v_mfma_f32_16x16x32_bf16 v[106:109], v[142:145], v[174:177], v[106:109]
	v_mfma_f32_16x16x32_bf16 v[94:97], v[134:137], v[182:185], v[94:97]
	v_mfma_f32_16x16x32_bf16 v[90:93], v[142:145], v[182:185], v[90:93]
	v_mfma_f32_16x16x32_bf16 v[78:81], v[134:137], v[214:217], v[78:81]
	v_mfma_f32_16x16x32_bf16 v[74:77], v[142:145], v[214:217], v[74:77]
	v_mfma_f32_16x16x32_bf16 v[118:121], v[146:149], v[162:165], v[118:121]
	v_mfma_f32_16x16x32_bf16 v[114:117], v[154:157], v[162:165], v[114:117]
	v_mfma_f32_16x16x32_bf16 v[102:105], v[146:149], v[170:173], v[102:105]
	v_mfma_f32_16x16x32_bf16 v[98:101], v[154:157], v[170:173], v[98:101]
	v_mfma_f32_16x16x32_bf16 v[86:89], v[146:149], v[178:181], v[86:89]
	v_mfma_f32_16x16x32_bf16 v[82:85], v[154:157], v[178:181], v[82:85]
	v_mfma_f32_16x16x32_bf16 v[70:73], v[146:149], v[210:213], v[70:73]
	v_mfma_f32_16x16x32_bf16 v[66:69], v[154:157], v[210:213], v[66:69]
	v_mfma_f32_16x16x32_bf16 v[118:121], v[150:153], v[166:169], v[118:121]
	v_mfma_f32_16x16x32_bf16 v[114:117], v[158:161], v[166:169], v[114:117]
	v_mfma_f32_16x16x32_bf16 v[102:105], v[150:153], v[174:177], v[102:105]
	v_mfma_f32_16x16x32_bf16 v[98:101], v[158:161], v[174:177], v[98:101]
	v_mfma_f32_16x16x32_bf16 v[86:89], v[150:153], v[182:185], v[86:89]
	v_mfma_f32_16x16x32_bf16 v[82:85], v[158:161], v[182:185], v[82:85]
	v_mfma_f32_16x16x32_bf16 v[70:73], v[150:153], v[214:217], v[70:73]
	v_mfma_f32_16x16x32_bf16 v[66:69], v[158:161], v[214:217], v[66:69]
	s_barrier
	s_add_i32 s38, s65, s45
	v_lshl_add_u64 v[196:197], v[196:197], 0, s[94:95]
	s_mov_b32 m0, s38
	ds_read_b128 v[162:165], v228 offset:49152
	ds_read_b128 v[166:169], v228 offset:50176
	ds_read_b128 v[170:173], v228 offset:51200
	ds_read_b128 v[174:177], v228 offset:52224
	ds_read_b128 v[178:181], v228 offset:53248
	ds_read_b128 v[182:185], v228 offset:54272
	ds_read_b128 v[210:213], v228 offset:55296
	ds_read_b128 v[214:217], v228 offset:56320
	global_load_lds_dwordx4 v[196:197], off
	s_add_i32 m0, s38, 0x2000
	s_add_u32 s36, s36, 0x40080
	v_lshl_add_u64 v[196:197], v[198:199], 0, s[94:95]
	s_addc_u32 s37, s37, 0
	s_add_i32 s38, s66, s45
	global_load_lds_dwordx4 v[196:197], off
	v_lshl_add_u64 v[196:197], s[36:37], 0, v[190:191]
	s_mov_b32 m0, s38
	s_nop 0
	global_load_lds_dwordx4 v[196:197], off
	v_lshl_add_u64 v[196:197], s[36:37], 0, v[186:187]
	s_add_i32 m0, s38, 0x2000
	s_nop 0
	global_load_lds_dwordx4 v[196:197], off
	v_lshl_add_u64 v[196:197], v[220:221], 0, s[94:95]
	s_mov_b32 m0, s55
	s_nop 0
	global_load_lds_dwordx4 v[196:197], off
	v_lshl_add_u64 v[196:197], v[222:223], 0, s[94:95]
	s_mov_b32 m0, s56
	s_nop 0
	global_load_lds_dwordx4 v[196:197], off
	s_waitcnt vmcnt(8)
	s_waitcnt lgkmcnt(0)
	s_barrier
	s_waitcnt lgkmcnt(0)
	v_mfma_f32_16x16x32_bf16 v[62:65], v[130:133], v[162:165], v[62:65]
	v_mfma_f32_16x16x32_bf16 v[58:61], v[138:141], v[162:165], v[58:61]
	v_mfma_f32_16x16x32_bf16 v[46:49], v[130:133], v[170:173], v[46:49]
	v_mfma_f32_16x16x32_bf16 v[42:45], v[138:141], v[170:173], v[42:45]
	v_mfma_f32_16x16x32_bf16 v[30:33], v[130:133], v[178:181], v[30:33]
	v_mfma_f32_16x16x32_bf16 v[26:29], v[138:141], v[178:181], v[26:29]
	v_mfma_f32_16x16x32_bf16 v[14:17], v[130:133], v[210:213], v[14:17]
	v_mfma_f32_16x16x32_bf16 v[10:13], v[138:141], v[210:213], v[10:13]
	v_mfma_f32_16x16x32_bf16 v[62:65], v[134:137], v[166:169], v[62:65]
	v_mfma_f32_16x16x32_bf16 v[58:61], v[142:145], v[166:169], v[58:61]
	v_mfma_f32_16x16x32_bf16 v[46:49], v[134:137], v[174:177], v[46:49]
	v_mfma_f32_16x16x32_bf16 v[42:45], v[142:145], v[174:177], v[42:45]
	v_mfma_f32_16x16x32_bf16 v[30:33], v[134:137], v[182:185], v[30:33]
	v_mfma_f32_16x16x32_bf16 v[26:29], v[142:145], v[182:185], v[26:29]
	v_mfma_f32_16x16x32_bf16 v[14:17], v[134:137], v[214:217], v[14:17]
	v_mfma_f32_16x16x32_bf16 v[10:13], v[142:145], v[214:217], v[10:13]
	v_mfma_f32_16x16x32_bf16 v[54:57], v[146:149], v[162:165], v[54:57]
	v_mfma_f32_16x16x32_bf16 v[50:53], v[154:157], v[162:165], v[50:53]
	v_mfma_f32_16x16x32_bf16 v[38:41], v[146:149], v[170:173], v[38:41]
	v_mfma_f32_16x16x32_bf16 v[34:37], v[154:157], v[170:173], v[34:37]
	v_mfma_f32_16x16x32_bf16 v[22:25], v[146:149], v[178:181], v[22:25]
	v_mfma_f32_16x16x32_bf16 v[18:21], v[154:157], v[178:181], v[18:21]
	v_mfma_f32_16x16x32_bf16 v[6:9], v[146:149], v[210:213], v[6:9]
	v_mfma_f32_16x16x32_bf16 v[2:5], v[154:157], v[210:213], v[2:5]
	v_mfma_f32_16x16x32_bf16 v[54:57], v[150:153], v[166:169], v[54:57]
	v_mfma_f32_16x16x32_bf16 v[50:53], v[158:161], v[166:169], v[50:53]
	v_mfma_f32_16x16x32_bf16 v[38:41], v[150:153], v[174:177], v[38:41]
	v_mfma_f32_16x16x32_bf16 v[34:37], v[158:161], v[174:177], v[34:37]
	v_mfma_f32_16x16x32_bf16 v[22:25], v[150:153], v[182:185], v[22:25]
	v_mfma_f32_16x16x32_bf16 v[18:21], v[158:161], v[182:185], v[18:21]
	v_mfma_f32_16x16x32_bf16 v[6:9], v[150:153], v[214:217], v[6:9]
	v_mfma_f32_16x16x32_bf16 v[2:5], v[158:161], v[214:217], v[2:5]
	s_barrier
	s_add_i32 s36, s64, 2
	s_add_u32 s34, s34, 0x100
	s_addc_u32 s35, s35, 0
	s_cmp_gt_u32 s64, 13
	s_mov_b32 s64, s36
	s_cbranch_scc1 .LBB0_812

.LBB0_890:
	s_add_u32 s28, s26, 0xfffc0080
	s_addc_u32 s29, s27, -1
	s_add_i32 s55, 0, 0x10000
	s_cmp_eq_u32 s54, 12
	s_cselect_b32 s31, s17, s29
	s_cselect_b32 s30, s23, s28
	s_cselect_b32 s29, s15, s53
	s_cselect_b32 s28, s51, s52
	s_add_i32 s58, 0, 0x14000
	v_add_u32_e32 v134, s55, v1
	v_add_u32_e32 v154, s58, v1
	ds_read_b128 v[110:113], v134
	ds_read_b128 v[118:121], v134 offset:1024
	ds_read_b128 v[122:125], v134 offset:2048
	ds_read_b128 v[134:137], v134 offset:3072
	ds_read_b128 v[138:141], v154
	ds_read_b128 v[142:145], v154 offset:1024
	ds_read_b128 v[146:149], v154 offset:2048
	ds_read_b128 v[154:157], v154 offset:3072
	v_lshl_add_u64 v[196:197], s[26:27], 0, v[206:207]
	s_add_i32 m0, s25, 0xc000
	ds_read_b128 v[162:165], v214
	ds_read_b128 v[166:169], v214 offset:1024
	ds_read_b128 v[170:173], v214 offset:2048
	ds_read_b128 v[174:177], v214 offset:3072
	ds_read_b128 v[178:181], v214 offset:4096
	ds_read_b128 v[182:185], v214 offset:5120
	ds_read_b128 v[186:189], v214 offset:6144
	ds_read_b128 v[210:213], v214 offset:7168
	global_load_lds_dwordx4 v[196:197], off
	v_lshl_add_u64 v[196:197], s[26:27], 0, v[208:209]
	s_add_i32 m0, s25, 0xe000
	s_nop 0
	global_load_lds_dwordx4 v[196:197], off
	s_waitcnt vmcnt(8)
	s_waitcnt lgkmcnt(0)
	s_barrier
	s_waitcnt lgkmcnt(0)
	v_mfma_f32_16x16x32_bf16 v[158:161], v[110:113], v[162:165], v[158:161]
	v_mfma_f32_16x16x32_bf16 v[150:153], v[122:125], v[162:165], v[150:153]
	v_mfma_f32_16x16x32_bf16 v[114:117], v[110:113], v[170:173], v[114:117]
	v_mfma_f32_16x16x32_bf16 v[106:109], v[122:125], v[170:173], v[106:109]
	v_mfma_f32_16x16x32_bf16 v[94:97], v[110:113], v[178:181], v[94:97]
	v_mfma_f32_16x16x32_bf16 v[90:93], v[122:125], v[178:181], v[90:93]
	v_mfma_f32_16x16x32_bf16 v[78:81], v[110:113], v[186:189], v[78:81]
	v_mfma_f32_16x16x32_bf16 v[74:77], v[122:125], v[186:189], v[74:77]
	v_mfma_f32_16x16x32_bf16 v[158:161], v[118:121], v[166:169], v[158:161]
	v_mfma_f32_16x16x32_bf16 v[150:153], v[134:137], v[166:169], v[150:153]
	v_mfma_f32_16x16x32_bf16 v[114:117], v[118:121], v[174:177], v[114:117]
	v_mfma_f32_16x16x32_bf16 v[106:109], v[134:137], v[174:177], v[106:109]
	v_mfma_f32_16x16x32_bf16 v[94:97], v[118:121], v[182:185], v[94:97]
	v_mfma_f32_16x16x32_bf16 v[90:93], v[134:137], v[182:185], v[90:93]
	v_mfma_f32_16x16x32_bf16 v[78:81], v[118:121], v[210:213], v[78:81]
	v_mfma_f32_16x16x32_bf16 v[74:77], v[134:137], v[210:213], v[74:77]
	v_mfma_f32_16x16x32_bf16 v[130:133], v[138:141], v[162:165], v[130:133]
	v_mfma_f32_16x16x32_bf16 v[126:129], v[146:149], v[162:165], v[126:129]
	v_mfma_f32_16x16x32_bf16 v[102:105], v[138:141], v[170:173], v[102:105]
	v_mfma_f32_16x16x32_bf16 v[98:101], v[146:149], v[170:173], v[98:101]
	v_mfma_f32_16x16x32_bf16 v[86:89], v[138:141], v[178:181], v[86:89]
	v_mfma_f32_16x16x32_bf16 v[82:85], v[146:149], v[178:181], v[82:85]
	v_mfma_f32_16x16x32_bf16 v[70:73], v[138:141], v[186:189], v[70:73]
	v_mfma_f32_16x16x32_bf16 v[66:69], v[146:149], v[186:189], v[66:69]
	v_mfma_f32_16x16x32_bf16 v[130:133], v[142:145], v[166:169], v[130:133]
	v_mfma_f32_16x16x32_bf16 v[126:129], v[154:157], v[166:169], v[126:129]
	v_mfma_f32_16x16x32_bf16 v[102:105], v[142:145], v[174:177], v[102:105]
	v_mfma_f32_16x16x32_bf16 v[98:101], v[154:157], v[174:177], v[98:101]
	v_mfma_f32_16x16x32_bf16 v[86:89], v[142:145], v[182:185], v[86:89]
	v_mfma_f32_16x16x32_bf16 v[82:85], v[154:157], v[182:185], v[82:85]
	v_mfma_f32_16x16x32_bf16 v[70:73], v[142:145], v[210:213], v[70:73]
	v_mfma_f32_16x16x32_bf16 v[66:69], v[154:157], v[210:213], v[66:69]
	s_barrier
	s_add_i32 s55, s55, s40
	v_lshl_add_u64 v[196:197], s[28:29], 0, v[192:193]
	s_mov_b32 m0, s55
	ds_read_b128 v[162:165], v214 offset:16384
	ds_read_b128 v[166:169], v214 offset:17408
	ds_read_b128 v[170:173], v214 offset:18432
	ds_read_b128 v[174:177], v214 offset:19456
	ds_read_b128 v[178:181], v214 offset:20480
	ds_read_b128 v[182:185], v214 offset:21504
	ds_read_b128 v[186:189], v214 offset:22528
	ds_read_b128 v[210:213], v214 offset:23552
	global_load_lds_dwordx4 v[196:197], off
	s_add_i32 m0, s55, 0x2000
	s_add_u32 s56, s28, 0x40000
	v_lshl_add_u64 v[198:199], s[28:29], 0, v[204:205]
	s_addc_u32 s57, s29, 0
	s_add_i32 s55, s58, s40
	global_load_lds_dwordx4 v[198:199], off
	v_lshl_add_u64 v[216:217], s[56:57], 0, v[192:193]
	s_mov_b32 m0, s55
	v_lshl_add_u64 v[220:221], s[30:31], 0, v[194:195]
	global_load_lds_dwordx4 v[216:217], off
	v_lshl_add_u64 v[216:217], s[56:57], 0, v[204:205]
	s_add_i32 m0, s55, 0x2000
	s_nop 0
	global_load_lds_dwordx4 v[216:217], off
	v_lshl_add_u64 v[216:217], s[30:31], 0, v[190:191]
	s_mov_b32 m0, s25
	s_nop 0
	global_load_lds_dwordx4 v[216:217], off
	s_mov_b32 m0, s41
	s_nop 0
	global_load_lds_dwordx4 v[220:221], off
	s_waitcnt vmcnt(8)
	s_waitcnt lgkmcnt(0)
	s_barrier
	s_waitcnt lgkmcnt(0)
	v_mfma_f32_16x16x32_bf16 v[62:65], v[110:113], v[162:165], v[62:65]
	v_mfma_f32_16x16x32_bf16 v[58:61], v[122:125], v[162:165], v[58:61]
	v_mfma_f32_16x16x32_bf16 v[46:49], v[110:113], v[170:173], v[46:49]
	v_mfma_f32_16x16x32_bf16 v[42:45], v[122:125], v[170:173], v[42:45]
	v_mfma_f32_16x16x32_bf16 v[30:33], v[110:113], v[178:181], v[30:33]
	v_mfma_f32_16x16x32_bf16 v[26:29], v[122:125], v[178:181], v[26:29]
	v_mfma_f32_16x16x32_bf16 v[14:17], v[110:113], v[186:189], v[14:17]
	v_mfma_f32_16x16x32_bf16 v[10:13], v[122:125], v[186:189], v[10:13]
	v_mfma_f32_16x16x32_bf16 v[62:65], v[118:121], v[166:169], v[62:65]
	v_mfma_f32_16x16x32_bf16 v[58:61], v[134:137], v[166:169], v[58:61]
	v_mfma_f32_16x16x32_bf16 v[46:49], v[118:121], v[174:177], v[46:49]
	v_mfma_f32_16x16x32_bf16 v[42:45], v[134:137], v[174:177], v[42:45]
	v_mfma_f32_16x16x32_bf16 v[30:33], v[118:121], v[182:185], v[30:33]
	v_mfma_f32_16x16x32_bf16 v[26:29], v[134:137], v[182:185], v[26:29]
	v_mfma_f32_16x16x32_bf16 v[14:17], v[118:121], v[210:213], v[14:17]
	v_mfma_f32_16x16x32_bf16 v[10:13], v[134:137], v[210:213], v[10:13]
	v_mfma_f32_16x16x32_bf16 v[54:57], v[138:141], v[162:165], v[54:57]
	v_mfma_f32_16x16x32_bf16 v[50:53], v[146:149], v[162:165], v[50:53]
	v_mfma_f32_16x16x32_bf16 v[38:41], v[138:141], v[170:173], v[38:41]
	v_mfma_f32_16x16x32_bf16 v[34:37], v[146:149], v[170:173], v[34:37]
	v_mfma_f32_16x16x32_bf16 v[22:25], v[138:141], v[178:181], v[22:25]
	v_mfma_f32_16x16x32_bf16 v[18:21], v[146:149], v[178:181], v[18:21]
	v_mfma_f32_16x16x32_bf16 v[6:9], v[138:141], v[186:189], v[6:9]
	v_mfma_f32_16x16x32_bf16 v[2:5], v[146:149], v[186:189], v[2:5]
	v_mfma_f32_16x16x32_bf16 v[54:57], v[142:145], v[166:169], v[54:57]
	v_mfma_f32_16x16x32_bf16 v[50:53], v[154:157], v[166:169], v[50:53]
	v_mfma_f32_16x16x32_bf16 v[38:41], v[142:145], v[174:177], v[38:41]
	v_mfma_f32_16x16x32_bf16 v[34:37], v[154:157], v[174:177], v[34:37]
	v_mfma_f32_16x16x32_bf16 v[22:25], v[142:145], v[182:185], v[22:25]
	v_mfma_f32_16x16x32_bf16 v[18:21], v[154:157], v[182:185], v[18:21]
	v_mfma_f32_16x16x32_bf16 v[6:9], v[142:145], v[210:213], v[6:9]
	v_mfma_f32_16x16x32_bf16 v[2:5], v[154:157], v[210:213], v[2:5]
	s_barrier
	s_add_i32 s55, 0, 0x18000
	s_add_i32 s56, 0, 0x1c000
	v_add_u32_e32 v134, s55, v1
	v_add_u32_e32 v154, s56, v1
	ds_read_b128 v[110:113], v134
	ds_read_b128 v[118:121], v134 offset:1024
	ds_read_b128 v[122:125], v134 offset:2048
	ds_read_b128 v[134:137], v134 offset:3072
	ds_read_b128 v[138:141], v154
	ds_read_b128 v[142:145], v154 offset:1024
	ds_read_b128 v[146:149], v154 offset:2048
	ds_read_b128 v[154:157], v154 offset:3072
	s_add_u32 s30, s30, 0x40000
	s_addc_u32 s31, s31, 0
	s_mov_b32 m0, s42
	v_lshl_add_u64 v[222:223], s[30:31], 0, v[190:191]
	ds_read_b128 v[162:165], v214 offset:32768
	ds_read_b128 v[166:169], v214 offset:33792
	ds_read_b128 v[170:173], v214 offset:34816
	ds_read_b128 v[174:177], v214 offset:35840
	ds_read_b128 v[178:181], v214 offset:36864
	ds_read_b128 v[182:185], v214 offset:37888
	ds_read_b128 v[186:189], v214 offset:38912
	ds_read_b128 v[210:213], v214 offset:39936
	global_load_lds_dwordx4 v[222:223], off
	v_lshl_add_u64 v[222:223], s[30:31], 0, v[194:195]
	s_mov_b32 m0, s43
	s_nop 0
	global_load_lds_dwordx4 v[222:223], off
	s_waitcnt vmcnt(8)
	s_waitcnt lgkmcnt(0)
	s_barrier
	s_waitcnt lgkmcnt(0)
	v_mfma_f32_16x16x32_bf16 v[158:161], v[110:113], v[162:165], v[158:161]
	v_mfma_f32_16x16x32_bf16 v[150:153], v[122:125], v[162:165], v[150:153]
	v_mfma_f32_16x16x32_bf16 v[114:117], v[110:113], v[170:173], v[114:117]
	v_mfma_f32_16x16x32_bf16 v[106:109], v[122:125], v[170:173], v[106:109]
	v_mfma_f32_16x16x32_bf16 v[94:97], v[110:113], v[178:181], v[94:97]
	v_mfma_f32_16x16x32_bf16 v[90:93], v[122:125], v[178:181], v[90:93]
	v_mfma_f32_16x16x32_bf16 v[78:81], v[110:113], v[186:189], v[78:81]
	v_mfma_f32_16x16x32_bf16 v[74:77], v[122:125], v[186:189], v[74:77]
	v_mfma_f32_16x16x32_bf16 v[158:161], v[118:121], v[166:169], v[158:161]
	v_mfma_f32_16x16x32_bf16 v[150:153], v[134:137], v[166:169], v[150:153]
	v_mfma_f32_16x16x32_bf16 v[114:117], v[118:121], v[174:177], v[114:117]
	v_mfma_f32_16x16x32_bf16 v[106:109], v[134:137], v[174:177], v[106:109]
	v_mfma_f32_16x16x32_bf16 v[94:97], v[118:121], v[182:185], v[94:97]
	v_mfma_f32_16x16x32_bf16 v[90:93], v[134:137], v[182:185], v[90:93]
	v_mfma_f32_16x16x32_bf16 v[78:81], v[118:121], v[210:213], v[78:81]
	v_mfma_f32_16x16x32_bf16 v[74:77], v[134:137], v[210:213], v[74:77]
	v_mfma_f32_16x16x32_bf16 v[130:133], v[138:141], v[162:165], v[130:133]
	v_mfma_f32_16x16x32_bf16 v[126:129], v[146:149], v[162:165], v[126:129]
	v_mfma_f32_16x16x32_bf16 v[102:105], v[138:141], v[170:173], v[102:105]
	v_mfma_f32_16x16x32_bf16 v[98:101], v[146:149], v[170:173], v[98:101]
	v_mfma_f32_16x16x32_bf16 v[86:89], v[138:141], v[178:181], v[86:89]
	v_mfma_f32_16x16x32_bf16 v[82:85], v[146:149], v[178:181], v[82:85]
	v_mfma_f32_16x16x32_bf16 v[70:73], v[138:141], v[186:189], v[70:73]
	v_mfma_f32_16x16x32_bf16 v[66:69], v[146:149], v[186:189], v[66:69]
	v_mfma_f32_16x16x32_bf16 v[130:133], v[142:145], v[166:169], v[130:133]
	v_mfma_f32_16x16x32_bf16 v[126:129], v[154:157], v[166:169], v[126:129]
	v_mfma_f32_16x16x32_bf16 v[102:105], v[142:145], v[174:177], v[102:105]
	v_mfma_f32_16x16x32_bf16 v[98:101], v[154:157], v[174:177], v[98:101]
	v_mfma_f32_16x16x32_bf16 v[86:89], v[142:145], v[182:185], v[86:89]
	v_mfma_f32_16x16x32_bf16 v[82:85], v[154:157], v[182:185], v[82:85]
	v_mfma_f32_16x16x32_bf16 v[70:73], v[142:145], v[210:213], v[70:73]
	v_mfma_f32_16x16x32_bf16 v[66:69], v[154:157], v[210:213], v[66:69]
	s_barrier
	s_add_i32 s30, s55, s40
	v_lshl_add_u64 v[196:197], v[196:197], 0, s[94:95]
	s_mov_b32 m0, s30
	ds_read_b128 v[162:165], v214 offset:49152
	ds_read_b128 v[166:169], v214 offset:50176
	ds_read_b128 v[170:173], v214 offset:51200
	ds_read_b128 v[174:177], v214 offset:52224
	ds_read_b128 v[178:181], v214 offset:53248
	ds_read_b128 v[182:185], v214 offset:54272
	ds_read_b128 v[186:189], v214 offset:55296
	ds_read_b128 v[210:213], v214 offset:56320
	global_load_lds_dwordx4 v[196:197], off
	s_add_i32 m0, s30, 0x2000
	s_add_u32 s28, s28, 0x40080
	v_lshl_add_u64 v[196:197], v[198:199], 0, s[94:95]
	s_addc_u32 s29, s29, 0
	s_add_i32 s30, s56, s40
	global_load_lds_dwordx4 v[196:197], off
	v_lshl_add_u64 v[196:197], s[28:29], 0, v[192:193]
	s_mov_b32 m0, s30
	s_nop 0
	global_load_lds_dwordx4 v[196:197], off
	v_lshl_add_u64 v[196:197], s[28:29], 0, v[204:205]
	s_add_i32 m0, s30, 0x2000
	s_nop 0
	global_load_lds_dwordx4 v[196:197], off
	v_lshl_add_u64 v[196:197], v[216:217], 0, s[94:95]
	s_mov_b32 m0, s46
	s_nop 0
	global_load_lds_dwordx4 v[196:197], off
	v_lshl_add_u64 v[196:197], v[220:221], 0, s[94:95]
	s_mov_b32 m0, s47
	s_nop 0
	global_load_lds_dwordx4 v[196:197], off
	s_waitcnt vmcnt(8)
	s_waitcnt lgkmcnt(0)
	s_barrier
	s_waitcnt lgkmcnt(0)
	v_mfma_f32_16x16x32_bf16 v[62:65], v[110:113], v[162:165], v[62:65]
	v_mfma_f32_16x16x32_bf16 v[58:61], v[122:125], v[162:165], v[58:61]
	v_mfma_f32_16x16x32_bf16 v[46:49], v[110:113], v[170:173], v[46:49]
	v_mfma_f32_16x16x32_bf16 v[42:45], v[122:125], v[170:173], v[42:45]
	v_mfma_f32_16x16x32_bf16 v[30:33], v[110:113], v[178:181], v[30:33]
	v_mfma_f32_16x16x32_bf16 v[26:29], v[122:125], v[178:181], v[26:29]
	v_mfma_f32_16x16x32_bf16 v[14:17], v[110:113], v[186:189], v[14:17]
	v_mfma_f32_16x16x32_bf16 v[10:13], v[122:125], v[186:189], v[10:13]
	v_mfma_f32_16x16x32_bf16 v[62:65], v[118:121], v[166:169], v[62:65]
	v_mfma_f32_16x16x32_bf16 v[58:61], v[134:137], v[166:169], v[58:61]
	v_mfma_f32_16x16x32_bf16 v[46:49], v[118:121], v[174:177], v[46:49]
	v_mfma_f32_16x16x32_bf16 v[42:45], v[134:137], v[174:177], v[42:45]
	v_mfma_f32_16x16x32_bf16 v[30:33], v[118:121], v[182:185], v[30:33]
	v_mfma_f32_16x16x32_bf16 v[26:29], v[134:137], v[182:185], v[26:29]
	v_mfma_f32_16x16x32_bf16 v[14:17], v[118:121], v[210:213], v[14:17]
	v_mfma_f32_16x16x32_bf16 v[10:13], v[134:137], v[210:213], v[10:13]
	v_mfma_f32_16x16x32_bf16 v[54:57], v[138:141], v[162:165], v[54:57]
	v_mfma_f32_16x16x32_bf16 v[50:53], v[146:149], v[162:165], v[50:53]
	v_mfma_f32_16x16x32_bf16 v[38:41], v[138:141], v[170:173], v[38:41]
	v_mfma_f32_16x16x32_bf16 v[34:37], v[146:149], v[170:173], v[34:37]
	v_mfma_f32_16x16x32_bf16 v[22:25], v[138:141], v[178:181], v[22:25]
	v_mfma_f32_16x16x32_bf16 v[18:21], v[146:149], v[178:181], v[18:21]
	v_mfma_f32_16x16x32_bf16 v[6:9], v[138:141], v[186:189], v[6:9]
	v_mfma_f32_16x16x32_bf16 v[2:5], v[146:149], v[186:189], v[2:5]
	v_mfma_f32_16x16x32_bf16 v[54:57], v[142:145], v[166:169], v[54:57]
	v_mfma_f32_16x16x32_bf16 v[50:53], v[154:157], v[166:169], v[50:53]
	v_mfma_f32_16x16x32_bf16 v[38:41], v[142:145], v[174:177], v[38:41]
	v_mfma_f32_16x16x32_bf16 v[34:37], v[154:157], v[174:177], v[34:37]
	v_mfma_f32_16x16x32_bf16 v[22:25], v[142:145], v[182:185], v[22:25]
	v_mfma_f32_16x16x32_bf16 v[18:21], v[154:157], v[182:185], v[18:21]
	v_mfma_f32_16x16x32_bf16 v[6:9], v[142:145], v[210:213], v[6:9]
	v_mfma_f32_16x16x32_bf16 v[2:5], v[154:157], v[210:213], v[2:5]
	s_barrier
	s_add_i32 s54, s54, 2
	s_add_u32 s26, s26, 0x100
	s_addc_u32 s27, s27, 0
	s_add_u32 s52, s52, 0x100
	s_addc_u32 s53, s53, 0
	s_cmp_gt_u32 s54, 13
	s_cbranch_scc0 .LBB0_890
	s_and_b64 vcc, exec, s[12:13]
	s_cbranch_vccz .LBB0_893
	s_barrier

.LBB0_984:
	s_add_u32 s28, s4, 0xfffc0080
	s_addc_u32 s29, s5, -1
	s_add_i32 s58, 0, 0x10000
	s_cmp_eq_u32 s57, 12
	s_cselect_b32 s31, s19, s29
	s_cselect_b32 s30, s53, s28
	s_cselect_b32 s29, s17, s56
	s_cselect_b32 s28, s54, s55
	s_add_i32 s60, 0, 0x14000
	v_add_u32_e32 v154, s58, v1
	v_add_u32_e32 v170, s60, v1
	ds_read_b128 v[142:145], v154
	ds_read_b128 v[146:149], v154 offset:1024
	ds_read_b128 v[150:153], v154 offset:2048
	ds_read_b128 v[154:157], v154 offset:3072
	ds_read_b128 v[158:161], v170
	ds_read_b128 v[162:165], v170 offset:1024
	ds_read_b128 v[166:169], v170 offset:2048
	ds_read_b128 v[170:173], v170 offset:3072
	v_lshl_add_u64 v[196:197], s[4:5], 0, v[138:139]
	s_add_i32 m0, s25, 0xc000
	ds_read_b128 v[174:177], v190
	ds_read_b128 v[178:181], v190 offset:1024
	ds_read_b128 v[182:185], v190 offset:2048
	ds_read_b128 v[186:189], v190 offset:3072
	ds_read_b128 v[192:195], v190 offset:4096
	ds_read_b128 v[204:207], v190 offset:5120
	ds_read_b128 v[208:211], v190 offset:6144
	ds_read_b128 v[212:215], v190 offset:7168
	global_load_lds_dwordx4 v[196:197], off
	v_lshl_add_u64 v[196:197], s[4:5], 0, v[140:141]
	s_add_i32 m0, s25, 0xe000
	s_nop 0
	global_load_lds_dwordx4 v[196:197], off
	s_waitcnt vmcnt(8)
	s_waitcnt lgkmcnt(0)
	s_barrier
	s_waitcnt lgkmcnt(0)
	v_mfma_f32_16x16x32_bf16 v[126:129], v[142:145], v[174:177], v[126:129]
	v_mfma_f32_16x16x32_bf16 v[122:125], v[150:153], v[174:177], v[122:125]
	v_mfma_f32_16x16x32_bf16 v[110:113], v[142:145], v[182:185], v[110:113]
	v_mfma_f32_16x16x32_bf16 v[106:109], v[150:153], v[182:185], v[106:109]
	v_mfma_f32_16x16x32_bf16 v[94:97], v[142:145], v[192:195], v[94:97]
	v_mfma_f32_16x16x32_bf16 v[90:93], v[150:153], v[192:195], v[90:93]
	v_mfma_f32_16x16x32_bf16 v[78:81], v[142:145], v[208:211], v[78:81]
	v_mfma_f32_16x16x32_bf16 v[74:77], v[150:153], v[208:211], v[74:77]
	v_mfma_f32_16x16x32_bf16 v[126:129], v[146:149], v[178:181], v[126:129]
	v_mfma_f32_16x16x32_bf16 v[122:125], v[154:157], v[178:181], v[122:125]
	v_mfma_f32_16x16x32_bf16 v[110:113], v[146:149], v[186:189], v[110:113]
	v_mfma_f32_16x16x32_bf16 v[106:109], v[154:157], v[186:189], v[106:109]
	v_mfma_f32_16x16x32_bf16 v[94:97], v[146:149], v[204:207], v[94:97]
	v_mfma_f32_16x16x32_bf16 v[90:93], v[154:157], v[204:207], v[90:93]
	v_mfma_f32_16x16x32_bf16 v[78:81], v[146:149], v[212:215], v[78:81]
	v_mfma_f32_16x16x32_bf16 v[74:77], v[154:157], v[212:215], v[74:77]
	v_mfma_f32_16x16x32_bf16 v[118:121], v[158:161], v[174:177], v[118:121]
	v_mfma_f32_16x16x32_bf16 v[114:117], v[166:169], v[174:177], v[114:117]
	v_mfma_f32_16x16x32_bf16 v[102:105], v[158:161], v[182:185], v[102:105]
	v_mfma_f32_16x16x32_bf16 v[98:101], v[166:169], v[182:185], v[98:101]
	v_mfma_f32_16x16x32_bf16 v[86:89], v[158:161], v[192:195], v[86:89]
	v_mfma_f32_16x16x32_bf16 v[82:85], v[166:169], v[192:195], v[82:85]
	v_mfma_f32_16x16x32_bf16 v[70:73], v[158:161], v[208:211], v[70:73]
	v_mfma_f32_16x16x32_bf16 v[66:69], v[166:169], v[208:211], v[66:69]
	v_mfma_f32_16x16x32_bf16 v[118:121], v[162:165], v[178:181], v[118:121]
	v_mfma_f32_16x16x32_bf16 v[114:117], v[170:173], v[178:181], v[114:117]
	v_mfma_f32_16x16x32_bf16 v[102:105], v[162:165], v[186:189], v[102:105]
	v_mfma_f32_16x16x32_bf16 v[98:101], v[170:173], v[186:189], v[98:101]
	v_mfma_f32_16x16x32_bf16 v[86:89], v[162:165], v[204:207], v[86:89]
	v_mfma_f32_16x16x32_bf16 v[82:85], v[170:173], v[204:207], v[82:85]
	v_mfma_f32_16x16x32_bf16 v[70:73], v[162:165], v[212:215], v[70:73]
	v_mfma_f32_16x16x32_bf16 v[66:69], v[170:173], v[212:215], v[66:69]
	s_barrier
	s_add_i32 s58, s58, s40
	v_lshl_add_u64 v[196:197], s[28:29], 0, v[132:133]
	s_mov_b32 m0, s58
	ds_read_b128 v[174:177], v190 offset:16384
	ds_read_b128 v[178:181], v190 offset:17408
	ds_read_b128 v[182:185], v190 offset:18432
	ds_read_b128 v[186:189], v190 offset:19456
	ds_read_b128 v[192:195], v190 offset:20480
	ds_read_b128 v[204:207], v190 offset:21504
	ds_read_b128 v[208:211], v190 offset:22528
	ds_read_b128 v[212:215], v190 offset:23552
	global_load_lds_dwordx4 v[196:197], off
	s_add_i32 m0, s58, 0x2000
	s_add_u32 s58, s28, 0x40000
	v_lshl_add_u64 v[198:199], s[28:29], 0, v[136:137]
	s_addc_u32 s59, s29, 0
	s_add_i32 s60, s60, s40
	global_load_lds_dwordx4 v[198:199], off
	v_lshl_add_u64 v[216:217], s[58:59], 0, v[132:133]
	s_mov_b32 m0, s60
	v_lshl_add_u64 v[220:221], s[30:31], 0, v[134:135]
	global_load_lds_dwordx4 v[216:217], off
	v_lshl_add_u64 v[216:217], s[58:59], 0, v[136:137]
	s_add_i32 m0, s60, 0x2000
	s_nop 0
	global_load_lds_dwordx4 v[216:217], off
	v_lshl_add_u64 v[216:217], s[30:31], 0, v[130:131]
	s_mov_b32 m0, s25
	s_nop 0
	global_load_lds_dwordx4 v[216:217], off
	s_mov_b32 m0, s27
	s_nop 0
	global_load_lds_dwordx4 v[220:221], off
	s_waitcnt vmcnt(8)
	s_waitcnt lgkmcnt(0)
	s_barrier
	s_waitcnt lgkmcnt(0)
	v_mfma_f32_16x16x32_bf16 v[62:65], v[142:145], v[174:177], v[62:65]
	v_mfma_f32_16x16x32_bf16 v[58:61], v[150:153], v[174:177], v[58:61]
	v_mfma_f32_16x16x32_bf16 v[46:49], v[142:145], v[182:185], v[46:49]
	v_mfma_f32_16x16x32_bf16 v[42:45], v[150:153], v[182:185], v[42:45]
	v_mfma_f32_16x16x32_bf16 v[30:33], v[142:145], v[192:195], v[30:33]
	v_mfma_f32_16x16x32_bf16 v[26:29], v[150:153], v[192:195], v[26:29]
	v_mfma_f32_16x16x32_bf16 v[14:17], v[142:145], v[208:211], v[14:17]
	v_mfma_f32_16x16x32_bf16 v[10:13], v[150:153], v[208:211], v[10:13]
	v_mfma_f32_16x16x32_bf16 v[62:65], v[146:149], v[178:181], v[62:65]
	v_mfma_f32_16x16x32_bf16 v[58:61], v[154:157], v[178:181], v[58:61]
	v_mfma_f32_16x16x32_bf16 v[46:49], v[146:149], v[186:189], v[46:49]
	v_mfma_f32_16x16x32_bf16 v[42:45], v[154:157], v[186:189], v[42:45]
	v_mfma_f32_16x16x32_bf16 v[30:33], v[146:149], v[204:207], v[30:33]
	v_mfma_f32_16x16x32_bf16 v[26:29], v[154:157], v[204:207], v[26:29]
	v_mfma_f32_16x16x32_bf16 v[14:17], v[146:149], v[212:215], v[14:17]
	v_mfma_f32_16x16x32_bf16 v[10:13], v[154:157], v[212:215], v[10:13]
	v_mfma_f32_16x16x32_bf16 v[54:57], v[158:161], v[174:177], v[54:57]
	v_mfma_f32_16x16x32_bf16 v[50:53], v[166:169], v[174:177], v[50:53]
	v_mfma_f32_16x16x32_bf16 v[38:41], v[158:161], v[182:185], v[38:41]
	v_mfma_f32_16x16x32_bf16 v[34:37], v[166:169], v[182:185], v[34:37]
	v_mfma_f32_16x16x32_bf16 v[22:25], v[158:161], v[192:195], v[22:25]
	v_mfma_f32_16x16x32_bf16 v[18:21], v[166:169], v[192:195], v[18:21]
	v_mfma_f32_16x16x32_bf16 v[6:9], v[158:161], v[208:211], v[6:9]
	v_mfma_f32_16x16x32_bf16 v[2:5], v[166:169], v[208:211], v[2:5]
	v_mfma_f32_16x16x32_bf16 v[54:57], v[162:165], v[178:181], v[54:57]
	v_mfma_f32_16x16x32_bf16 v[50:53], v[170:173], v[178:181], v[50:53]
	v_mfma_f32_16x16x32_bf16 v[38:41], v[162:165], v[186:189], v[38:41]
	v_mfma_f32_16x16x32_bf16 v[34:37], v[170:173], v[186:189], v[34:37]
	v_mfma_f32_16x16x32_bf16 v[22:25], v[162:165], v[204:207], v[22:25]
	v_mfma_f32_16x16x32_bf16 v[18:21], v[170:173], v[204:207], v[18:21]
	v_mfma_f32_16x16x32_bf16 v[6:9], v[162:165], v[212:215], v[6:9]
	v_mfma_f32_16x16x32_bf16 v[2:5], v[170:173], v[212:215], v[2:5]
	s_barrier
	s_add_i32 s58, 0, 0x18000
	s_add_i32 s59, 0, 0x1c000
	v_add_u32_e32 v154, s58, v1
	v_add_u32_e32 v170, s59, v1
	ds_read_b128 v[142:145], v154
	ds_read_b128 v[146:149], v154 offset:1024
	ds_read_b128 v[150:153], v154 offset:2048
	ds_read_b128 v[154:157], v154 offset:3072
	ds_read_b128 v[158:161], v170
	ds_read_b128 v[162:165], v170 offset:1024
	ds_read_b128 v[166:169], v170 offset:2048
	ds_read_b128 v[170:173], v170 offset:3072
	s_add_u32 s30, s30, 0x40000
	s_addc_u32 s31, s31, 0
	s_mov_b32 m0, s41
	v_lshl_add_u64 v[222:223], s[30:31], 0, v[130:131]
	ds_read_b128 v[174:177], v190 offset:32768
	ds_read_b128 v[178:181], v190 offset:33792
	ds_read_b128 v[182:185], v190 offset:34816
	ds_read_b128 v[186:189], v190 offset:35840
	ds_read_b128 v[192:195], v190 offset:36864
	ds_read_b128 v[204:207], v190 offset:37888
	ds_read_b128 v[208:211], v190 offset:38912
	ds_read_b128 v[212:215], v190 offset:39936
	global_load_lds_dwordx4 v[222:223], off
	v_lshl_add_u64 v[222:223], s[30:31], 0, v[134:135]
	s_mov_b32 m0, s42
	s_nop 0
	global_load_lds_dwordx4 v[222:223], off
	s_waitcnt vmcnt(8)
	s_waitcnt lgkmcnt(0)
	s_barrier
	s_waitcnt lgkmcnt(0)
	v_mfma_f32_16x16x32_bf16 v[126:129], v[142:145], v[174:177], v[126:129]
	v_mfma_f32_16x16x32_bf16 v[122:125], v[150:153], v[174:177], v[122:125]
	v_mfma_f32_16x16x32_bf16 v[110:113], v[142:145], v[182:185], v[110:113]
	v_mfma_f32_16x16x32_bf16 v[106:109], v[150:153], v[182:185], v[106:109]
	v_mfma_f32_16x16x32_bf16 v[94:97], v[142:145], v[192:195], v[94:97]
	v_mfma_f32_16x16x32_bf16 v[90:93], v[150:153], v[192:195], v[90:93]
	v_mfma_f32_16x16x32_bf16 v[78:81], v[142:145], v[208:211], v[78:81]
	v_mfma_f32_16x16x32_bf16 v[74:77], v[150:153], v[208:211], v[74:77]
	v_mfma_f32_16x16x32_bf16 v[126:129], v[146:149], v[178:181], v[126:129]
	v_mfma_f32_16x16x32_bf16 v[122:125], v[154:157], v[178:181], v[122:125]
	v_mfma_f32_16x16x32_bf16 v[110:113], v[146:149], v[186:189], v[110:113]
	v_mfma_f32_16x16x32_bf16 v[106:109], v[154:157], v[186:189], v[106:109]
	v_mfma_f32_16x16x32_bf16 v[94:97], v[146:149], v[204:207], v[94:97]
	v_mfma_f32_16x16x32_bf16 v[90:93], v[154:157], v[204:207], v[90:93]
	v_mfma_f32_16x16x32_bf16 v[78:81], v[146:149], v[212:215], v[78:81]
	v_mfma_f32_16x16x32_bf16 v[74:77], v[154:157], v[212:215], v[74:77]
	v_mfma_f32_16x16x32_bf16 v[118:121], v[158:161], v[174:177], v[118:121]
	v_mfma_f32_16x16x32_bf16 v[114:117], v[166:169], v[174:177], v[114:117]
	v_mfma_f32_16x16x32_bf16 v[102:105], v[158:161], v[182:185], v[102:105]
	v_mfma_f32_16x16x32_bf16 v[98:101], v[166:169], v[182:185], v[98:101]
	v_mfma_f32_16x16x32_bf16 v[86:89], v[158:161], v[192:195], v[86:89]
	v_mfma_f32_16x16x32_bf16 v[82:85], v[166:169], v[192:195], v[82:85]
	v_mfma_f32_16x16x32_bf16 v[70:73], v[158:161], v[208:211], v[70:73]
	v_mfma_f32_16x16x32_bf16 v[66:69], v[166:169], v[208:211], v[66:69]
	v_mfma_f32_16x16x32_bf16 v[118:121], v[162:165], v[178:181], v[118:121]
	v_mfma_f32_16x16x32_bf16 v[114:117], v[170:173], v[178:181], v[114:117]
	v_mfma_f32_16x16x32_bf16 v[102:105], v[162:165], v[186:189], v[102:105]
	v_mfma_f32_16x16x32_bf16 v[98:101], v[170:173], v[186:189], v[98:101]
	v_mfma_f32_16x16x32_bf16 v[86:89], v[162:165], v[204:207], v[86:89]
	v_mfma_f32_16x16x32_bf16 v[82:85], v[170:173], v[204:207], v[82:85]
	v_mfma_f32_16x16x32_bf16 v[70:73], v[162:165], v[212:215], v[70:73]
	v_mfma_f32_16x16x32_bf16 v[66:69], v[170:173], v[212:215], v[66:69]
	s_barrier
	s_add_i32 s30, s58, s40
	v_lshl_add_u64 v[196:197], v[196:197], 0, s[94:95]
	s_mov_b32 m0, s30
	ds_read_b128 v[174:177], v190 offset:49152
	ds_read_b128 v[178:181], v190 offset:50176
	ds_read_b128 v[182:185], v190 offset:51200
	ds_read_b128 v[186:189], v190 offset:52224
	ds_read_b128 v[192:195], v190 offset:53248
	ds_read_b128 v[204:207], v190 offset:54272
	ds_read_b128 v[208:211], v190 offset:55296
	ds_read_b128 v[212:215], v190 offset:56320
	global_load_lds_dwordx4 v[196:197], off
	s_add_i32 m0, s30, 0x2000
	s_add_u32 s28, s28, 0x40080
	v_lshl_add_u64 v[196:197], v[198:199], 0, s[94:95]
	s_addc_u32 s29, s29, 0
	s_add_i32 s30, s59, s40
	global_load_lds_dwordx4 v[196:197], off
	v_lshl_add_u64 v[196:197], s[28:29], 0, v[132:133]
	s_mov_b32 m0, s30
	s_nop 0
	global_load_lds_dwordx4 v[196:197], off
	v_lshl_add_u64 v[196:197], s[28:29], 0, v[136:137]
	s_add_i32 m0, s30, 0x2000
	s_nop 0
	global_load_lds_dwordx4 v[196:197], off
	v_lshl_add_u64 v[196:197], v[216:217], 0, s[94:95]
	s_mov_b32 m0, s45
	s_nop 0
	global_load_lds_dwordx4 v[196:197], off
	v_lshl_add_u64 v[196:197], v[220:221], 0, s[94:95]
	s_mov_b32 m0, s46
	s_nop 0
	global_load_lds_dwordx4 v[196:197], off
	s_waitcnt vmcnt(8)
	s_waitcnt lgkmcnt(0)
	s_barrier
	s_waitcnt lgkmcnt(0)
	v_mfma_f32_16x16x32_bf16 v[62:65], v[142:145], v[174:177], v[62:65]
	v_mfma_f32_16x16x32_bf16 v[58:61], v[150:153], v[174:177], v[58:61]
	v_mfma_f32_16x16x32_bf16 v[46:49], v[142:145], v[182:185], v[46:49]
	v_mfma_f32_16x16x32_bf16 v[42:45], v[150:153], v[182:185], v[42:45]
	v_mfma_f32_16x16x32_bf16 v[30:33], v[142:145], v[192:195], v[30:33]
	v_mfma_f32_16x16x32_bf16 v[26:29], v[150:153], v[192:195], v[26:29]
	v_mfma_f32_16x16x32_bf16 v[14:17], v[142:145], v[208:211], v[14:17]
	v_mfma_f32_16x16x32_bf16 v[10:13], v[150:153], v[208:211], v[10:13]
	v_mfma_f32_16x16x32_bf16 v[62:65], v[146:149], v[178:181], v[62:65]
	v_mfma_f32_16x16x32_bf16 v[58:61], v[154:157], v[178:181], v[58:61]
	v_mfma_f32_16x16x32_bf16 v[46:49], v[146:149], v[186:189], v[46:49]
	v_mfma_f32_16x16x32_bf16 v[42:45], v[154:157], v[186:189], v[42:45]
	v_mfma_f32_16x16x32_bf16 v[30:33], v[146:149], v[204:207], v[30:33]
	v_mfma_f32_16x16x32_bf16 v[26:29], v[154:157], v[204:207], v[26:29]
	v_mfma_f32_16x16x32_bf16 v[14:17], v[146:149], v[212:215], v[14:17]
	v_mfma_f32_16x16x32_bf16 v[10:13], v[154:157], v[212:215], v[10:13]
	v_mfma_f32_16x16x32_bf16 v[54:57], v[158:161], v[174:177], v[54:57]
	v_mfma_f32_16x16x32_bf16 v[50:53], v[166:169], v[174:177], v[50:53]
	v_mfma_f32_16x16x32_bf16 v[38:41], v[158:161], v[182:185], v[38:41]
	v_mfma_f32_16x16x32_bf16 v[34:37], v[166:169], v[182:185], v[34:37]
	v_mfma_f32_16x16x32_bf16 v[22:25], v[158:161], v[192:195], v[22:25]
	v_mfma_f32_16x16x32_bf16 v[18:21], v[166:169], v[192:195], v[18:21]
	v_mfma_f32_16x16x32_bf16 v[6:9], v[158:161], v[208:211], v[6:9]
	v_mfma_f32_16x16x32_bf16 v[2:5], v[166:169], v[208:211], v[2:5]
	v_mfma_f32_16x16x32_bf16 v[54:57], v[162:165], v[178:181], v[54:57]
	v_mfma_f32_16x16x32_bf16 v[50:53], v[170:173], v[178:181], v[50:53]
	v_mfma_f32_16x16x32_bf16 v[38:41], v[162:165], v[186:189], v[38:41]
	v_mfma_f32_16x16x32_bf16 v[34:37], v[170:173], v[186:189], v[34:37]
	v_mfma_f32_16x16x32_bf16 v[22:25], v[162:165], v[204:207], v[22:25]
	v_mfma_f32_16x16x32_bf16 v[18:21], v[170:173], v[204:207], v[18:21]
	v_mfma_f32_16x16x32_bf16 v[6:9], v[162:165], v[212:215], v[6:9]
	v_mfma_f32_16x16x32_bf16 v[2:5], v[170:173], v[212:215], v[2:5]
	s_barrier
	s_add_i32 s57, s57, 2
	s_add_u32 s4, s4, 0x100
	s_addc_u32 s5, s5, 0
	s_add_u32 s55, s55, 0x100
	s_addc_u32 s56, s56, 0
	s_cmp_gt_u32 s57, 13
	s_cbranch_scc0 .LBB0_984
	s_and_b64 vcc, exec, s[14:15]
	s_cbranch_vccz .LBB0_987
	s_barrier

.LBB0_1096:
	s_add_u32 s28, s4, 0xfffc0080
	s_addc_u32 s29, s5, -1
	s_add_i32 s53, 0, 0x10000
	s_cmp_eq_u32 s52, 12
	s_cselect_b32 s31, s17, s29
	s_cselect_b32 s30, s19, s28
	s_cselect_b32 s29, s21, s51
	s_cselect_b32 s28, s20, s50
	s_add_i32 s56, 0, 0x14000
	v_add_u32_e32 v134, s53, v1
	v_add_u32_e32 v154, s56, v1
	ds_read_b128 v[110:113], v134
	ds_read_b128 v[118:121], v134 offset:1024
	ds_read_b128 v[122:125], v134 offset:2048
	ds_read_b128 v[134:137], v134 offset:3072
	ds_read_b128 v[138:141], v154
	ds_read_b128 v[142:145], v154 offset:1024
	ds_read_b128 v[146:149], v154 offset:2048
	ds_read_b128 v[154:157], v154 offset:3072
	v_lshl_add_u64 v[196:197], s[4:5], 0, v[206:207]
	s_add_i32 m0, s25, 0xc000
	ds_read_b128 v[162:165], v214
	ds_read_b128 v[166:169], v214 offset:1024
	ds_read_b128 v[170:173], v214 offset:2048
	ds_read_b128 v[174:177], v214 offset:3072
	ds_read_b128 v[178:181], v214 offset:4096
	ds_read_b128 v[182:185], v214 offset:5120
	ds_read_b128 v[186:189], v214 offset:6144
	ds_read_b128 v[210:213], v214 offset:7168
	global_load_lds_dwordx4 v[196:197], off
	v_lshl_add_u64 v[196:197], s[4:5], 0, v[208:209]
	s_add_i32 m0, s25, 0xe000
	s_nop 0
	global_load_lds_dwordx4 v[196:197], off
	s_waitcnt vmcnt(8)
	s_waitcnt lgkmcnt(0)
	s_barrier
	s_waitcnt lgkmcnt(0)
	v_mfma_f32_16x16x32_bf16 v[158:161], v[110:113], v[162:165], v[158:161]
	v_mfma_f32_16x16x32_bf16 v[150:153], v[122:125], v[162:165], v[150:153]
	v_mfma_f32_16x16x32_bf16 v[114:117], v[110:113], v[170:173], v[114:117]
	v_mfma_f32_16x16x32_bf16 v[106:109], v[122:125], v[170:173], v[106:109]
	v_mfma_f32_16x16x32_bf16 v[94:97], v[110:113], v[178:181], v[94:97]
	v_mfma_f32_16x16x32_bf16 v[90:93], v[122:125], v[178:181], v[90:93]
	v_mfma_f32_16x16x32_bf16 v[78:81], v[110:113], v[186:189], v[78:81]
	v_mfma_f32_16x16x32_bf16 v[74:77], v[122:125], v[186:189], v[74:77]
	v_mfma_f32_16x16x32_bf16 v[158:161], v[118:121], v[166:169], v[158:161]
	v_mfma_f32_16x16x32_bf16 v[150:153], v[134:137], v[166:169], v[150:153]
	v_mfma_f32_16x16x32_bf16 v[114:117], v[118:121], v[174:177], v[114:117]
	v_mfma_f32_16x16x32_bf16 v[106:109], v[134:137], v[174:177], v[106:109]
	v_mfma_f32_16x16x32_bf16 v[94:97], v[118:121], v[182:185], v[94:97]
	v_mfma_f32_16x16x32_bf16 v[90:93], v[134:137], v[182:185], v[90:93]
	v_mfma_f32_16x16x32_bf16 v[78:81], v[118:121], v[210:213], v[78:81]
	v_mfma_f32_16x16x32_bf16 v[74:77], v[134:137], v[210:213], v[74:77]
	v_mfma_f32_16x16x32_bf16 v[130:133], v[138:141], v[162:165], v[130:133]
	v_mfma_f32_16x16x32_bf16 v[126:129], v[146:149], v[162:165], v[126:129]
	v_mfma_f32_16x16x32_bf16 v[102:105], v[138:141], v[170:173], v[102:105]
	v_mfma_f32_16x16x32_bf16 v[98:101], v[146:149], v[170:173], v[98:101]
	v_mfma_f32_16x16x32_bf16 v[86:89], v[138:141], v[178:181], v[86:89]
	v_mfma_f32_16x16x32_bf16 v[82:85], v[146:149], v[178:181], v[82:85]
	v_mfma_f32_16x16x32_bf16 v[70:73], v[138:141], v[186:189], v[70:73]
	v_mfma_f32_16x16x32_bf16 v[66:69], v[146:149], v[186:189], v[66:69]
	v_mfma_f32_16x16x32_bf16 v[130:133], v[142:145], v[166:169], v[130:133]
	v_mfma_f32_16x16x32_bf16 v[126:129], v[154:157], v[166:169], v[126:129]
	v_mfma_f32_16x16x32_bf16 v[102:105], v[142:145], v[174:177], v[102:105]
	v_mfma_f32_16x16x32_bf16 v[98:101], v[154:157], v[174:177], v[98:101]
	v_mfma_f32_16x16x32_bf16 v[86:89], v[142:145], v[182:185], v[86:89]
	v_mfma_f32_16x16x32_bf16 v[82:85], v[154:157], v[182:185], v[82:85]
	v_mfma_f32_16x16x32_bf16 v[70:73], v[142:145], v[210:213], v[70:73]
	v_mfma_f32_16x16x32_bf16 v[66:69], v[154:157], v[210:213], v[66:69]
	s_barrier
	s_add_i32 s53, s53, s40
	v_lshl_add_u64 v[196:197], s[28:29], 0, v[192:193]
	s_mov_b32 m0, s53
	ds_read_b128 v[162:165], v214 offset:16384
	ds_read_b128 v[166:169], v214 offset:17408
	ds_read_b128 v[170:173], v214 offset:18432
	ds_read_b128 v[174:177], v214 offset:19456
	ds_read_b128 v[178:181], v214 offset:20480
	ds_read_b128 v[182:185], v214 offset:21504
	ds_read_b128 v[186:189], v214 offset:22528
	ds_read_b128 v[210:213], v214 offset:23552
	global_load_lds_dwordx4 v[196:197], off
	s_add_i32 m0, s53, 0x2000
	s_add_u32 s54, s28, 0x40000
	v_lshl_add_u64 v[198:199], s[28:29], 0, v[204:205]
	s_addc_u32 s55, s29, 0
	s_add_i32 s53, s56, s40
	global_load_lds_dwordx4 v[198:199], off
	v_lshl_add_u64 v[216:217], s[54:55], 0, v[192:193]
	s_mov_b32 m0, s53
	v_lshl_add_u64 v[220:221], s[30:31], 0, v[194:195]
	global_load_lds_dwordx4 v[216:217], off
	v_lshl_add_u64 v[216:217], s[54:55], 0, v[204:205]
	s_add_i32 m0, s53, 0x2000
	s_nop 0
	global_load_lds_dwordx4 v[216:217], off
	v_lshl_add_u64 v[216:217], s[30:31], 0, v[190:191]
	s_mov_b32 m0, s25
	s_nop 0
	global_load_lds_dwordx4 v[216:217], off
	s_mov_b32 m0, s27
	s_nop 0
	global_load_lds_dwordx4 v[220:221], off
	s_waitcnt vmcnt(8)
	s_waitcnt lgkmcnt(0)
	s_barrier
	s_waitcnt lgkmcnt(0)
	v_mfma_f32_16x16x32_bf16 v[62:65], v[110:113], v[162:165], v[62:65]
	v_mfma_f32_16x16x32_bf16 v[58:61], v[122:125], v[162:165], v[58:61]
	v_mfma_f32_16x16x32_bf16 v[46:49], v[110:113], v[170:173], v[46:49]
	v_mfma_f32_16x16x32_bf16 v[42:45], v[122:125], v[170:173], v[42:45]
	v_mfma_f32_16x16x32_bf16 v[30:33], v[110:113], v[178:181], v[30:33]
	v_mfma_f32_16x16x32_bf16 v[26:29], v[122:125], v[178:181], v[26:29]
	v_mfma_f32_16x16x32_bf16 v[14:17], v[110:113], v[186:189], v[14:17]
	v_mfma_f32_16x16x32_bf16 v[10:13], v[122:125], v[186:189], v[10:13]
	v_mfma_f32_16x16x32_bf16 v[62:65], v[118:121], v[166:169], v[62:65]
	v_mfma_f32_16x16x32_bf16 v[58:61], v[134:137], v[166:169], v[58:61]
	v_mfma_f32_16x16x32_bf16 v[46:49], v[118:121], v[174:177], v[46:49]
	v_mfma_f32_16x16x32_bf16 v[42:45], v[134:137], v[174:177], v[42:45]
	v_mfma_f32_16x16x32_bf16 v[30:33], v[118:121], v[182:185], v[30:33]
	v_mfma_f32_16x16x32_bf16 v[26:29], v[134:137], v[182:185], v[26:29]
	v_mfma_f32_16x16x32_bf16 v[14:17], v[118:121], v[210:213], v[14:17]
	v_mfma_f32_16x16x32_bf16 v[10:13], v[134:137], v[210:213], v[10:13]
	v_mfma_f32_16x16x32_bf16 v[54:57], v[138:141], v[162:165], v[54:57]
	v_mfma_f32_16x16x32_bf16 v[50:53], v[146:149], v[162:165], v[50:53]
	v_mfma_f32_16x16x32_bf16 v[38:41], v[138:141], v[170:173], v[38:41]
	v_mfma_f32_16x16x32_bf16 v[34:37], v[146:149], v[170:173], v[34:37]
	v_mfma_f32_16x16x32_bf16 v[22:25], v[138:141], v[178:181], v[22:25]
	v_mfma_f32_16x16x32_bf16 v[18:21], v[146:149], v[178:181], v[18:21]
	v_mfma_f32_16x16x32_bf16 v[6:9], v[138:141], v[186:189], v[6:9]
	v_mfma_f32_16x16x32_bf16 v[2:5], v[146:149], v[186:189], v[2:5]
	v_mfma_f32_16x16x32_bf16 v[54:57], v[142:145], v[166:169], v[54:57]
	v_mfma_f32_16x16x32_bf16 v[50:53], v[154:157], v[166:169], v[50:53]
	v_mfma_f32_16x16x32_bf16 v[38:41], v[142:145], v[174:177], v[38:41]
	v_mfma_f32_16x16x32_bf16 v[34:37], v[154:157], v[174:177], v[34:37]
	v_mfma_f32_16x16x32_bf16 v[22:25], v[142:145], v[182:185], v[22:25]
	v_mfma_f32_16x16x32_bf16 v[18:21], v[154:157], v[182:185], v[18:21]
	v_mfma_f32_16x16x32_bf16 v[6:9], v[142:145], v[210:213], v[6:9]
	v_mfma_f32_16x16x32_bf16 v[2:5], v[154:157], v[210:213], v[2:5]
	s_barrier
	s_add_i32 s53, 0, 0x18000
	s_add_i32 s54, 0, 0x1c000
	v_add_u32_e32 v134, s53, v1
	v_add_u32_e32 v154, s54, v1
	ds_read_b128 v[110:113], v134
	ds_read_b128 v[118:121], v134 offset:1024
	ds_read_b128 v[122:125], v134 offset:2048
	ds_read_b128 v[134:137], v134 offset:3072
	ds_read_b128 v[138:141], v154
	ds_read_b128 v[142:145], v154 offset:1024
	ds_read_b128 v[146:149], v154 offset:2048
	ds_read_b128 v[154:157], v154 offset:3072
	s_add_u32 s30, s30, 0x40000
	s_addc_u32 s31, s31, 0
	s_mov_b32 m0, s41
	v_lshl_add_u64 v[222:223], s[30:31], 0, v[190:191]
	ds_read_b128 v[162:165], v214 offset:32768
	ds_read_b128 v[166:169], v214 offset:33792
	ds_read_b128 v[170:173], v214 offset:34816
	ds_read_b128 v[174:177], v214 offset:35840
	ds_read_b128 v[178:181], v214 offset:36864
	ds_read_b128 v[182:185], v214 offset:37888
	ds_read_b128 v[186:189], v214 offset:38912
	ds_read_b128 v[210:213], v214 offset:39936
	global_load_lds_dwordx4 v[222:223], off
	v_lshl_add_u64 v[222:223], s[30:31], 0, v[194:195]
	s_mov_b32 m0, s42
	s_nop 0
	global_load_lds_dwordx4 v[222:223], off
	s_waitcnt vmcnt(8)
	s_waitcnt lgkmcnt(0)
	s_barrier
	s_waitcnt lgkmcnt(0)
	v_mfma_f32_16x16x32_bf16 v[158:161], v[110:113], v[162:165], v[158:161]
	v_mfma_f32_16x16x32_bf16 v[150:153], v[122:125], v[162:165], v[150:153]
	v_mfma_f32_16x16x32_bf16 v[114:117], v[110:113], v[170:173], v[114:117]
	v_mfma_f32_16x16x32_bf16 v[106:109], v[122:125], v[170:173], v[106:109]
	v_mfma_f32_16x16x32_bf16 v[94:97], v[110:113], v[178:181], v[94:97]
	v_mfma_f32_16x16x32_bf16 v[90:93], v[122:125], v[178:181], v[90:93]
	v_mfma_f32_16x16x32_bf16 v[78:81], v[110:113], v[186:189], v[78:81]
	v_mfma_f32_16x16x32_bf16 v[74:77], v[122:125], v[186:189], v[74:77]
	v_mfma_f32_16x16x32_bf16 v[158:161], v[118:121], v[166:169], v[158:161]
	v_mfma_f32_16x16x32_bf16 v[150:153], v[134:137], v[166:169], v[150:153]
	v_mfma_f32_16x16x32_bf16 v[114:117], v[118:121], v[174:177], v[114:117]
	v_mfma_f32_16x16x32_bf16 v[106:109], v[134:137], v[174:177], v[106:109]
	v_mfma_f32_16x16x32_bf16 v[94:97], v[118:121], v[182:185], v[94:97]
	v_mfma_f32_16x16x32_bf16 v[90:93], v[134:137], v[182:185], v[90:93]
	v_mfma_f32_16x16x32_bf16 v[78:81], v[118:121], v[210:213], v[78:81]
	v_mfma_f32_16x16x32_bf16 v[74:77], v[134:137], v[210:213], v[74:77]
	v_mfma_f32_16x16x32_bf16 v[130:133], v[138:141], v[162:165], v[130:133]
	v_mfma_f32_16x16x32_bf16 v[126:129], v[146:149], v[162:165], v[126:129]
	v_mfma_f32_16x16x32_bf16 v[102:105], v[138:141], v[170:173], v[102:105]
	v_mfma_f32_16x16x32_bf16 v[98:101], v[146:149], v[170:173], v[98:101]
	v_mfma_f32_16x16x32_bf16 v[86:89], v[138:141], v[178:181], v[86:89]
	v_mfma_f32_16x16x32_bf16 v[82:85], v[146:149], v[178:181], v[82:85]
	v_mfma_f32_16x16x32_bf16 v[70:73], v[138:141], v[186:189], v[70:73]
	v_mfma_f32_16x16x32_bf16 v[66:69], v[146:149], v[186:189], v[66:69]
	v_mfma_f32_16x16x32_bf16 v[130:133], v[142:145], v[166:169], v[130:133]
	v_mfma_f32_16x16x32_bf16 v[126:129], v[154:157], v[166:169], v[126:129]
	v_mfma_f32_16x16x32_bf16 v[102:105], v[142:145], v[174:177], v[102:105]
	v_mfma_f32_16x16x32_bf16 v[98:101], v[154:157], v[174:177], v[98:101]
	v_mfma_f32_16x16x32_bf16 v[86:89], v[142:145], v[182:185], v[86:89]
	v_mfma_f32_16x16x32_bf16 v[82:85], v[154:157], v[182:185], v[82:85]
	v_mfma_f32_16x16x32_bf16 v[70:73], v[142:145], v[210:213], v[70:73]
	v_mfma_f32_16x16x32_bf16 v[66:69], v[154:157], v[210:213], v[66:69]
	s_barrier
	s_add_i32 s30, s53, s40
	v_lshl_add_u64 v[196:197], v[196:197], 0, s[94:95]
	s_mov_b32 m0, s30
	ds_read_b128 v[162:165], v214 offset:49152
	ds_read_b128 v[166:169], v214 offset:50176
	ds_read_b128 v[170:173], v214 offset:51200
	ds_read_b128 v[174:177], v214 offset:52224
	ds_read_b128 v[178:181], v214 offset:53248
	ds_read_b128 v[182:185], v214 offset:54272
	ds_read_b128 v[186:189], v214 offset:55296
	ds_read_b128 v[210:213], v214 offset:56320
	global_load_lds_dwordx4 v[196:197], off
	s_add_i32 m0, s30, 0x2000
	s_add_u32 s28, s28, 0x40080
	v_lshl_add_u64 v[196:197], v[198:199], 0, s[94:95]
	s_addc_u32 s29, s29, 0
	s_add_i32 s30, s54, s40
	global_load_lds_dwordx4 v[196:197], off
	v_lshl_add_u64 v[196:197], s[28:29], 0, v[192:193]
	s_mov_b32 m0, s30
	s_nop 0
	global_load_lds_dwordx4 v[196:197], off
	v_lshl_add_u64 v[196:197], s[28:29], 0, v[204:205]
	s_add_i32 m0, s30, 0x2000
	s_nop 0
	global_load_lds_dwordx4 v[196:197], off
	v_lshl_add_u64 v[196:197], v[216:217], 0, s[94:95]
	s_mov_b32 m0, s45
	s_nop 0
	global_load_lds_dwordx4 v[196:197], off
	v_lshl_add_u64 v[196:197], v[220:221], 0, s[94:95]
	s_mov_b32 m0, s46
	s_nop 0
	global_load_lds_dwordx4 v[196:197], off
	s_waitcnt vmcnt(8)
	s_waitcnt lgkmcnt(0)
	s_barrier
	s_waitcnt lgkmcnt(0)
	v_mfma_f32_16x16x32_bf16 v[62:65], v[110:113], v[162:165], v[62:65]
	v_mfma_f32_16x16x32_bf16 v[58:61], v[122:125], v[162:165], v[58:61]
	v_mfma_f32_16x16x32_bf16 v[46:49], v[110:113], v[170:173], v[46:49]
	v_mfma_f32_16x16x32_bf16 v[42:45], v[122:125], v[170:173], v[42:45]
	v_mfma_f32_16x16x32_bf16 v[30:33], v[110:113], v[178:181], v[30:33]
	v_mfma_f32_16x16x32_bf16 v[26:29], v[122:125], v[178:181], v[26:29]
	v_mfma_f32_16x16x32_bf16 v[14:17], v[110:113], v[186:189], v[14:17]
	v_mfma_f32_16x16x32_bf16 v[10:13], v[122:125], v[186:189], v[10:13]
	v_mfma_f32_16x16x32_bf16 v[62:65], v[118:121], v[166:169], v[62:65]
	v_mfma_f32_16x16x32_bf16 v[58:61], v[134:137], v[166:169], v[58:61]
	v_mfma_f32_16x16x32_bf16 v[46:49], v[118:121], v[174:177], v[46:49]
	v_mfma_f32_16x16x32_bf16 v[42:45], v[134:137], v[174:177], v[42:45]
	v_mfma_f32_16x16x32_bf16 v[30:33], v[118:121], v[182:185], v[30:33]
	v_mfma_f32_16x16x32_bf16 v[26:29], v[134:137], v[182:185], v[26:29]
	v_mfma_f32_16x16x32_bf16 v[14:17], v[118:121], v[210:213], v[14:17]
	v_mfma_f32_16x16x32_bf16 v[10:13], v[134:137], v[210:213], v[10:13]
	v_mfma_f32_16x16x32_bf16 v[54:57], v[138:141], v[162:165], v[54:57]
	v_mfma_f32_16x16x32_bf16 v[50:53], v[146:149], v[162:165], v[50:53]
	v_mfma_f32_16x16x32_bf16 v[38:41], v[138:141], v[170:173], v[38:41]
	v_mfma_f32_16x16x32_bf16 v[34:37], v[146:149], v[170:173], v[34:37]
	v_mfma_f32_16x16x32_bf16 v[22:25], v[138:141], v[178:181], v[22:25]
	v_mfma_f32_16x16x32_bf16 v[18:21], v[146:149], v[178:181], v[18:21]
	v_mfma_f32_16x16x32_bf16 v[6:9], v[138:141], v[186:189], v[6:9]
	v_mfma_f32_16x16x32_bf16 v[2:5], v[146:149], v[186:189], v[2:5]
	v_mfma_f32_16x16x32_bf16 v[54:57], v[142:145], v[166:169], v[54:57]
	v_mfma_f32_16x16x32_bf16 v[50:53], v[154:157], v[166:169], v[50:53]
	v_mfma_f32_16x16x32_bf16 v[38:41], v[142:145], v[174:177], v[38:41]
	v_mfma_f32_16x16x32_bf16 v[34:37], v[154:157], v[174:177], v[34:37]
	v_mfma_f32_16x16x32_bf16 v[22:25], v[142:145], v[182:185], v[22:25]
	v_mfma_f32_16x16x32_bf16 v[18:21], v[154:157], v[182:185], v[18:21]
	v_mfma_f32_16x16x32_bf16 v[6:9], v[142:145], v[210:213], v[6:9]
	v_mfma_f32_16x16x32_bf16 v[2:5], v[154:157], v[210:213], v[2:5]
	s_barrier
	s_add_i32 s52, s52, 2
	s_add_u32 s4, s4, 0x100
	s_addc_u32 s5, s5, 0
	s_add_u32 s50, s50, 0x100
	s_addc_u32 s51, s51, 0
	s_cmp_gt_u32 s52, 13
	s_cbranch_scc0 .LBB0_1096
	s_and_b64 vcc, exec, s[14:15]
	s_cbranch_vccz .LBB0_1099
	s_barrier

.LBB0_1180:
	s_add_u32 s26, s24, 0xfffc0080
	s_addc_u32 s27, s25, -1
	s_add_i32 s55, 0, 0x10000
	s_cmp_eq_u32 s54, 12
	s_cselect_b32 s29, s17, s27
	s_cselect_b32 s28, s50, s26
	v_add_u32_e32 v150, s55, v1
	s_cselect_b32 s27, s15, s53
	s_cselect_b32 s26, s51, s52
	s_add_i32 s58, 0, 0x14000
	ds_read_b128 v[142:145], v150
	ds_read_b128 v[146:149], v150 offset:1024
	ds_read_b128 v[154:157], v150 offset:2048
	ds_read_b128 v[158:161], v150 offset:3072
	v_add_u32_e32 v150, s58, v1
	ds_read_b128 v[162:165], v150
	ds_read_b128 v[166:169], v150 offset:1024
	ds_read_b128 v[170:173], v150 offset:2048
	ds_read_b128 v[174:177], v150 offset:3072
	v_lshl_add_u64 v[150:151], s[24:25], 0, v[138:139]
	s_add_i32 m0, s40, 0xc000
	ds_read_b128 v[178:181], v152
	ds_read_b128 v[182:185], v152 offset:1024
	ds_read_b128 v[186:189], v152 offset:2048
	ds_read_b128 v[190:193], v152 offset:3072
	ds_read_b128 v[204:207], v152 offset:4096
	ds_read_b128 v[208:211], v152 offset:5120
	ds_read_b128 v[212:215], v152 offset:6144
	ds_read_b128 v[228:231], v152 offset:7168
	global_load_lds_dwordx4 v[150:151], off
	v_lshl_add_u64 v[150:151], s[24:25], 0, v[140:141]
	s_add_i32 m0, s40, 0xe000
	s_nop 0
	global_load_lds_dwordx4 v[150:151], off
	s_waitcnt vmcnt(8)
	s_waitcnt lgkmcnt(0)
	s_barrier
	s_waitcnt lgkmcnt(0)
	v_mfma_f32_16x16x32_bf16 v[126:129], v[142:145], v[178:181], v[126:129]
	v_mfma_f32_16x16x32_bf16 v[122:125], v[154:157], v[178:181], v[122:125]
	v_mfma_f32_16x16x32_bf16 v[110:113], v[142:145], v[186:189], v[110:113]
	v_mfma_f32_16x16x32_bf16 v[106:109], v[154:157], v[186:189], v[106:109]
	v_mfma_f32_16x16x32_bf16 v[94:97], v[142:145], v[204:207], v[94:97]
	v_mfma_f32_16x16x32_bf16 v[90:93], v[154:157], v[204:207], v[90:93]
	v_mfma_f32_16x16x32_bf16 v[78:81], v[142:145], v[212:215], v[78:81]
	v_mfma_f32_16x16x32_bf16 v[74:77], v[154:157], v[212:215], v[74:77]
	v_mfma_f32_16x16x32_bf16 v[126:129], v[146:149], v[182:185], v[126:129]
	v_mfma_f32_16x16x32_bf16 v[122:125], v[158:161], v[182:185], v[122:125]
	v_mfma_f32_16x16x32_bf16 v[110:113], v[146:149], v[190:193], v[110:113]
	v_mfma_f32_16x16x32_bf16 v[106:109], v[158:161], v[190:193], v[106:109]
	v_mfma_f32_16x16x32_bf16 v[94:97], v[146:149], v[208:211], v[94:97]
	v_mfma_f32_16x16x32_bf16 v[90:93], v[158:161], v[208:211], v[90:93]
	v_mfma_f32_16x16x32_bf16 v[78:81], v[146:149], v[228:231], v[78:81]
	v_mfma_f32_16x16x32_bf16 v[74:77], v[158:161], v[228:231], v[74:77]
	v_mfma_f32_16x16x32_bf16 v[118:121], v[162:165], v[178:181], v[118:121]
	v_mfma_f32_16x16x32_bf16 v[114:117], v[170:173], v[178:181], v[114:117]
	v_mfma_f32_16x16x32_bf16 v[102:105], v[162:165], v[186:189], v[102:105]
	v_mfma_f32_16x16x32_bf16 v[98:101], v[170:173], v[186:189], v[98:101]
	v_mfma_f32_16x16x32_bf16 v[86:89], v[162:165], v[204:207], v[86:89]
	v_mfma_f32_16x16x32_bf16 v[82:85], v[170:173], v[204:207], v[82:85]
	v_mfma_f32_16x16x32_bf16 v[70:73], v[162:165], v[212:215], v[70:73]
	v_mfma_f32_16x16x32_bf16 v[66:69], v[170:173], v[212:215], v[66:69]
	v_mfma_f32_16x16x32_bf16 v[118:121], v[166:169], v[182:185], v[118:121]
	v_mfma_f32_16x16x32_bf16 v[114:117], v[174:177], v[182:185], v[114:117]
	v_mfma_f32_16x16x32_bf16 v[102:105], v[166:169], v[190:193], v[102:105]
	v_mfma_f32_16x16x32_bf16 v[98:101], v[174:177], v[190:193], v[98:101]
	v_mfma_f32_16x16x32_bf16 v[86:89], v[166:169], v[208:211], v[86:89]
	v_mfma_f32_16x16x32_bf16 v[82:85], v[174:177], v[208:211], v[82:85]
	v_mfma_f32_16x16x32_bf16 v[70:73], v[166:169], v[228:231], v[70:73]
	v_mfma_f32_16x16x32_bf16 v[66:69], v[174:177], v[228:231], v[66:69]
	s_barrier
	s_add_i32 s55, s55, s39
	v_lshl_add_u64 v[150:151], s[26:27], 0, v[134:135]
	s_mov_b32 m0, s55
	ds_read_b128 v[178:181], v152 offset:16384
	ds_read_b128 v[182:185], v152 offset:17408
	ds_read_b128 v[186:189], v152 offset:18432
	ds_read_b128 v[190:193], v152 offset:19456
	ds_read_b128 v[204:207], v152 offset:20480
	ds_read_b128 v[208:211], v152 offset:21504
	ds_read_b128 v[212:215], v152 offset:22528
	ds_read_b128 v[228:231], v152 offset:23552
	global_load_lds_dwordx4 v[150:151], off
	s_add_i32 m0, s55, 0x2000
	s_add_u32 s56, s26, 0x40000
	v_lshl_add_u64 v[194:195], s[26:27], 0, v[130:131]
	s_addc_u32 s57, s27, 0
	s_add_i32 s55, s58, s39
	global_load_lds_dwordx4 v[194:195], off
	v_lshl_add_u64 v[196:197], s[56:57], 0, v[134:135]
	s_mov_b32 m0, s55
	v_lshl_add_u64 v[198:199], s[28:29], 0, v[132:133]
	global_load_lds_dwordx4 v[196:197], off
	v_lshl_add_u64 v[196:197], s[56:57], 0, v[130:131]
	s_add_i32 m0, s55, 0x2000
	s_nop 0
	global_load_lds_dwordx4 v[196:197], off
	v_lshl_add_u64 v[196:197], s[28:29], 0, v[136:137]
	s_mov_b32 m0, s40
	s_nop 0
	global_load_lds_dwordx4 v[196:197], off
	s_mov_b32 m0, s41
	s_nop 0
	global_load_lds_dwordx4 v[198:199], off
	s_waitcnt vmcnt(8)
	s_waitcnt lgkmcnt(0)
	s_barrier
	s_waitcnt lgkmcnt(0)
	v_mfma_f32_16x16x32_bf16 v[62:65], v[142:145], v[178:181], v[62:65]
	v_mfma_f32_16x16x32_bf16 v[58:61], v[154:157], v[178:181], v[58:61]
	v_mfma_f32_16x16x32_bf16 v[46:49], v[142:145], v[186:189], v[46:49]
	v_mfma_f32_16x16x32_bf16 v[42:45], v[154:157], v[186:189], v[42:45]
	v_mfma_f32_16x16x32_bf16 v[30:33], v[142:145], v[204:207], v[30:33]
	v_mfma_f32_16x16x32_bf16 v[26:29], v[154:157], v[204:207], v[26:29]
	v_mfma_f32_16x16x32_bf16 v[14:17], v[142:145], v[212:215], v[14:17]
	v_mfma_f32_16x16x32_bf16 v[10:13], v[154:157], v[212:215], v[10:13]
	v_mfma_f32_16x16x32_bf16 v[62:65], v[146:149], v[182:185], v[62:65]
	v_mfma_f32_16x16x32_bf16 v[58:61], v[158:161], v[182:185], v[58:61]
	v_mfma_f32_16x16x32_bf16 v[46:49], v[146:149], v[190:193], v[46:49]
	v_mfma_f32_16x16x32_bf16 v[42:45], v[158:161], v[190:193], v[42:45]
	v_mfma_f32_16x16x32_bf16 v[30:33], v[146:149], v[208:211], v[30:33]
	v_mfma_f32_16x16x32_bf16 v[26:29], v[158:161], v[208:211], v[26:29]
	v_mfma_f32_16x16x32_bf16 v[14:17], v[146:149], v[228:231], v[14:17]
	v_mfma_f32_16x16x32_bf16 v[10:13], v[158:161], v[228:231], v[10:13]
	v_mfma_f32_16x16x32_bf16 v[54:57], v[162:165], v[178:181], v[54:57]
	v_mfma_f32_16x16x32_bf16 v[50:53], v[170:173], v[178:181], v[50:53]
	v_mfma_f32_16x16x32_bf16 v[38:41], v[162:165], v[186:189], v[38:41]
	v_mfma_f32_16x16x32_bf16 v[34:37], v[170:173], v[186:189], v[34:37]
	v_mfma_f32_16x16x32_bf16 v[22:25], v[162:165], v[204:207], v[22:25]
	v_mfma_f32_16x16x32_bf16 v[18:21], v[170:173], v[204:207], v[18:21]
	v_mfma_f32_16x16x32_bf16 v[6:9], v[162:165], v[212:215], v[6:9]
	v_mfma_f32_16x16x32_bf16 v[2:5], v[170:173], v[212:215], v[2:5]
	v_mfma_f32_16x16x32_bf16 v[54:57], v[166:169], v[182:185], v[54:57]
	v_mfma_f32_16x16x32_bf16 v[50:53], v[174:177], v[182:185], v[50:53]
	v_mfma_f32_16x16x32_bf16 v[38:41], v[166:169], v[190:193], v[38:41]
	v_mfma_f32_16x16x32_bf16 v[34:37], v[174:177], v[190:193], v[34:37]
	v_mfma_f32_16x16x32_bf16 v[22:25], v[166:169], v[208:211], v[22:25]
	v_mfma_f32_16x16x32_bf16 v[18:21], v[174:177], v[208:211], v[18:21]
	v_mfma_f32_16x16x32_bf16 v[6:9], v[166:169], v[228:231], v[6:9]
	v_mfma_f32_16x16x32_bf16 v[2:5], v[174:177], v[228:231], v[2:5]
	s_barrier
	s_add_i32 s55, 0, 0x18000
	v_add_u32_e32 v153, s55, v1
	s_add_i32 s56, 0, 0x1c000
	ds_read_b128 v[142:145], v153
	ds_read_b128 v[146:149], v153 offset:1024
	ds_read_b128 v[154:157], v153 offset:2048
	ds_read_b128 v[158:161], v153 offset:3072
	v_add_u32_e32 v153, s56, v1
	ds_read_b128 v[162:165], v153
	ds_read_b128 v[166:169], v153 offset:1024
	ds_read_b128 v[170:173], v153 offset:2048
	ds_read_b128 v[174:177], v153 offset:3072
	s_add_u32 s28, s28, 0x40000
	s_addc_u32 s29, s29, 0
	s_mov_b32 m0, s42
	v_lshl_add_u64 v[216:217], s[28:29], 0, v[136:137]
	ds_read_b128 v[178:181], v152 offset:32768
	ds_read_b128 v[182:185], v152 offset:33792
	ds_read_b128 v[186:189], v152 offset:34816
	ds_read_b128 v[190:193], v152 offset:35840
	ds_read_b128 v[204:207], v152 offset:36864
	ds_read_b128 v[208:211], v152 offset:37888
	ds_read_b128 v[212:215], v152 offset:38912
	ds_read_b128 v[228:231], v152 offset:39936
	global_load_lds_dwordx4 v[216:217], off
	v_lshl_add_u64 v[216:217], s[28:29], 0, v[132:133]
	s_mov_b32 m0, s43
	s_nop 0
	global_load_lds_dwordx4 v[216:217], off
	s_waitcnt vmcnt(8)
	s_waitcnt lgkmcnt(0)
	s_barrier
	s_waitcnt lgkmcnt(0)
	v_mfma_f32_16x16x32_bf16 v[126:129], v[142:145], v[178:181], v[126:129]
	v_mfma_f32_16x16x32_bf16 v[122:125], v[154:157], v[178:181], v[122:125]
	v_mfma_f32_16x16x32_bf16 v[110:113], v[142:145], v[186:189], v[110:113]
	v_mfma_f32_16x16x32_bf16 v[106:109], v[154:157], v[186:189], v[106:109]
	v_mfma_f32_16x16x32_bf16 v[94:97], v[142:145], v[204:207], v[94:97]
	v_mfma_f32_16x16x32_bf16 v[90:93], v[154:157], v[204:207], v[90:93]
	v_mfma_f32_16x16x32_bf16 v[78:81], v[142:145], v[212:215], v[78:81]
	v_mfma_f32_16x16x32_bf16 v[74:77], v[154:157], v[212:215], v[74:77]
	v_mfma_f32_16x16x32_bf16 v[126:129], v[146:149], v[182:185], v[126:129]
	v_mfma_f32_16x16x32_bf16 v[122:125], v[158:161], v[182:185], v[122:125]
	v_mfma_f32_16x16x32_bf16 v[110:113], v[146:149], v[190:193], v[110:113]
	v_mfma_f32_16x16x32_bf16 v[106:109], v[158:161], v[190:193], v[106:109]
	v_mfma_f32_16x16x32_bf16 v[94:97], v[146:149], v[208:211], v[94:97]
	v_mfma_f32_16x16x32_bf16 v[90:93], v[158:161], v[208:211], v[90:93]
	v_mfma_f32_16x16x32_bf16 v[78:81], v[146:149], v[228:231], v[78:81]
	v_mfma_f32_16x16x32_bf16 v[74:77], v[158:161], v[228:231], v[74:77]
	v_mfma_f32_16x16x32_bf16 v[118:121], v[162:165], v[178:181], v[118:121]
	v_mfma_f32_16x16x32_bf16 v[114:117], v[170:173], v[178:181], v[114:117]
	v_mfma_f32_16x16x32_bf16 v[102:105], v[162:165], v[186:189], v[102:105]
	v_mfma_f32_16x16x32_bf16 v[98:101], v[170:173], v[186:189], v[98:101]
	v_mfma_f32_16x16x32_bf16 v[86:89], v[162:165], v[204:207], v[86:89]
	v_mfma_f32_16x16x32_bf16 v[82:85], v[170:173], v[204:207], v[82:85]
	v_mfma_f32_16x16x32_bf16 v[70:73], v[162:165], v[212:215], v[70:73]
	v_mfma_f32_16x16x32_bf16 v[66:69], v[170:173], v[212:215], v[66:69]
	v_mfma_f32_16x16x32_bf16 v[118:121], v[166:169], v[182:185], v[118:121]
	v_mfma_f32_16x16x32_bf16 v[114:117], v[174:177], v[182:185], v[114:117]
	v_mfma_f32_16x16x32_bf16 v[102:105], v[166:169], v[190:193], v[102:105]
	v_mfma_f32_16x16x32_bf16 v[98:101], v[174:177], v[190:193], v[98:101]
	v_mfma_f32_16x16x32_bf16 v[86:89], v[166:169], v[208:211], v[86:89]
	v_mfma_f32_16x16x32_bf16 v[82:85], v[174:177], v[208:211], v[82:85]
	v_mfma_f32_16x16x32_bf16 v[70:73], v[166:169], v[228:231], v[70:73]
	v_mfma_f32_16x16x32_bf16 v[66:69], v[174:177], v[228:231], v[66:69]
	s_barrier
	s_add_i32 s28, s55, s39
	v_lshl_add_u64 v[150:151], v[150:151], 0, s[94:95]
	s_mov_b32 m0, s28
	ds_read_b128 v[178:181], v152 offset:49152
	ds_read_b128 v[182:185], v152 offset:50176
	ds_read_b128 v[186:189], v152 offset:51200
	ds_read_b128 v[190:193], v152 offset:52224
	ds_read_b128 v[204:207], v152 offset:53248
	ds_read_b128 v[208:211], v152 offset:54272
	ds_read_b128 v[212:215], v152 offset:55296
	ds_read_b128 v[228:231], v152 offset:56320
	global_load_lds_dwordx4 v[150:151], off
	s_add_i32 m0, s28, 0x2000
	s_add_u32 s26, s26, 0x40080
	v_lshl_add_u64 v[150:151], v[194:195], 0, s[94:95]
	s_addc_u32 s27, s27, 0
	s_add_i32 s28, s56, s39
	global_load_lds_dwordx4 v[150:151], off
	v_lshl_add_u64 v[150:151], s[26:27], 0, v[134:135]
	s_mov_b32 m0, s28
	s_nop 0
	global_load_lds_dwordx4 v[150:151], off
	v_lshl_add_u64 v[150:151], s[26:27], 0, v[130:131]
	s_add_i32 m0, s28, 0x2000
	s_nop 0
	global_load_lds_dwordx4 v[150:151], off
	v_lshl_add_u64 v[150:151], v[196:197], 0, s[94:95]
	s_mov_b32 m0, s47
	s_nop 0
	global_load_lds_dwordx4 v[150:151], off
	v_lshl_add_u64 v[150:151], v[198:199], 0, s[94:95]
	s_mov_b32 m0, s48
	s_nop 0
	global_load_lds_dwordx4 v[150:151], off
	s_waitcnt vmcnt(8)
	s_waitcnt lgkmcnt(0)
	s_barrier
	s_waitcnt lgkmcnt(0)
	v_mfma_f32_16x16x32_bf16 v[62:65], v[142:145], v[178:181], v[62:65]
	v_mfma_f32_16x16x32_bf16 v[58:61], v[154:157], v[178:181], v[58:61]
	v_mfma_f32_16x16x32_bf16 v[46:49], v[142:145], v[186:189], v[46:49]
	v_mfma_f32_16x16x32_bf16 v[42:45], v[154:157], v[186:189], v[42:45]
	v_mfma_f32_16x16x32_bf16 v[30:33], v[142:145], v[204:207], v[30:33]
	v_mfma_f32_16x16x32_bf16 v[26:29], v[154:157], v[204:207], v[26:29]
	v_mfma_f32_16x16x32_bf16 v[14:17], v[142:145], v[212:215], v[14:17]
	v_mfma_f32_16x16x32_bf16 v[10:13], v[154:157], v[212:215], v[10:13]
	v_mfma_f32_16x16x32_bf16 v[62:65], v[146:149], v[182:185], v[62:65]
	v_mfma_f32_16x16x32_bf16 v[58:61], v[158:161], v[182:185], v[58:61]
	v_mfma_f32_16x16x32_bf16 v[46:49], v[146:149], v[190:193], v[46:49]
	v_mfma_f32_16x16x32_bf16 v[42:45], v[158:161], v[190:193], v[42:45]
	v_mfma_f32_16x16x32_bf16 v[30:33], v[146:149], v[208:211], v[30:33]
	v_mfma_f32_16x16x32_bf16 v[26:29], v[158:161], v[208:211], v[26:29]
	v_mfma_f32_16x16x32_bf16 v[14:17], v[146:149], v[228:231], v[14:17]
	v_mfma_f32_16x16x32_bf16 v[10:13], v[158:161], v[228:231], v[10:13]
	v_mfma_f32_16x16x32_bf16 v[54:57], v[162:165], v[178:181], v[54:57]
	v_mfma_f32_16x16x32_bf16 v[50:53], v[170:173], v[178:181], v[50:53]
	v_mfma_f32_16x16x32_bf16 v[38:41], v[162:165], v[186:189], v[38:41]
	v_mfma_f32_16x16x32_bf16 v[34:37], v[170:173], v[186:189], v[34:37]
	v_mfma_f32_16x16x32_bf16 v[22:25], v[162:165], v[204:207], v[22:25]
	v_mfma_f32_16x16x32_bf16 v[18:21], v[170:173], v[204:207], v[18:21]
	v_mfma_f32_16x16x32_bf16 v[6:9], v[162:165], v[212:215], v[6:9]
	v_mfma_f32_16x16x32_bf16 v[2:5], v[170:173], v[212:215], v[2:5]
	v_mfma_f32_16x16x32_bf16 v[54:57], v[166:169], v[182:185], v[54:57]
	v_mfma_f32_16x16x32_bf16 v[50:53], v[174:177], v[182:185], v[50:53]
	v_mfma_f32_16x16x32_bf16 v[38:41], v[166:169], v[190:193], v[38:41]
	v_mfma_f32_16x16x32_bf16 v[34:37], v[174:177], v[190:193], v[34:37]
	v_mfma_f32_16x16x32_bf16 v[22:25], v[166:169], v[208:211], v[22:25]
	v_mfma_f32_16x16x32_bf16 v[18:21], v[174:177], v[208:211], v[18:21]
	v_mfma_f32_16x16x32_bf16 v[6:9], v[166:169], v[228:231], v[6:9]
	v_mfma_f32_16x16x32_bf16 v[2:5], v[174:177], v[228:231], v[2:5]
	s_barrier
	s_add_i32 s54, s54, 2
	s_add_u32 s24, s24, 0x100
	s_addc_u32 s25, s25, 0
	s_add_u32 s52, s52, 0x100
	s_addc_u32 s53, s53, 0
	s_cmp_gt_u32 s54, 13
	s_cbranch_scc0 .LBB0_1180
	s_and_b64 vcc, exec, s[12:13]
	s_cbranch_vccz .LBB0_1183
	s_barrier

.LBB0_1263:
	s_add_u32 s20, s18, 0x100
	s_addc_u32 s21, s19, 0
	s_add_i32 s53, 0, 0x10000
	s_cmp_eq_u32 s52, 40
	s_cselect_b32 s25, s5, s21
	s_cselect_b32 s24, s4, s20
	s_cselect_b32 s23, s17, s51
	s_cselect_b32 s22, s16, s50
	s_add_i32 s54, 0, 0x14000
	v_add_u32_e32 v134, s53, v1
	v_add_u32_e32 v154, s54, v1
	ds_read_b128 v[110:113], v134
	ds_read_b128 v[118:121], v134 offset:1024
	ds_read_b128 v[122:125], v134 offset:2048
	ds_read_b128 v[134:137], v134 offset:3072
	ds_read_b128 v[138:141], v154
	ds_read_b128 v[142:145], v154 offset:1024
	ds_read_b128 v[146:149], v154 offset:2048
	ds_read_b128 v[154:157], v154 offset:3072
	v_lshl_add_u64 v[196:197], s[18:19], 0, v[206:207]
	s_add_i32 m0, s35, 0xc000
	ds_read_b128 v[162:165], v214
	ds_read_b128 v[166:169], v214 offset:1024
	ds_read_b128 v[170:173], v214 offset:2048
	ds_read_b128 v[174:177], v214 offset:3072
	ds_read_b128 v[178:181], v214 offset:4096
	ds_read_b128 v[182:185], v214 offset:5120
	ds_read_b128 v[186:189], v214 offset:6144
	ds_read_b128 v[210:213], v214 offset:7168
	global_load_lds_dwordx4 v[196:197], off
	v_lshl_add_u64 v[196:197], s[18:19], 0, v[208:209]
	s_add_i32 m0, s35, 0xe000
	s_nop 0
	global_load_lds_dwordx4 v[196:197], off
	s_waitcnt vmcnt(8)
	s_waitcnt lgkmcnt(0)
	s_barrier
	s_waitcnt lgkmcnt(0)
	v_mfma_f32_16x16x32_bf16 v[158:161], v[110:113], v[162:165], v[158:161]
	v_mfma_f32_16x16x32_bf16 v[150:153], v[122:125], v[162:165], v[150:153]
	v_mfma_f32_16x16x32_bf16 v[114:117], v[110:113], v[170:173], v[114:117]
	v_mfma_f32_16x16x32_bf16 v[106:109], v[122:125], v[170:173], v[106:109]
	v_mfma_f32_16x16x32_bf16 v[94:97], v[110:113], v[178:181], v[94:97]
	v_mfma_f32_16x16x32_bf16 v[90:93], v[122:125], v[178:181], v[90:93]
	v_mfma_f32_16x16x32_bf16 v[78:81], v[110:113], v[186:189], v[78:81]
	v_mfma_f32_16x16x32_bf16 v[74:77], v[122:125], v[186:189], v[74:77]
	v_mfma_f32_16x16x32_bf16 v[158:161], v[118:121], v[166:169], v[158:161]
	v_mfma_f32_16x16x32_bf16 v[150:153], v[134:137], v[166:169], v[150:153]
	v_mfma_f32_16x16x32_bf16 v[114:117], v[118:121], v[174:177], v[114:117]
	v_mfma_f32_16x16x32_bf16 v[106:109], v[134:137], v[174:177], v[106:109]
	v_mfma_f32_16x16x32_bf16 v[94:97], v[118:121], v[182:185], v[94:97]
	v_mfma_f32_16x16x32_bf16 v[90:93], v[134:137], v[182:185], v[90:93]
	v_mfma_f32_16x16x32_bf16 v[78:81], v[118:121], v[210:213], v[78:81]
	v_mfma_f32_16x16x32_bf16 v[74:77], v[134:137], v[210:213], v[74:77]
	v_mfma_f32_16x16x32_bf16 v[130:133], v[138:141], v[162:165], v[130:133]
	v_mfma_f32_16x16x32_bf16 v[126:129], v[146:149], v[162:165], v[126:129]
	v_mfma_f32_16x16x32_bf16 v[102:105], v[138:141], v[170:173], v[102:105]
	v_mfma_f32_16x16x32_bf16 v[98:101], v[146:149], v[170:173], v[98:101]
	v_mfma_f32_16x16x32_bf16 v[86:89], v[138:141], v[178:181], v[86:89]
	v_mfma_f32_16x16x32_bf16 v[82:85], v[146:149], v[178:181], v[82:85]
	v_mfma_f32_16x16x32_bf16 v[70:73], v[138:141], v[186:189], v[70:73]
	v_mfma_f32_16x16x32_bf16 v[66:69], v[146:149], v[186:189], v[66:69]
	v_mfma_f32_16x16x32_bf16 v[130:133], v[142:145], v[166:169], v[130:133]
	v_mfma_f32_16x16x32_bf16 v[126:129], v[154:157], v[166:169], v[126:129]
	v_mfma_f32_16x16x32_bf16 v[102:105], v[142:145], v[174:177], v[102:105]
	v_mfma_f32_16x16x32_bf16 v[98:101], v[154:157], v[174:177], v[98:101]
	v_mfma_f32_16x16x32_bf16 v[86:89], v[142:145], v[182:185], v[86:89]
	v_mfma_f32_16x16x32_bf16 v[82:85], v[154:157], v[182:185], v[82:85]
	v_mfma_f32_16x16x32_bf16 v[70:73], v[142:145], v[210:213], v[70:73]
	v_mfma_f32_16x16x32_bf16 v[66:69], v[154:157], v[210:213], v[66:69]
	s_barrier
	s_add_i32 s18, s53, s34
	v_lshl_add_u64 v[196:197], s[22:23], 0, v[192:193]
	s_mov_b32 m0, s18
	ds_read_b128 v[162:165], v214 offset:16384
	ds_read_b128 v[166:169], v214 offset:17408
	ds_read_b128 v[170:173], v214 offset:18432
	ds_read_b128 v[174:177], v214 offset:19456
	ds_read_b128 v[178:181], v214 offset:20480
	ds_read_b128 v[182:185], v214 offset:21504
	ds_read_b128 v[186:189], v214 offset:22528
	ds_read_b128 v[210:213], v214 offset:23552
	global_load_lds_dwordx4 v[196:197], off
	s_add_i32 m0, s18, 0x2000
	s_add_u32 s18, s22, 0xb0000
	v_lshl_add_u64 v[198:199], s[22:23], 0, v[204:205]
	s_addc_u32 s19, s23, 0
	s_add_i32 s53, s54, s34
	global_load_lds_dwordx4 v[198:199], off
	v_lshl_add_u64 v[216:217], s[18:19], 0, v[192:193]
	s_mov_b32 m0, s53
	v_lshl_add_u64 v[220:221], s[24:25], 0, v[194:195]
	global_load_lds_dwordx4 v[216:217], off
	v_lshl_add_u64 v[216:217], s[18:19], 0, v[204:205]
	s_add_i32 m0, s53, 0x2000
	s_nop 0
	global_load_lds_dwordx4 v[216:217], off
	v_lshl_add_u64 v[216:217], s[24:25], 0, v[190:191]
	s_mov_b32 m0, s35
	s_nop 0
	global_load_lds_dwordx4 v[216:217], off
	s_mov_b32 m0, s36
	s_nop 0
	global_load_lds_dwordx4 v[220:221], off
	s_waitcnt vmcnt(8)
	s_waitcnt lgkmcnt(0)
	s_barrier
	s_waitcnt lgkmcnt(0)
	v_mfma_f32_16x16x32_bf16 v[62:65], v[110:113], v[162:165], v[62:65]
	v_mfma_f32_16x16x32_bf16 v[58:61], v[122:125], v[162:165], v[58:61]
	v_mfma_f32_16x16x32_bf16 v[46:49], v[110:113], v[170:173], v[46:49]
	v_mfma_f32_16x16x32_bf16 v[42:45], v[122:125], v[170:173], v[42:45]
	v_mfma_f32_16x16x32_bf16 v[30:33], v[110:113], v[178:181], v[30:33]
	v_mfma_f32_16x16x32_bf16 v[26:29], v[122:125], v[178:181], v[26:29]
	v_mfma_f32_16x16x32_bf16 v[14:17], v[110:113], v[186:189], v[14:17]
	v_mfma_f32_16x16x32_bf16 v[10:13], v[122:125], v[186:189], v[10:13]
	v_mfma_f32_16x16x32_bf16 v[62:65], v[118:121], v[166:169], v[62:65]
	v_mfma_f32_16x16x32_bf16 v[58:61], v[134:137], v[166:169], v[58:61]
	v_mfma_f32_16x16x32_bf16 v[46:49], v[118:121], v[174:177], v[46:49]
	v_mfma_f32_16x16x32_bf16 v[42:45], v[134:137], v[174:177], v[42:45]
	v_mfma_f32_16x16x32_bf16 v[30:33], v[118:121], v[182:185], v[30:33]
	v_mfma_f32_16x16x32_bf16 v[26:29], v[134:137], v[182:185], v[26:29]
	v_mfma_f32_16x16x32_bf16 v[14:17], v[118:121], v[210:213], v[14:17]
	v_mfma_f32_16x16x32_bf16 v[10:13], v[134:137], v[210:213], v[10:13]
	v_mfma_f32_16x16x32_bf16 v[54:57], v[138:141], v[162:165], v[54:57]
	v_mfma_f32_16x16x32_bf16 v[50:53], v[146:149], v[162:165], v[50:53]
	v_mfma_f32_16x16x32_bf16 v[38:41], v[138:141], v[170:173], v[38:41]
	v_mfma_f32_16x16x32_bf16 v[34:37], v[146:149], v[170:173], v[34:37]
	v_mfma_f32_16x16x32_bf16 v[22:25], v[138:141], v[178:181], v[22:25]
	v_mfma_f32_16x16x32_bf16 v[18:21], v[146:149], v[178:181], v[18:21]
	v_mfma_f32_16x16x32_bf16 v[6:9], v[138:141], v[186:189], v[6:9]
	v_mfma_f32_16x16x32_bf16 v[2:5], v[146:149], v[186:189], v[2:5]
	v_mfma_f32_16x16x32_bf16 v[54:57], v[142:145], v[166:169], v[54:57]
	v_mfma_f32_16x16x32_bf16 v[50:53], v[154:157], v[166:169], v[50:53]
	v_mfma_f32_16x16x32_bf16 v[38:41], v[142:145], v[174:177], v[38:41]
	v_mfma_f32_16x16x32_bf16 v[34:37], v[154:157], v[174:177], v[34:37]
	v_mfma_f32_16x16x32_bf16 v[22:25], v[142:145], v[182:185], v[22:25]
	v_mfma_f32_16x16x32_bf16 v[18:21], v[154:157], v[182:185], v[18:21]
	v_mfma_f32_16x16x32_bf16 v[6:9], v[142:145], v[210:213], v[6:9]
	v_mfma_f32_16x16x32_bf16 v[2:5], v[154:157], v[210:213], v[2:5]
	s_barrier
	s_add_i32 s53, 0, 0x18000
	s_add_i32 s54, 0, 0x1c000
	v_add_u32_e32 v134, s53, v1
	v_add_u32_e32 v154, s54, v1
	ds_read_b128 v[110:113], v134
	ds_read_b128 v[118:121], v134 offset:1024
	ds_read_b128 v[122:125], v134 offset:2048
	ds_read_b128 v[134:137], v134 offset:3072
	ds_read_b128 v[138:141], v154
	ds_read_b128 v[142:145], v154 offset:1024
	ds_read_b128 v[146:149], v154 offset:2048
	ds_read_b128 v[154:157], v154 offset:3072
	s_add_u32 s18, s24, 0xb0000
	s_addc_u32 s19, s25, 0
	s_mov_b32 m0, s37
	v_lshl_add_u64 v[222:223], s[18:19], 0, v[190:191]
	ds_read_b128 v[162:165], v214 offset:32768
	ds_read_b128 v[166:169], v214 offset:33792
	ds_read_b128 v[170:173], v214 offset:34816
	ds_read_b128 v[174:177], v214 offset:35840
	ds_read_b128 v[178:181], v214 offset:36864
	ds_read_b128 v[182:185], v214 offset:37888
	ds_read_b128 v[186:189], v214 offset:38912
	ds_read_b128 v[210:213], v214 offset:39936
	global_load_lds_dwordx4 v[222:223], off
	v_lshl_add_u64 v[222:223], s[18:19], 0, v[194:195]
	s_mov_b32 m0, s38
	s_nop 0
	global_load_lds_dwordx4 v[222:223], off
	s_waitcnt vmcnt(8)
	s_waitcnt lgkmcnt(0)
	s_barrier
	s_waitcnt lgkmcnt(0)
	v_mfma_f32_16x16x32_bf16 v[158:161], v[110:113], v[162:165], v[158:161]
	v_mfma_f32_16x16x32_bf16 v[150:153], v[122:125], v[162:165], v[150:153]
	v_mfma_f32_16x16x32_bf16 v[114:117], v[110:113], v[170:173], v[114:117]
	v_mfma_f32_16x16x32_bf16 v[106:109], v[122:125], v[170:173], v[106:109]
	v_mfma_f32_16x16x32_bf16 v[94:97], v[110:113], v[178:181], v[94:97]
	v_mfma_f32_16x16x32_bf16 v[90:93], v[122:125], v[178:181], v[90:93]
	v_mfma_f32_16x16x32_bf16 v[78:81], v[110:113], v[186:189], v[78:81]
	v_mfma_f32_16x16x32_bf16 v[74:77], v[122:125], v[186:189], v[74:77]
	v_mfma_f32_16x16x32_bf16 v[158:161], v[118:121], v[166:169], v[158:161]
	v_mfma_f32_16x16x32_bf16 v[150:153], v[134:137], v[166:169], v[150:153]
	v_mfma_f32_16x16x32_bf16 v[114:117], v[118:121], v[174:177], v[114:117]
	v_mfma_f32_16x16x32_bf16 v[106:109], v[134:137], v[174:177], v[106:109]
	v_mfma_f32_16x16x32_bf16 v[94:97], v[118:121], v[182:185], v[94:97]
	v_mfma_f32_16x16x32_bf16 v[90:93], v[134:137], v[182:185], v[90:93]
	v_mfma_f32_16x16x32_bf16 v[78:81], v[118:121], v[210:213], v[78:81]
	v_mfma_f32_16x16x32_bf16 v[74:77], v[134:137], v[210:213], v[74:77]
	v_mfma_f32_16x16x32_bf16 v[130:133], v[138:141], v[162:165], v[130:133]
	v_mfma_f32_16x16x32_bf16 v[126:129], v[146:149], v[162:165], v[126:129]
	v_mfma_f32_16x16x32_bf16 v[102:105], v[138:141], v[170:173], v[102:105]
	v_mfma_f32_16x16x32_bf16 v[98:101], v[146:149], v[170:173], v[98:101]
	v_mfma_f32_16x16x32_bf16 v[86:89], v[138:141], v[178:181], v[86:89]
	v_mfma_f32_16x16x32_bf16 v[82:85], v[146:149], v[178:181], v[82:85]
	v_mfma_f32_16x16x32_bf16 v[70:73], v[138:141], v[186:189], v[70:73]
	v_mfma_f32_16x16x32_bf16 v[66:69], v[146:149], v[186:189], v[66:69]
	v_mfma_f32_16x16x32_bf16 v[130:133], v[142:145], v[166:169], v[130:133]
	v_mfma_f32_16x16x32_bf16 v[126:129], v[154:157], v[166:169], v[126:129]
	v_mfma_f32_16x16x32_bf16 v[102:105], v[142:145], v[174:177], v[102:105]
	v_mfma_f32_16x16x32_bf16 v[98:101], v[154:157], v[174:177], v[98:101]
	v_mfma_f32_16x16x32_bf16 v[86:89], v[142:145], v[182:185], v[86:89]
	v_mfma_f32_16x16x32_bf16 v[82:85], v[154:157], v[182:185], v[82:85]
	v_mfma_f32_16x16x32_bf16 v[70:73], v[142:145], v[210:213], v[70:73]
	v_mfma_f32_16x16x32_bf16 v[66:69], v[154:157], v[210:213], v[66:69]
	s_barrier
	s_add_i32 s18, s53, s34
	v_lshl_add_u64 v[196:197], v[196:197], 0, s[94:95]
	s_mov_b32 m0, s18
	ds_read_b128 v[162:165], v214 offset:49152
	ds_read_b128 v[166:169], v214 offset:50176
	ds_read_b128 v[170:173], v214 offset:51200
	ds_read_b128 v[174:177], v214 offset:52224
	ds_read_b128 v[178:181], v214 offset:53248
	ds_read_b128 v[182:185], v214 offset:54272
	ds_read_b128 v[186:189], v214 offset:55296
	ds_read_b128 v[210:213], v214 offset:56320
	global_load_lds_dwordx4 v[196:197], off
	s_add_i32 m0, s18, 0x2000
	s_add_u32 s18, s22, 0xb0080
	v_lshl_add_u64 v[196:197], v[198:199], 0, s[94:95]
	s_addc_u32 s19, s23, 0
	s_add_i32 s22, s54, s34
	global_load_lds_dwordx4 v[196:197], off
	v_lshl_add_u64 v[196:197], s[18:19], 0, v[192:193]
	s_mov_b32 m0, s22
	s_nop 0
	global_load_lds_dwordx4 v[196:197], off
	v_lshl_add_u64 v[196:197], s[18:19], 0, v[204:205]
	s_add_i32 m0, s22, 0x2000
	s_nop 0
	global_load_lds_dwordx4 v[196:197], off
	v_lshl_add_u64 v[196:197], v[216:217], 0, s[94:95]
	s_mov_b32 m0, s41
	s_nop 0
	global_load_lds_dwordx4 v[196:197], off
	v_lshl_add_u64 v[196:197], v[220:221], 0, s[94:95]
	s_mov_b32 m0, s42
	s_nop 0
	global_load_lds_dwordx4 v[196:197], off
	s_waitcnt vmcnt(8)
	s_waitcnt lgkmcnt(0)
	s_barrier
	s_waitcnt lgkmcnt(0)
	v_mfma_f32_16x16x32_bf16 v[62:65], v[110:113], v[162:165], v[62:65]
	v_mfma_f32_16x16x32_bf16 v[58:61], v[122:125], v[162:165], v[58:61]
	v_mfma_f32_16x16x32_bf16 v[46:49], v[110:113], v[170:173], v[46:49]
	v_mfma_f32_16x16x32_bf16 v[42:45], v[122:125], v[170:173], v[42:45]
	v_mfma_f32_16x16x32_bf16 v[30:33], v[110:113], v[178:181], v[30:33]
	v_mfma_f32_16x16x32_bf16 v[26:29], v[122:125], v[178:181], v[26:29]
	v_mfma_f32_16x16x32_bf16 v[14:17], v[110:113], v[186:189], v[14:17]
	v_mfma_f32_16x16x32_bf16 v[10:13], v[122:125], v[186:189], v[10:13]
	v_mfma_f32_16x16x32_bf16 v[62:65], v[118:121], v[166:169], v[62:65]
	v_mfma_f32_16x16x32_bf16 v[58:61], v[134:137], v[166:169], v[58:61]
	v_mfma_f32_16x16x32_bf16 v[46:49], v[118:121], v[174:177], v[46:49]
	v_mfma_f32_16x16x32_bf16 v[42:45], v[134:137], v[174:177], v[42:45]
	v_mfma_f32_16x16x32_bf16 v[30:33], v[118:121], v[182:185], v[30:33]
	v_mfma_f32_16x16x32_bf16 v[26:29], v[134:137], v[182:185], v[26:29]
	v_mfma_f32_16x16x32_bf16 v[14:17], v[118:121], v[210:213], v[14:17]
	v_mfma_f32_16x16x32_bf16 v[10:13], v[134:137], v[210:213], v[10:13]
	v_mfma_f32_16x16x32_bf16 v[54:57], v[138:141], v[162:165], v[54:57]
	v_mfma_f32_16x16x32_bf16 v[50:53], v[146:149], v[162:165], v[50:53]
	v_mfma_f32_16x16x32_bf16 v[38:41], v[138:141], v[170:173], v[38:41]
	v_mfma_f32_16x16x32_bf16 v[34:37], v[146:149], v[170:173], v[34:37]
	v_mfma_f32_16x16x32_bf16 v[22:25], v[138:141], v[178:181], v[22:25]
	v_mfma_f32_16x16x32_bf16 v[18:21], v[146:149], v[178:181], v[18:21]
	v_mfma_f32_16x16x32_bf16 v[6:9], v[138:141], v[186:189], v[6:9]
	v_mfma_f32_16x16x32_bf16 v[2:5], v[146:149], v[186:189], v[2:5]
	v_mfma_f32_16x16x32_bf16 v[54:57], v[142:145], v[166:169], v[54:57]
	v_mfma_f32_16x16x32_bf16 v[50:53], v[154:157], v[166:169], v[50:53]
	v_mfma_f32_16x16x32_bf16 v[38:41], v[142:145], v[174:177], v[38:41]
	v_mfma_f32_16x16x32_bf16 v[34:37], v[154:157], v[174:177], v[34:37]
	v_mfma_f32_16x16x32_bf16 v[22:25], v[142:145], v[182:185], v[22:25]
	v_mfma_f32_16x16x32_bf16 v[18:21], v[154:157], v[182:185], v[18:21]
	v_mfma_f32_16x16x32_bf16 v[6:9], v[142:145], v[210:213], v[6:9]
	v_mfma_f32_16x16x32_bf16 v[2:5], v[154:157], v[210:213], v[2:5]
	s_barrier
	s_add_i32 s52, s52, 2
	s_add_u32 s50, s50, 0x100
	s_addc_u32 s51, s51, 0
	s_cmp_gt_u32 s52, 41
	s_mov_b64 s[18:19], s[20:21]
	s_cbranch_scc0 .LBB0_1263
	s_and_b64 vcc, exec, s[14:15]
	s_cbranch_vccz .LBB0_1266
	s_barrier
